# K-loop head also computes the phase-1 a2/b2 pointer selects (4 fewer scalar instructions per iteration)
# speedup vs baseline: 1.0017x; 1.0017x over previous
.LBB0_161:
	s_add_u32 s86, s69, s6
	s_addc_u32 s87, s70, s7
	s_add_u32 s88, s71, s8
	s_addc_u32 s89, s72, s9
	s_ashr_i32 s23, s22, 31
	s_lshl_b64 s[6:7], s[22:23], 19
	s_add_u32 s24, s34, s6
	s_addc_u32 s25, s35, s7
	s_and_b64 s[8:9], s[0:1], exec
	s_cselect_b32 s23, s25, s43
	s_cselect_b32 s90, s24, s42
	s_ashr_i32 s21, s20, 31
	s_lshl_b64 s[8:9], s[20:21], 19
	s_add_u32 s26, s17, s8
	s_addc_u32 s27, s19, s9
	s_and_b64 s[48:49], s[0:1], exec
	s_cselect_b32 s21, s27, s39
	s_cselect_b32 s91, s26, s38
	s_add_u32 s48, s90, 0x80
	s_addc_u32 s49, s23, 0
	s_add_u32 s54, s91, 0x80
	s_addc_u32 s55, s21, 0
	v_lshl_add_u64 v[128:129], s[42:43], 0, v[150:151]
	v_lshl_add_u64 v[130:131], s[42:43], 0, v[152:153]
	s_mov_b32 s92, 0
	s_mov_b64 s[56:57], 0
	s_add_u32 s64, s42, s56
	s_addc_u32 s65, s43, s57
	s_add_u32 s94, s38, s56
	s_addc_u32 s93, s39, s57
	s_add_u32 s58, s64, 0x180
	s_addc_u32 s59, s65, 0
	s_add_u32 s60, s94, 0x180
	s_addc_u32 s61, s93, 0
	s_add_u32 s64, s64, 0x100
	s_addc_u32 s65, s65, 0
	s_add_u32 s62, s94, 0x100
	s_addc_u32 s63, s93, 0
	s_cmpk_eq_i32 s56, 0x700
	s_cselect_b32 s58, s48, s58
	s_cselect_b32 s59, s49, s59
	s_cselect_b32 s60, s54, s60
	s_cselect_b32 s61, s55, s61
	s_cselect_b32 s64, s90, s64
	s_cselect_b32 s65, s23, s65
	s_cselect_b32 s62, s91, s62
	s_cselect_b32 s63, s21, s63
	v_add_u32_e32 v144, s82, v171
	ds_read_b128 v[132:135], v144
	ds_read_b128 v[158:161], v144 offset:1024
	ds_read_b128 v[162:165], v144 offset:2048
	ds_read_b128 v[166:169], v144 offset:3072
	v_add_u32_e32 v144, s83, v171
	ds_read_b128 v[184:187], v144
	ds_read_b128 v[188:191], v144 offset:1024
	ds_read_b128 v[192:195], v144 offset:2048
	ds_read_b128 v[196:199], v144 offset:3072
	v_lshl_add_u64 v[232:233], v[128:129], 0, s[56:57]
	s_add_i32 m0, s29, 0xc000
	ds_read_b128 v[200:203], v181
	ds_read_b128 v[204:207], v181 offset:1024
	ds_read_b128 v[208:211], v181 offset:2048
	ds_read_b128 v[212:215], v181 offset:3072
	ds_read_b128 v[216:219], v181 offset:4096
	ds_read_b128 v[220:223], v181 offset:5120
	ds_read_b128 v[224:227], v181 offset:6144
	global_load_lds_dwordx4 v[232:233], off
	v_lshl_add_u64 v[232:233], v[130:131], 0, s[56:57]
	s_add_i32 m0, s29, 0xe000
	ds_read_b128 v[228:231], v181 offset:7168
	global_load_lds_dwordx4 v[232:233], off
	s_waitcnt vmcnt(8)
	s_waitcnt lgkmcnt(0)
	s_barrier
	s_setprio 1
	s_waitcnt lgkmcnt(0)
	v_mfma_f32_16x16x32_bf16 v[124:127], v[132:135], v[200:203], 0
	v_mfma_f32_16x16x32_bf16 v[120:123], v[162:165], v[200:203], 0
	v_mfma_f32_16x16x32_bf16 v[108:111], v[132:135], v[208:211], 0
	v_mfma_f32_16x16x32_bf16 v[104:107], v[162:165], v[208:211], 0
	v_mfma_f32_16x16x32_bf16 v[92:95], v[132:135], v[216:219], 0
	v_mfma_f32_16x16x32_bf16 v[88:91], v[162:165], v[216:219], 0
	v_mfma_f32_16x16x32_bf16 v[76:79], v[132:135], v[224:227], 0
	v_mfma_f32_16x16x32_bf16 v[72:75], v[162:165], v[224:227], 0
	v_mfma_f32_16x16x32_bf16 v[124:127], v[158:161], v[204:207], v[124:127]
	v_mfma_f32_16x16x32_bf16 v[120:123], v[166:169], v[204:207], v[120:123]
	v_mfma_f32_16x16x32_bf16 v[108:111], v[158:161], v[212:215], v[108:111]
	v_mfma_f32_16x16x32_bf16 v[104:107], v[166:169], v[212:215], v[104:107]
	v_mfma_f32_16x16x32_bf16 v[92:95], v[158:161], v[220:223], v[92:95]
	v_mfma_f32_16x16x32_bf16 v[88:91], v[166:169], v[220:223], v[88:91]
	v_mfma_f32_16x16x32_bf16 v[76:79], v[158:161], v[228:231], v[76:79]
	v_mfma_f32_16x16x32_bf16 v[72:75], v[166:169], v[228:231], v[72:75]
	s_setprio 0
	s_setprio 1
	v_mfma_f32_16x16x32_bf16 v[116:119], v[184:187], v[200:203], 0
	v_mfma_f32_16x16x32_bf16 v[112:115], v[192:195], v[200:203], 0
	v_mfma_f32_16x16x32_bf16 v[100:103], v[184:187], v[208:211], 0
	v_mfma_f32_16x16x32_bf16 v[96:99], v[192:195], v[208:211], 0
	v_mfma_f32_16x16x32_bf16 v[84:87], v[184:187], v[216:219], 0
	v_mfma_f32_16x16x32_bf16 v[80:83], v[192:195], v[216:219], 0
	v_mfma_f32_16x16x32_bf16 v[68:71], v[184:187], v[224:227], 0
	v_mfma_f32_16x16x32_bf16 v[64:67], v[192:195], v[224:227], 0
	v_mfma_f32_16x16x32_bf16 v[116:119], v[188:191], v[204:207], v[116:119]
	v_mfma_f32_16x16x32_bf16 v[112:115], v[196:199], v[204:207], v[112:115]
	v_mfma_f32_16x16x32_bf16 v[100:103], v[188:191], v[212:215], v[100:103]
	v_mfma_f32_16x16x32_bf16 v[96:99], v[196:199], v[212:215], v[96:99]
	v_mfma_f32_16x16x32_bf16 v[84:87], v[188:191], v[220:223], v[84:87]
	v_mfma_f32_16x16x32_bf16 v[80:83], v[196:199], v[220:223], v[80:83]
	v_mfma_f32_16x16x32_bf16 v[68:71], v[188:191], v[228:231], v[68:71]
	v_mfma_f32_16x16x32_bf16 v[64:67], v[196:199], v[228:231], v[64:67]
	s_setprio 0
	s_barrier
	s_add_i32 s10, s82, s66
	s_mov_b32 m0, s10
	ds_read_b128 v[200:203], v181 offset:16384
	ds_read_b128 v[204:207], v181 offset:17408
	ds_read_b128 v[208:211], v181 offset:18432
	global_load_lds_dwordx4 v138, s[62:63]
	s_add_i32 m0, s10, 0x2000
	ds_read_b128 v[212:215], v181 offset:19456
	global_load_lds_dwordx4 v142, s[62:63]
	s_add_u32 s62, s62, 0x40000
	s_addc_u32 s63, s63, 0
	s_add_i32 s10, s83, s66
	s_mov_b32 m0, s10
	ds_read_b128 v[216:219], v181 offset:20480
	global_load_lds_dwordx4 v138, s[62:63]
	s_add_i32 m0, s10, 0x2000
	ds_read_b128 v[220:223], v181 offset:21504
	global_load_lds_dwordx4 v142, s[62:63]
	s_mov_b32 m0, s29
	ds_read_b128 v[224:227], v181 offset:22528
	global_load_lds_dwordx4 v136, s[64:65]
	s_mov_b32 m0, s31
	ds_read_b128 v[228:231], v181 offset:23552
	global_load_lds_dwordx4 v140, s[64:65]
	s_waitcnt vmcnt(8)
	s_waitcnt lgkmcnt(0)
	s_barrier
	s_setprio 1
	s_waitcnt lgkmcnt(0)
	v_mfma_f32_16x16x32_bf16 v[60:63], v[132:135], v[200:203], 0
	v_mfma_f32_16x16x32_bf16 v[56:59], v[162:165], v[200:203], 0
	v_mfma_f32_16x16x32_bf16 v[44:47], v[132:135], v[208:211], 0
	v_mfma_f32_16x16x32_bf16 v[40:43], v[162:165], v[208:211], 0
	v_mfma_f32_16x16x32_bf16 v[28:31], v[132:135], v[216:219], 0
	v_mfma_f32_16x16x32_bf16 v[24:27], v[162:165], v[216:219], 0
	v_mfma_f32_16x16x32_bf16 v[12:15], v[132:135], v[224:227], 0
	v_mfma_f32_16x16x32_bf16 v[8:11], v[162:165], v[224:227], 0
	v_mfma_f32_16x16x32_bf16 v[60:63], v[158:161], v[204:207], v[60:63]
	v_mfma_f32_16x16x32_bf16 v[56:59], v[166:169], v[204:207], v[56:59]
	v_mfma_f32_16x16x32_bf16 v[44:47], v[158:161], v[212:215], v[44:47]
	v_mfma_f32_16x16x32_bf16 v[40:43], v[166:169], v[212:215], v[40:43]
	v_mfma_f32_16x16x32_bf16 v[28:31], v[158:161], v[220:223], v[28:31]
	v_mfma_f32_16x16x32_bf16 v[24:27], v[166:169], v[220:223], v[24:27]
	v_mfma_f32_16x16x32_bf16 v[12:15], v[158:161], v[228:231], v[12:15]
	v_mfma_f32_16x16x32_bf16 v[8:11], v[166:169], v[228:231], v[8:11]
	s_setprio 0
	s_setprio 1
	v_mfma_f32_16x16x32_bf16 v[52:55], v[184:187], v[200:203], 0
	v_mfma_f32_16x16x32_bf16 v[48:51], v[192:195], v[200:203], 0
	v_mfma_f32_16x16x32_bf16 v[36:39], v[184:187], v[208:211], 0
	v_mfma_f32_16x16x32_bf16 v[32:35], v[192:195], v[208:211], 0
	v_mfma_f32_16x16x32_bf16 v[20:23], v[184:187], v[216:219], 0
	v_mfma_f32_16x16x32_bf16 v[16:19], v[192:195], v[216:219], 0
	v_mfma_f32_16x16x32_bf16 v[4:7], v[184:187], v[224:227], 0
	v_mfma_f32_16x16x32_bf16 v[0:3], v[192:195], v[224:227], 0
	v_mfma_f32_16x16x32_bf16 v[52:55], v[188:191], v[204:207], v[52:55]
	v_mfma_f32_16x16x32_bf16 v[48:51], v[196:199], v[204:207], v[48:51]
	v_mfma_f32_16x16x32_bf16 v[36:39], v[188:191], v[212:215], v[36:39]
	v_mfma_f32_16x16x32_bf16 v[32:35], v[196:199], v[212:215], v[32:35]
	v_mfma_f32_16x16x32_bf16 v[20:23], v[188:191], v[220:223], v[20:23]
	v_mfma_f32_16x16x32_bf16 v[16:19], v[196:199], v[220:223], v[16:19]
	v_mfma_f32_16x16x32_bf16 v[4:7], v[188:191], v[228:231], v[4:7]
	v_mfma_f32_16x16x32_bf16 v[0:3], v[196:199], v[228:231], v[0:3]
	s_setprio 0
	s_barrier
	s_add_i32 s10, 0, 0x18000
	v_add_u32_e32 v144, s10, v171
	s_add_i32 s93, 0, 0x1c000
	ds_read_b128 v[132:135], v144
	ds_read_b128 v[158:161], v144 offset:1024
	ds_read_b128 v[162:165], v144 offset:2048
	ds_read_b128 v[166:169], v144 offset:3072
	v_add_u32_e32 v144, s93, v171
	ds_read_b128 v[184:187], v144
	ds_read_b128 v[188:191], v144 offset:1024
	ds_read_b128 v[192:195], v144 offset:2048
	ds_read_b128 v[196:199], v144 offset:3072
	s_add_u32 s62, s64, 0x40000
	s_addc_u32 s63, s65, 0
	s_mov_b32 m0, s67
	ds_read_b128 v[200:203], v181 offset:32768
	ds_read_b128 v[204:207], v181 offset:33792
	ds_read_b128 v[208:211], v181 offset:34816
	ds_read_b128 v[212:215], v181 offset:35840
	ds_read_b128 v[216:219], v181 offset:36864
	ds_read_b128 v[220:223], v181 offset:37888
	ds_read_b128 v[224:227], v181 offset:38912
	global_load_lds_dwordx4 v136, s[62:63]
	s_mov_b32 m0, s68
	ds_read_b128 v[228:231], v181 offset:39936
	global_load_lds_dwordx4 v140, s[62:63]
	s_waitcnt vmcnt(8)
	s_waitcnt lgkmcnt(0)
	s_barrier
	s_setprio 1
	s_waitcnt lgkmcnt(0)
	v_mfma_f32_16x16x32_bf16 v[124:127], v[132:135], v[200:203], v[124:127]
	v_mfma_f32_16x16x32_bf16 v[120:123], v[162:165], v[200:203], v[120:123]
	v_mfma_f32_16x16x32_bf16 v[108:111], v[132:135], v[208:211], v[108:111]
	v_mfma_f32_16x16x32_bf16 v[104:107], v[162:165], v[208:211], v[104:107]
	v_mfma_f32_16x16x32_bf16 v[92:95], v[132:135], v[216:219], v[92:95]
	v_mfma_f32_16x16x32_bf16 v[88:91], v[162:165], v[216:219], v[88:91]
	v_mfma_f32_16x16x32_bf16 v[76:79], v[132:135], v[224:227], v[76:79]
	v_mfma_f32_16x16x32_bf16 v[72:75], v[162:165], v[224:227], v[72:75]
	v_mfma_f32_16x16x32_bf16 v[124:127], v[158:161], v[204:207], v[124:127]
	v_mfma_f32_16x16x32_bf16 v[120:123], v[166:169], v[204:207], v[120:123]
	v_mfma_f32_16x16x32_bf16 v[108:111], v[158:161], v[212:215], v[108:111]
	v_mfma_f32_16x16x32_bf16 v[104:107], v[166:169], v[212:215], v[104:107]
	v_mfma_f32_16x16x32_bf16 v[92:95], v[158:161], v[220:223], v[92:95]
	v_mfma_f32_16x16x32_bf16 v[88:91], v[166:169], v[220:223], v[88:91]
	v_mfma_f32_16x16x32_bf16 v[76:79], v[158:161], v[228:231], v[76:79]
	v_mfma_f32_16x16x32_bf16 v[72:75], v[166:169], v[228:231], v[72:75]
	s_setprio 0
	s_setprio 1
	v_mfma_f32_16x16x32_bf16 v[116:119], v[184:187], v[200:203], v[116:119]
	v_mfma_f32_16x16x32_bf16 v[112:115], v[192:195], v[200:203], v[112:115]
	v_mfma_f32_16x16x32_bf16 v[100:103], v[184:187], v[208:211], v[100:103]
	v_mfma_f32_16x16x32_bf16 v[96:99], v[192:195], v[208:211], v[96:99]
	v_mfma_f32_16x16x32_bf16 v[84:87], v[184:187], v[216:219], v[84:87]
	v_mfma_f32_16x16x32_bf16 v[80:83], v[192:195], v[216:219], v[80:83]
	v_mfma_f32_16x16x32_bf16 v[68:71], v[184:187], v[224:227], v[68:71]
	v_mfma_f32_16x16x32_bf16 v[64:67], v[192:195], v[224:227], v[64:67]
	v_mfma_f32_16x16x32_bf16 v[116:119], v[188:191], v[204:207], v[116:119]
	v_mfma_f32_16x16x32_bf16 v[112:115], v[196:199], v[204:207], v[112:115]
	v_mfma_f32_16x16x32_bf16 v[100:103], v[188:191], v[212:215], v[100:103]
	v_mfma_f32_16x16x32_bf16 v[96:99], v[196:199], v[212:215], v[96:99]
	v_mfma_f32_16x16x32_bf16 v[84:87], v[188:191], v[220:223], v[84:87]
	v_mfma_f32_16x16x32_bf16 v[80:83], v[196:199], v[220:223], v[80:83]
	v_mfma_f32_16x16x32_bf16 v[68:71], v[188:191], v[228:231], v[68:71]
	v_mfma_f32_16x16x32_bf16 v[64:67], v[196:199], v[228:231], v[64:67]
	s_setprio 0
	s_barrier
	s_add_i32 s10, s10, s66
	s_mov_b32 m0, s10
	ds_read_b128 v[200:203], v181 offset:49152
	ds_read_b128 v[204:207], v181 offset:50176
	ds_read_b128 v[208:211], v181 offset:51200
	global_load_lds_dwordx4 v138, s[60:61]
	s_add_i32 m0, s10, 0x2000
	ds_read_b128 v[212:215], v181 offset:52224
	global_load_lds_dwordx4 v142, s[60:61]
	s_add_u32 s60, s60, 0x40000
	s_addc_u32 s61, s61, 0
	s_add_i32 s10, s93, s66
	s_mov_b32 m0, s10
	ds_read_b128 v[216:219], v181 offset:53248
	global_load_lds_dwordx4 v138, s[60:61]
	s_add_i32 m0, s10, 0x2000
	ds_read_b128 v[220:223], v181 offset:54272
	global_load_lds_dwordx4 v142, s[60:61]
	s_mov_b32 m0, s73
	ds_read_b128 v[224:227], v181 offset:55296
	global_load_lds_dwordx4 v136, s[58:59]
	v_lshl_add_u64 v[232:233], s[58:59], 0, v[140:141]
	s_mov_b32 m0, s78
	ds_read_b128 v[228:231], v181 offset:56320
	global_load_lds_dwordx4 v[232:233], off
	s_waitcnt vmcnt(8)
	s_waitcnt lgkmcnt(0)
	s_barrier
	s_setprio 1
	s_waitcnt lgkmcnt(0)
	v_mfma_f32_16x16x32_bf16 v[60:63], v[132:135], v[200:203], v[60:63]
	v_mfma_f32_16x16x32_bf16 v[56:59], v[162:165], v[200:203], v[56:59]
	v_mfma_f32_16x16x32_bf16 v[44:47], v[132:135], v[208:211], v[44:47]
	v_mfma_f32_16x16x32_bf16 v[40:43], v[162:165], v[208:211], v[40:43]
	v_mfma_f32_16x16x32_bf16 v[28:31], v[132:135], v[216:219], v[28:31]
	v_mfma_f32_16x16x32_bf16 v[24:27], v[162:165], v[216:219], v[24:27]
	v_mfma_f32_16x16x32_bf16 v[12:15], v[132:135], v[224:227], v[12:15]
	v_mfma_f32_16x16x32_bf16 v[8:11], v[162:165], v[224:227], v[8:11]
	v_mfma_f32_16x16x32_bf16 v[60:63], v[158:161], v[204:207], v[60:63]
	v_mfma_f32_16x16x32_bf16 v[56:59], v[166:169], v[204:207], v[56:59]
	v_mfma_f32_16x16x32_bf16 v[44:47], v[158:161], v[212:215], v[44:47]
	v_mfma_f32_16x16x32_bf16 v[40:43], v[166:169], v[212:215], v[40:43]
	v_mfma_f32_16x16x32_bf16 v[28:31], v[158:161], v[220:223], v[28:31]
	v_mfma_f32_16x16x32_bf16 v[24:27], v[166:169], v[220:223], v[24:27]
	v_mfma_f32_16x16x32_bf16 v[12:15], v[158:161], v[228:231], v[12:15]
	v_mfma_f32_16x16x32_bf16 v[8:11], v[166:169], v[228:231], v[8:11]
	s_setprio 0
	s_setprio 1
	v_mfma_f32_16x16x32_bf16 v[52:55], v[184:187], v[200:203], v[52:55]
	v_mfma_f32_16x16x32_bf16 v[48:51], v[192:195], v[200:203], v[48:51]
	v_mfma_f32_16x16x32_bf16 v[36:39], v[184:187], v[208:211], v[36:39]
	v_mfma_f32_16x16x32_bf16 v[32:35], v[192:195], v[208:211], v[32:35]
	v_mfma_f32_16x16x32_bf16 v[20:23], v[184:187], v[216:219], v[20:23]
	v_mfma_f32_16x16x32_bf16 v[16:19], v[192:195], v[216:219], v[16:19]
	v_mfma_f32_16x16x32_bf16 v[4:7], v[184:187], v[224:227], v[4:7]
	v_mfma_f32_16x16x32_bf16 v[0:3], v[192:195], v[224:227], v[0:3]
	v_mfma_f32_16x16x32_bf16 v[52:55], v[188:191], v[204:207], v[52:55]
	v_mfma_f32_16x16x32_bf16 v[48:51], v[196:199], v[204:207], v[48:51]
	v_mfma_f32_16x16x32_bf16 v[36:39], v[188:191], v[212:215], v[36:39]
	v_mfma_f32_16x16x32_bf16 v[32:35], v[196:199], v[212:215], v[32:35]
	v_mfma_f32_16x16x32_bf16 v[20:23], v[188:191], v[220:223], v[20:23]
	v_mfma_f32_16x16x32_bf16 v[16:19], v[196:199], v[220:223], v[16:19]
	v_mfma_f32_16x16x32_bf16 v[4:7], v[188:191], v[228:231], v[4:7]
	v_mfma_f32_16x16x32_bf16 v[0:3], v[196:199], v[228:231], v[0:3]
	s_setprio 0
	s_barrier
	s_add_i32 s10, s92, 2
	s_add_u32 s56, s56, 0x100
	s_addc_u32 s57, s57, 0
	s_cmp_gt_u32 s92, 13
	s_mov_b32 s92, s10
	s_cbranch_scc1 .LBB0_169
	s_branch .LBB0_163
.LBB0_162:
	v_add_u32_e32 v144, s82, v171
	ds_read_b128 v[132:135], v144
	ds_read_b128 v[158:161], v144 offset:1024
	ds_read_b128 v[162:165], v144 offset:2048
	ds_read_b128 v[166:169], v144 offset:3072
	v_add_u32_e32 v144, s83, v171
	ds_read_b128 v[184:187], v144
	ds_read_b128 v[188:191], v144 offset:1024
	ds_read_b128 v[192:195], v144 offset:2048
	ds_read_b128 v[196:199], v144 offset:3072
	v_lshl_add_u64 v[232:233], v[128:129], 0, s[56:57]
	s_add_i32 m0, s29, 0xc000
	ds_read_b128 v[200:203], v181
	ds_read_b128 v[204:207], v181 offset:1024
	ds_read_b128 v[208:211], v181 offset:2048
	ds_read_b128 v[212:215], v181 offset:3072
	ds_read_b128 v[216:219], v181 offset:4096
	ds_read_b128 v[220:223], v181 offset:5120
	ds_read_b128 v[224:227], v181 offset:6144
	global_load_lds_dwordx4 v[232:233], off
	v_lshl_add_u64 v[232:233], v[130:131], 0, s[56:57]
	s_add_i32 m0, s29, 0xe000
	ds_read_b128 v[228:231], v181 offset:7168
	global_load_lds_dwordx4 v[232:233], off
	s_waitcnt vmcnt(8)
	s_waitcnt lgkmcnt(0)
	s_barrier
	s_setprio 1
	s_waitcnt lgkmcnt(0)
	v_mfma_f32_16x16x32_bf16 v[124:127], v[132:135], v[200:203], v[124:127]
	v_mfma_f32_16x16x32_bf16 v[120:123], v[162:165], v[200:203], v[120:123]
	v_mfma_f32_16x16x32_bf16 v[108:111], v[132:135], v[208:211], v[108:111]
	v_mfma_f32_16x16x32_bf16 v[104:107], v[162:165], v[208:211], v[104:107]
	v_mfma_f32_16x16x32_bf16 v[92:95], v[132:135], v[216:219], v[92:95]
	v_mfma_f32_16x16x32_bf16 v[88:91], v[162:165], v[216:219], v[88:91]
	v_mfma_f32_16x16x32_bf16 v[76:79], v[132:135], v[224:227], v[76:79]
	v_mfma_f32_16x16x32_bf16 v[72:75], v[162:165], v[224:227], v[72:75]
	v_mfma_f32_16x16x32_bf16 v[124:127], v[158:161], v[204:207], v[124:127]
	v_mfma_f32_16x16x32_bf16 v[120:123], v[166:169], v[204:207], v[120:123]
	v_mfma_f32_16x16x32_bf16 v[108:111], v[158:161], v[212:215], v[108:111]
	v_mfma_f32_16x16x32_bf16 v[104:107], v[166:169], v[212:215], v[104:107]
	v_mfma_f32_16x16x32_bf16 v[92:95], v[158:161], v[220:223], v[92:95]
	v_mfma_f32_16x16x32_bf16 v[88:91], v[166:169], v[220:223], v[88:91]
	v_mfma_f32_16x16x32_bf16 v[76:79], v[158:161], v[228:231], v[76:79]
	v_mfma_f32_16x16x32_bf16 v[72:75], v[166:169], v[228:231], v[72:75]
	s_setprio 0
	s_setprio 1
	v_mfma_f32_16x16x32_bf16 v[116:119], v[184:187], v[200:203], v[116:119]
	v_mfma_f32_16x16x32_bf16 v[112:115], v[192:195], v[200:203], v[112:115]
	v_mfma_f32_16x16x32_bf16 v[100:103], v[184:187], v[208:211], v[100:103]
	v_mfma_f32_16x16x32_bf16 v[96:99], v[192:195], v[208:211], v[96:99]
	v_mfma_f32_16x16x32_bf16 v[84:87], v[184:187], v[216:219], v[84:87]
	v_mfma_f32_16x16x32_bf16 v[80:83], v[192:195], v[216:219], v[80:83]
	v_mfma_f32_16x16x32_bf16 v[68:71], v[184:187], v[224:227], v[68:71]
	v_mfma_f32_16x16x32_bf16 v[64:67], v[192:195], v[224:227], v[64:67]
	v_mfma_f32_16x16x32_bf16 v[116:119], v[188:191], v[204:207], v[116:119]
	v_mfma_f32_16x16x32_bf16 v[112:115], v[196:199], v[204:207], v[112:115]
	v_mfma_f32_16x16x32_bf16 v[100:103], v[188:191], v[212:215], v[100:103]
	v_mfma_f32_16x16x32_bf16 v[96:99], v[196:199], v[212:215], v[96:99]
	v_mfma_f32_16x16x32_bf16 v[84:87], v[188:191], v[220:223], v[84:87]
	v_mfma_f32_16x16x32_bf16 v[80:83], v[196:199], v[220:223], v[80:83]
	v_mfma_f32_16x16x32_bf16 v[68:71], v[188:191], v[228:231], v[68:71]
	v_mfma_f32_16x16x32_bf16 v[64:67], v[196:199], v[228:231], v[64:67]
	s_setprio 0
	s_barrier
	s_add_i32 s10, s82, s66
	s_mov_b32 m0, s10
	ds_read_b128 v[200:203], v181 offset:16384
	ds_read_b128 v[204:207], v181 offset:17408
	ds_read_b128 v[208:211], v181 offset:18432
	global_load_lds_dwordx4 v138, s[62:63]
	s_add_i32 m0, s10, 0x2000
	ds_read_b128 v[212:215], v181 offset:19456
	global_load_lds_dwordx4 v142, s[62:63]
	s_add_u32 s62, s62, 0x40000
	s_addc_u32 s63, s63, 0
	s_add_i32 s10, s83, s66
	s_mov_b32 m0, s10
	ds_read_b128 v[216:219], v181 offset:20480
	global_load_lds_dwordx4 v138, s[62:63]
	s_add_i32 m0, s10, 0x2000
	ds_read_b128 v[220:223], v181 offset:21504
	global_load_lds_dwordx4 v142, s[62:63]
	s_mov_b32 m0, s29
	ds_read_b128 v[224:227], v181 offset:22528
	global_load_lds_dwordx4 v136, s[64:65]
	s_mov_b32 m0, s31
	ds_read_b128 v[228:231], v181 offset:23552
	global_load_lds_dwordx4 v140, s[64:65]
	s_waitcnt vmcnt(8)
	s_waitcnt lgkmcnt(0)
	s_barrier
	s_setprio 1
	s_waitcnt lgkmcnt(0)
	v_mfma_f32_16x16x32_bf16 v[60:63], v[132:135], v[200:203], v[60:63]
	v_mfma_f32_16x16x32_bf16 v[56:59], v[162:165], v[200:203], v[56:59]
	v_mfma_f32_16x16x32_bf16 v[44:47], v[132:135], v[208:211], v[44:47]
	v_mfma_f32_16x16x32_bf16 v[40:43], v[162:165], v[208:211], v[40:43]
	v_mfma_f32_16x16x32_bf16 v[28:31], v[132:135], v[216:219], v[28:31]
	v_mfma_f32_16x16x32_bf16 v[24:27], v[162:165], v[216:219], v[24:27]
	v_mfma_f32_16x16x32_bf16 v[12:15], v[132:135], v[224:227], v[12:15]
	v_mfma_f32_16x16x32_bf16 v[8:11], v[162:165], v[224:227], v[8:11]
	v_mfma_f32_16x16x32_bf16 v[60:63], v[158:161], v[204:207], v[60:63]
	v_mfma_f32_16x16x32_bf16 v[56:59], v[166:169], v[204:207], v[56:59]
	v_mfma_f32_16x16x32_bf16 v[44:47], v[158:161], v[212:215], v[44:47]
	v_mfma_f32_16x16x32_bf16 v[40:43], v[166:169], v[212:215], v[40:43]
	v_mfma_f32_16x16x32_bf16 v[28:31], v[158:161], v[220:223], v[28:31]
	v_mfma_f32_16x16x32_bf16 v[24:27], v[166:169], v[220:223], v[24:27]
	v_mfma_f32_16x16x32_bf16 v[12:15], v[158:161], v[228:231], v[12:15]
	v_mfma_f32_16x16x32_bf16 v[8:11], v[166:169], v[228:231], v[8:11]
	s_setprio 0
	s_setprio 1
	v_mfma_f32_16x16x32_bf16 v[52:55], v[184:187], v[200:203], v[52:55]
	v_mfma_f32_16x16x32_bf16 v[48:51], v[192:195], v[200:203], v[48:51]
	v_mfma_f32_16x16x32_bf16 v[36:39], v[184:187], v[208:211], v[36:39]
	v_mfma_f32_16x16x32_bf16 v[32:35], v[192:195], v[208:211], v[32:35]
	v_mfma_f32_16x16x32_bf16 v[20:23], v[184:187], v[216:219], v[20:23]
	v_mfma_f32_16x16x32_bf16 v[16:19], v[192:195], v[216:219], v[16:19]
	v_mfma_f32_16x16x32_bf16 v[4:7], v[184:187], v[224:227], v[4:7]
	v_mfma_f32_16x16x32_bf16 v[0:3], v[192:195], v[224:227], v[0:3]
	v_mfma_f32_16x16x32_bf16 v[52:55], v[188:191], v[204:207], v[52:55]
	v_mfma_f32_16x16x32_bf16 v[48:51], v[196:199], v[204:207], v[48:51]
	v_mfma_f32_16x16x32_bf16 v[36:39], v[188:191], v[212:215], v[36:39]
	v_mfma_f32_16x16x32_bf16 v[32:35], v[196:199], v[212:215], v[32:35]
	v_mfma_f32_16x16x32_bf16 v[20:23], v[188:191], v[220:223], v[20:23]
	v_mfma_f32_16x16x32_bf16 v[16:19], v[196:199], v[220:223], v[16:19]
	v_mfma_f32_16x16x32_bf16 v[4:7], v[188:191], v[228:231], v[4:7]
	v_mfma_f32_16x16x32_bf16 v[0:3], v[196:199], v[228:231], v[0:3]
	s_setprio 0
	s_barrier
	s_add_i32 s10, 0, 0x18000
	v_add_u32_e32 v144, s10, v171
	s_add_i32 s93, 0, 0x1c000
	ds_read_b128 v[132:135], v144
	ds_read_b128 v[158:161], v144 offset:1024
	ds_read_b128 v[162:165], v144 offset:2048
	ds_read_b128 v[166:169], v144 offset:3072
	v_add_u32_e32 v144, s93, v171
	ds_read_b128 v[184:187], v144
	ds_read_b128 v[188:191], v144 offset:1024
	ds_read_b128 v[192:195], v144 offset:2048
	ds_read_b128 v[196:199], v144 offset:3072
	s_add_u32 s62, s64, 0x40000
	s_addc_u32 s63, s65, 0
	s_mov_b32 m0, s67
	ds_read_b128 v[200:203], v181 offset:32768
	ds_read_b128 v[204:207], v181 offset:33792
	ds_read_b128 v[208:211], v181 offset:34816
	ds_read_b128 v[212:215], v181 offset:35840
	ds_read_b128 v[216:219], v181 offset:36864
	ds_read_b128 v[220:223], v181 offset:37888
	ds_read_b128 v[224:227], v181 offset:38912
	global_load_lds_dwordx4 v136, s[62:63]
	s_mov_b32 m0, s68
	ds_read_b128 v[228:231], v181 offset:39936
	global_load_lds_dwordx4 v140, s[62:63]
	s_waitcnt vmcnt(8)
	s_waitcnt lgkmcnt(0)
	s_barrier
	s_setprio 1
	s_waitcnt lgkmcnt(0)
	v_mfma_f32_16x16x32_bf16 v[124:127], v[132:135], v[200:203], v[124:127]
	v_mfma_f32_16x16x32_bf16 v[120:123], v[162:165], v[200:203], v[120:123]
	v_mfma_f32_16x16x32_bf16 v[108:111], v[132:135], v[208:211], v[108:111]
	v_mfma_f32_16x16x32_bf16 v[104:107], v[162:165], v[208:211], v[104:107]
	v_mfma_f32_16x16x32_bf16 v[92:95], v[132:135], v[216:219], v[92:95]
	v_mfma_f32_16x16x32_bf16 v[88:91], v[162:165], v[216:219], v[88:91]
	v_mfma_f32_16x16x32_bf16 v[76:79], v[132:135], v[224:227], v[76:79]
	v_mfma_f32_16x16x32_bf16 v[72:75], v[162:165], v[224:227], v[72:75]
	v_mfma_f32_16x16x32_bf16 v[124:127], v[158:161], v[204:207], v[124:127]
	v_mfma_f32_16x16x32_bf16 v[120:123], v[166:169], v[204:207], v[120:123]
	v_mfma_f32_16x16x32_bf16 v[108:111], v[158:161], v[212:215], v[108:111]
	v_mfma_f32_16x16x32_bf16 v[104:107], v[166:169], v[212:215], v[104:107]
	v_mfma_f32_16x16x32_bf16 v[92:95], v[158:161], v[220:223], v[92:95]
	v_mfma_f32_16x16x32_bf16 v[88:91], v[166:169], v[220:223], v[88:91]
	v_mfma_f32_16x16x32_bf16 v[76:79], v[158:161], v[228:231], v[76:79]
	v_mfma_f32_16x16x32_bf16 v[72:75], v[166:169], v[228:231], v[72:75]
	s_setprio 0
	s_setprio 1
	v_mfma_f32_16x16x32_bf16 v[116:119], v[184:187], v[200:203], v[116:119]
	v_mfma_f32_16x16x32_bf16 v[112:115], v[192:195], v[200:203], v[112:115]
	v_mfma_f32_16x16x32_bf16 v[100:103], v[184:187], v[208:211], v[100:103]
	v_mfma_f32_16x16x32_bf16 v[96:99], v[192:195], v[208:211], v[96:99]
	v_mfma_f32_16x16x32_bf16 v[84:87], v[184:187], v[216:219], v[84:87]
	v_mfma_f32_16x16x32_bf16 v[80:83], v[192:195], v[216:219], v[80:83]
	v_mfma_f32_16x16x32_bf16 v[68:71], v[184:187], v[224:227], v[68:71]
	v_mfma_f32_16x16x32_bf16 v[64:67], v[192:195], v[224:227], v[64:67]
	v_mfma_f32_16x16x32_bf16 v[116:119], v[188:191], v[204:207], v[116:119]
	v_mfma_f32_16x16x32_bf16 v[112:115], v[196:199], v[204:207], v[112:115]
	v_mfma_f32_16x16x32_bf16 v[100:103], v[188:191], v[212:215], v[100:103]
	v_mfma_f32_16x16x32_bf16 v[96:99], v[196:199], v[212:215], v[96:99]
	v_mfma_f32_16x16x32_bf16 v[84:87], v[188:191], v[220:223], v[84:87]
	v_mfma_f32_16x16x32_bf16 v[80:83], v[196:199], v[220:223], v[80:83]
	v_mfma_f32_16x16x32_bf16 v[68:71], v[188:191], v[228:231], v[68:71]
	v_mfma_f32_16x16x32_bf16 v[64:67], v[196:199], v[228:231], v[64:67]
	s_setprio 0
	s_barrier
	s_add_i32 s10, s10, s66
	s_mov_b32 m0, s10
	ds_read_b128 v[200:203], v181 offset:49152
	ds_read_b128 v[204:207], v181 offset:50176
	ds_read_b128 v[208:211], v181 offset:51200
	global_load_lds_dwordx4 v138, s[60:61]
	s_add_i32 m0, s10, 0x2000
	ds_read_b128 v[212:215], v181 offset:52224
	global_load_lds_dwordx4 v142, s[60:61]
	s_add_u32 s60, s60, 0x40000
	s_addc_u32 s61, s61, 0
	s_add_i32 s10, s93, s66
	s_mov_b32 m0, s10
	ds_read_b128 v[216:219], v181 offset:53248
	global_load_lds_dwordx4 v138, s[60:61]
	s_add_i32 m0, s10, 0x2000
	ds_read_b128 v[220:223], v181 offset:54272
	global_load_lds_dwordx4 v142, s[60:61]
	s_mov_b32 m0, s73
	ds_read_b128 v[224:227], v181 offset:55296
	global_load_lds_dwordx4 v136, s[58:59]
	v_lshl_add_u64 v[232:233], s[58:59], 0, v[140:141]
	s_mov_b32 m0, s78
	ds_read_b128 v[228:231], v181 offset:56320
	global_load_lds_dwordx4 v[232:233], off
	s_waitcnt vmcnt(8)
	s_waitcnt lgkmcnt(0)
	s_barrier
	s_setprio 1
	s_waitcnt lgkmcnt(0)
	v_mfma_f32_16x16x32_bf16 v[60:63], v[132:135], v[200:203], v[60:63]
	v_mfma_f32_16x16x32_bf16 v[56:59], v[162:165], v[200:203], v[56:59]
	v_mfma_f32_16x16x32_bf16 v[44:47], v[132:135], v[208:211], v[44:47]
	v_mfma_f32_16x16x32_bf16 v[40:43], v[162:165], v[208:211], v[40:43]
	v_mfma_f32_16x16x32_bf16 v[28:31], v[132:135], v[216:219], v[28:31]
	v_mfma_f32_16x16x32_bf16 v[24:27], v[162:165], v[216:219], v[24:27]
	v_mfma_f32_16x16x32_bf16 v[12:15], v[132:135], v[224:227], v[12:15]
	v_mfma_f32_16x16x32_bf16 v[8:11], v[162:165], v[224:227], v[8:11]
	v_mfma_f32_16x16x32_bf16 v[60:63], v[158:161], v[204:207], v[60:63]
	v_mfma_f32_16x16x32_bf16 v[56:59], v[166:169], v[204:207], v[56:59]
	v_mfma_f32_16x16x32_bf16 v[44:47], v[158:161], v[212:215], v[44:47]
	v_mfma_f32_16x16x32_bf16 v[40:43], v[166:169], v[212:215], v[40:43]
	v_mfma_f32_16x16x32_bf16 v[28:31], v[158:161], v[220:223], v[28:31]
	v_mfma_f32_16x16x32_bf16 v[24:27], v[166:169], v[220:223], v[24:27]
	v_mfma_f32_16x16x32_bf16 v[12:15], v[158:161], v[228:231], v[12:15]
	v_mfma_f32_16x16x32_bf16 v[8:11], v[166:169], v[228:231], v[8:11]
	s_setprio 0
	s_setprio 1
	v_mfma_f32_16x16x32_bf16 v[52:55], v[184:187], v[200:203], v[52:55]
	v_mfma_f32_16x16x32_bf16 v[48:51], v[192:195], v[200:203], v[48:51]
	v_mfma_f32_16x16x32_bf16 v[36:39], v[184:187], v[208:211], v[36:39]
	v_mfma_f32_16x16x32_bf16 v[32:35], v[192:195], v[208:211], v[32:35]
	v_mfma_f32_16x16x32_bf16 v[20:23], v[184:187], v[216:219], v[20:23]
	v_mfma_f32_16x16x32_bf16 v[16:19], v[192:195], v[216:219], v[16:19]
	v_mfma_f32_16x16x32_bf16 v[4:7], v[184:187], v[224:227], v[4:7]
	v_mfma_f32_16x16x32_bf16 v[0:3], v[192:195], v[224:227], v[0:3]
	v_mfma_f32_16x16x32_bf16 v[52:55], v[188:191], v[204:207], v[52:55]
	v_mfma_f32_16x16x32_bf16 v[48:51], v[196:199], v[204:207], v[48:51]
	v_mfma_f32_16x16x32_bf16 v[36:39], v[188:191], v[212:215], v[36:39]
	v_mfma_f32_16x16x32_bf16 v[32:35], v[196:199], v[212:215], v[32:35]
	v_mfma_f32_16x16x32_bf16 v[20:23], v[188:191], v[220:223], v[20:23]
	v_mfma_f32_16x16x32_bf16 v[16:19], v[196:199], v[220:223], v[16:19]
	v_mfma_f32_16x16x32_bf16 v[4:7], v[188:191], v[228:231], v[4:7]
	v_mfma_f32_16x16x32_bf16 v[0:3], v[196:199], v[228:231], v[0:3]
	s_setprio 0
	s_barrier
	s_add_i32 s10, s92, 2
	s_add_u32 s56, s56, 0x100
	s_addc_u32 s57, s57, 0
	s_cmp_gt_u32 s92, 13
	s_mov_b32 s92, s10
	s_cbranch_scc1 .LBB0_169
.LBB0_163:
	s_add_u32 s64, s42, s56
	s_addc_u32 s65, s43, s57
	s_add_u32 s94, s38, s56
	s_addc_u32 s93, s39, s57
	s_add_u32 s58, s64, 0x180
	s_addc_u32 s59, s65, 0
	s_add_u32 s60, s94, 0x180
	s_addc_u32 s61, s93, 0
	s_add_u32 s64, s64, 0x100
	s_addc_u32 s65, s65, 0
	s_add_u32 s62, s94, 0x100
	s_addc_u32 s63, s93, 0
	s_cmpk_eq_i32 s56, 0x700
	s_cselect_b32 s58, s48, s58
	s_cselect_b32 s59, s49, s59
	s_cselect_b32 s60, s54, s60
	s_cselect_b32 s61, s55, s61
	s_cselect_b32 s64, s90, s64
	s_cselect_b32 s65, s23, s65
	s_cselect_b32 s62, s91, s62
	s_cselect_b32 s63, s21, s63
	s_branch .LBB0_162

.LBB0_713:
	s_add_u32 s19, s63, s6
	s_addc_u32 s29, s64, s7
	s_add_u32 s31, s65, s8
	s_addc_u32 s79, s66, s9
	s_ashr_i32 s23, s22, 31
	s_lshl_b64 s[6:7], s[22:23], 19
	s_add_u32 s24, s34, s6
	s_addc_u32 s25, s35, s7
	s_and_b64 s[8:9], s[4:5], exec
	s_cselect_b32 s23, s25, s45
	s_cselect_b32 s80, s24, s44
	s_ashr_i32 s21, s20, 31
	s_lshl_b64 s[8:9], s[20:21], 19
	s_add_u32 s26, s42, s8
	s_addc_u32 s27, s43, s9
	s_and_b64 s[36:37], s[4:5], exec
	s_cselect_b32 s21, s27, s39
	s_cselect_b32 s81, s26, s38
	s_add_u32 s36, s80, 0x80
	s_addc_u32 s37, s23, 0
	s_add_u32 s46, s81, 0x80
	s_addc_u32 s47, s21, 0
	v_lshl_add_u64 v[128:129], s[44:45], 0, v[156:157]
	v_lshl_add_u64 v[130:131], s[44:45], 0, v[158:159]
	s_mov_b32 s82, 0
	s_mov_b64 s[48:49], 0
	s_add_u32 s56, s44, s48
	s_addc_u32 s57, s45, s49
	s_add_u32 s84, s38, s48
	s_addc_u32 s83, s39, s49
	s_add_u32 s50, s56, 0x180
	s_addc_u32 s51, s57, 0
	s_add_u32 s52, s84, 0x180
	s_addc_u32 s53, s83, 0
	s_add_u32 s56, s56, 0x100
	s_addc_u32 s57, s57, 0
	s_add_u32 s54, s84, 0x100
	s_addc_u32 s55, s83, 0
	s_cmpk_eq_i32 s48, 0x700
	s_cselect_b32 s50, s36, s50
	s_cselect_b32 s51, s37, s51
	s_cselect_b32 s52, s46, s52
	s_cselect_b32 s53, s47, s53
	s_cselect_b32 s56, s80, s56
	s_cselect_b32 s57, s23, s57
	s_cselect_b32 s54, s81, s54
	s_cselect_b32 s55, s21, s55
	v_add_u32_e32 v164, s72, v171
	v_add_u32_e32 v168, s73, v171
	ds_read_b128 v[132:135], v164
	ds_read_b128 v[136:139], v164 offset:1024
	ds_read_b128 v[140:143], v164 offset:2048
	ds_read_b128 v[164:167], v164 offset:3072
	ds_read_b128 v[174:177], v168
	ds_read_b128 v[178:181], v168 offset:1024
	ds_read_b128 v[182:185], v168 offset:2048
	ds_read_b128 v[186:189], v168 offset:3072
	v_lshl_add_u64 v[168:169], v[128:129], 0, s[48:49]
	s_add_i32 m0, s59, 0xc000
	ds_read_b128 v[190:193], v172
	ds_read_b128 v[194:197], v172 offset:1024
	ds_read_b128 v[198:201], v172 offset:2048
	ds_read_b128 v[202:205], v172 offset:3072
	ds_read_b128 v[206:209], v172 offset:4096
	ds_read_b128 v[210:213], v172 offset:5120
	ds_read_b128 v[214:217], v172 offset:6144
	global_load_lds_dwordx4 v[168:169], off
	v_lshl_add_u64 v[168:169], v[130:131], 0, s[48:49]
	s_add_i32 m0, s59, 0xe000
	ds_read_b128 v[218:221], v172 offset:7168
	global_load_lds_dwordx4 v[168:169], off
	s_waitcnt vmcnt(8)
	s_waitcnt lgkmcnt(0)
	s_barrier
	s_setprio 1
	s_waitcnt lgkmcnt(0)
	v_mfma_f32_16x16x32_bf16 v[124:127], v[132:135], v[190:193], 0
	v_mfma_f32_16x16x32_bf16 v[120:123], v[140:143], v[190:193], 0
	v_mfma_f32_16x16x32_bf16 v[108:111], v[132:135], v[198:201], 0
	v_mfma_f32_16x16x32_bf16 v[104:107], v[140:143], v[198:201], 0
	v_mfma_f32_16x16x32_bf16 v[92:95], v[132:135], v[206:209], 0
	v_mfma_f32_16x16x32_bf16 v[88:91], v[140:143], v[206:209], 0
	v_mfma_f32_16x16x32_bf16 v[76:79], v[132:135], v[214:217], 0
	v_mfma_f32_16x16x32_bf16 v[72:75], v[140:143], v[214:217], 0
	v_mfma_f32_16x16x32_bf16 v[124:127], v[136:139], v[194:197], v[124:127]
	v_mfma_f32_16x16x32_bf16 v[120:123], v[164:167], v[194:197], v[120:123]
	v_mfma_f32_16x16x32_bf16 v[108:111], v[136:139], v[202:205], v[108:111]
	v_mfma_f32_16x16x32_bf16 v[104:107], v[164:167], v[202:205], v[104:107]
	v_mfma_f32_16x16x32_bf16 v[92:95], v[136:139], v[210:213], v[92:95]
	v_mfma_f32_16x16x32_bf16 v[88:91], v[164:167], v[210:213], v[88:91]
	v_mfma_f32_16x16x32_bf16 v[76:79], v[136:139], v[218:221], v[76:79]
	v_mfma_f32_16x16x32_bf16 v[72:75], v[164:167], v[218:221], v[72:75]
	s_setprio 0
	s_setprio 1
	v_mfma_f32_16x16x32_bf16 v[116:119], v[174:177], v[190:193], 0
	v_mfma_f32_16x16x32_bf16 v[112:115], v[182:185], v[190:193], 0
	v_mfma_f32_16x16x32_bf16 v[100:103], v[174:177], v[198:201], 0
	v_mfma_f32_16x16x32_bf16 v[96:99], v[182:185], v[198:201], 0
	v_mfma_f32_16x16x32_bf16 v[84:87], v[174:177], v[206:209], 0
	v_mfma_f32_16x16x32_bf16 v[80:83], v[182:185], v[206:209], 0
	v_mfma_f32_16x16x32_bf16 v[68:71], v[174:177], v[214:217], 0
	v_mfma_f32_16x16x32_bf16 v[64:67], v[182:185], v[214:217], 0
	v_mfma_f32_16x16x32_bf16 v[116:119], v[178:181], v[194:197], v[116:119]
	v_mfma_f32_16x16x32_bf16 v[112:115], v[186:189], v[194:197], v[112:115]
	v_mfma_f32_16x16x32_bf16 v[100:103], v[178:181], v[202:205], v[100:103]
	v_mfma_f32_16x16x32_bf16 v[96:99], v[186:189], v[202:205], v[96:99]
	v_mfma_f32_16x16x32_bf16 v[84:87], v[178:181], v[210:213], v[84:87]
	v_mfma_f32_16x16x32_bf16 v[80:83], v[186:189], v[210:213], v[80:83]
	v_mfma_f32_16x16x32_bf16 v[68:71], v[178:181], v[218:221], v[68:71]
	v_mfma_f32_16x16x32_bf16 v[64:67], v[186:189], v[218:221], v[64:67]
	s_setprio 0
	s_barrier
	s_add_i32 s10, s72, s58
	s_mov_b32 m0, s10
	ds_read_b128 v[190:193], v172 offset:16384
	ds_read_b128 v[194:197], v172 offset:17408
	ds_read_b128 v[198:201], v172 offset:18432
	global_load_lds_dwordx4 v146, s[54:55]
	s_add_i32 m0, s10, 0x2000
	ds_read_b128 v[202:205], v172 offset:19456
	global_load_lds_dwordx4 v150, s[54:55]
	s_add_u32 s54, s54, 0x40000
	s_addc_u32 s55, s55, 0
	s_add_i32 s10, s73, s58
	s_mov_b32 m0, s10
	ds_read_b128 v[206:209], v172 offset:20480
	global_load_lds_dwordx4 v146, s[54:55]
	s_add_i32 m0, s10, 0x2000
	ds_read_b128 v[210:213], v172 offset:21504
	global_load_lds_dwordx4 v150, s[54:55]
	s_mov_b32 m0, s59
	ds_read_b128 v[214:217], v172 offset:22528
	global_load_lds_dwordx4 v144, s[56:57]
	s_mov_b32 m0, s60
	ds_read_b128 v[218:221], v172 offset:23552
	global_load_lds_dwordx4 v148, s[56:57]
	s_waitcnt vmcnt(8)
	s_waitcnt lgkmcnt(0)
	s_barrier
	s_setprio 1
	s_waitcnt lgkmcnt(0)
	v_mfma_f32_16x16x32_bf16 v[60:63], v[132:135], v[190:193], 0
	v_mfma_f32_16x16x32_bf16 v[56:59], v[140:143], v[190:193], 0
	v_mfma_f32_16x16x32_bf16 v[44:47], v[132:135], v[198:201], 0
	v_mfma_f32_16x16x32_bf16 v[40:43], v[140:143], v[198:201], 0
	v_mfma_f32_16x16x32_bf16 v[28:31], v[132:135], v[206:209], 0
	v_mfma_f32_16x16x32_bf16 v[24:27], v[140:143], v[206:209], 0
	v_mfma_f32_16x16x32_bf16 v[12:15], v[132:135], v[214:217], 0
	v_mfma_f32_16x16x32_bf16 v[8:11], v[140:143], v[214:217], 0
	v_mfma_f32_16x16x32_bf16 v[60:63], v[136:139], v[194:197], v[60:63]
	v_mfma_f32_16x16x32_bf16 v[56:59], v[164:167], v[194:197], v[56:59]
	v_mfma_f32_16x16x32_bf16 v[44:47], v[136:139], v[202:205], v[44:47]
	v_mfma_f32_16x16x32_bf16 v[40:43], v[164:167], v[202:205], v[40:43]
	v_mfma_f32_16x16x32_bf16 v[28:31], v[136:139], v[210:213], v[28:31]
	v_mfma_f32_16x16x32_bf16 v[24:27], v[164:167], v[210:213], v[24:27]
	v_mfma_f32_16x16x32_bf16 v[12:15], v[136:139], v[218:221], v[12:15]
	v_mfma_f32_16x16x32_bf16 v[8:11], v[164:167], v[218:221], v[8:11]
	s_setprio 0
	s_setprio 1
	v_mfma_f32_16x16x32_bf16 v[52:55], v[174:177], v[190:193], 0
	v_mfma_f32_16x16x32_bf16 v[48:51], v[182:185], v[190:193], 0
	v_mfma_f32_16x16x32_bf16 v[36:39], v[174:177], v[198:201], 0
	v_mfma_f32_16x16x32_bf16 v[32:35], v[182:185], v[198:201], 0
	v_mfma_f32_16x16x32_bf16 v[20:23], v[174:177], v[206:209], 0
	v_mfma_f32_16x16x32_bf16 v[16:19], v[182:185], v[206:209], 0
	v_mfma_f32_16x16x32_bf16 v[4:7], v[174:177], v[214:217], 0
	v_mfma_f32_16x16x32_bf16 v[0:3], v[182:185], v[214:217], 0
	v_mfma_f32_16x16x32_bf16 v[52:55], v[178:181], v[194:197], v[52:55]
	v_mfma_f32_16x16x32_bf16 v[48:51], v[186:189], v[194:197], v[48:51]
	v_mfma_f32_16x16x32_bf16 v[36:39], v[178:181], v[202:205], v[36:39]
	v_mfma_f32_16x16x32_bf16 v[32:35], v[186:189], v[202:205], v[32:35]
	v_mfma_f32_16x16x32_bf16 v[20:23], v[178:181], v[210:213], v[20:23]
	v_mfma_f32_16x16x32_bf16 v[16:19], v[186:189], v[210:213], v[16:19]
	v_mfma_f32_16x16x32_bf16 v[4:7], v[178:181], v[218:221], v[4:7]
	v_mfma_f32_16x16x32_bf16 v[0:3], v[186:189], v[218:221], v[0:3]
	s_setprio 0
	s_barrier
	s_add_i32 s10, 0, 0x18000
	s_add_i32 s83, 0, 0x1c000
	v_add_u32_e32 v164, s10, v171
	v_add_u32_e32 v168, s83, v171
	ds_read_b128 v[132:135], v164
	ds_read_b128 v[136:139], v164 offset:1024
	ds_read_b128 v[140:143], v164 offset:2048
	ds_read_b128 v[164:167], v164 offset:3072
	ds_read_b128 v[174:177], v168
	ds_read_b128 v[178:181], v168 offset:1024
	ds_read_b128 v[182:185], v168 offset:2048
	ds_read_b128 v[186:189], v168 offset:3072
	s_add_u32 s54, s56, 0x40000
	s_addc_u32 s55, s57, 0
	s_mov_b32 m0, s61
	ds_read_b128 v[190:193], v172 offset:32768
	ds_read_b128 v[194:197], v172 offset:33792
	ds_read_b128 v[198:201], v172 offset:34816
	ds_read_b128 v[202:205], v172 offset:35840
	ds_read_b128 v[206:209], v172 offset:36864
	ds_read_b128 v[210:213], v172 offset:37888
	ds_read_b128 v[214:217], v172 offset:38912
	global_load_lds_dwordx4 v144, s[54:55]
	s_mov_b32 m0, s62
	ds_read_b128 v[218:221], v172 offset:39936
	global_load_lds_dwordx4 v148, s[54:55]
	s_waitcnt vmcnt(8)
	s_waitcnt lgkmcnt(0)
	s_barrier
	s_setprio 1
	s_waitcnt lgkmcnt(0)
	v_mfma_f32_16x16x32_bf16 v[124:127], v[132:135], v[190:193], v[124:127]
	v_mfma_f32_16x16x32_bf16 v[120:123], v[140:143], v[190:193], v[120:123]
	v_mfma_f32_16x16x32_bf16 v[108:111], v[132:135], v[198:201], v[108:111]
	v_mfma_f32_16x16x32_bf16 v[104:107], v[140:143], v[198:201], v[104:107]
	v_mfma_f32_16x16x32_bf16 v[92:95], v[132:135], v[206:209], v[92:95]
	v_mfma_f32_16x16x32_bf16 v[88:91], v[140:143], v[206:209], v[88:91]
	v_mfma_f32_16x16x32_bf16 v[76:79], v[132:135], v[214:217], v[76:79]
	v_mfma_f32_16x16x32_bf16 v[72:75], v[140:143], v[214:217], v[72:75]
	v_mfma_f32_16x16x32_bf16 v[124:127], v[136:139], v[194:197], v[124:127]
	v_mfma_f32_16x16x32_bf16 v[120:123], v[164:167], v[194:197], v[120:123]
	v_mfma_f32_16x16x32_bf16 v[108:111], v[136:139], v[202:205], v[108:111]
	v_mfma_f32_16x16x32_bf16 v[104:107], v[164:167], v[202:205], v[104:107]
	v_mfma_f32_16x16x32_bf16 v[92:95], v[136:139], v[210:213], v[92:95]
	v_mfma_f32_16x16x32_bf16 v[88:91], v[164:167], v[210:213], v[88:91]
	v_mfma_f32_16x16x32_bf16 v[76:79], v[136:139], v[218:221], v[76:79]
	v_mfma_f32_16x16x32_bf16 v[72:75], v[164:167], v[218:221], v[72:75]
	s_setprio 0
	s_setprio 1
	v_mfma_f32_16x16x32_bf16 v[116:119], v[174:177], v[190:193], v[116:119]
	v_mfma_f32_16x16x32_bf16 v[112:115], v[182:185], v[190:193], v[112:115]
	v_mfma_f32_16x16x32_bf16 v[100:103], v[174:177], v[198:201], v[100:103]
	v_mfma_f32_16x16x32_bf16 v[96:99], v[182:185], v[198:201], v[96:99]
	v_mfma_f32_16x16x32_bf16 v[84:87], v[174:177], v[206:209], v[84:87]
	v_mfma_f32_16x16x32_bf16 v[80:83], v[182:185], v[206:209], v[80:83]
	v_mfma_f32_16x16x32_bf16 v[68:71], v[174:177], v[214:217], v[68:71]
	v_mfma_f32_16x16x32_bf16 v[64:67], v[182:185], v[214:217], v[64:67]
	v_mfma_f32_16x16x32_bf16 v[116:119], v[178:181], v[194:197], v[116:119]
	v_mfma_f32_16x16x32_bf16 v[112:115], v[186:189], v[194:197], v[112:115]
	v_mfma_f32_16x16x32_bf16 v[100:103], v[178:181], v[202:205], v[100:103]
	v_mfma_f32_16x16x32_bf16 v[96:99], v[186:189], v[202:205], v[96:99]
	v_mfma_f32_16x16x32_bf16 v[84:87], v[178:181], v[210:213], v[84:87]
	v_mfma_f32_16x16x32_bf16 v[80:83], v[186:189], v[210:213], v[80:83]
	v_mfma_f32_16x16x32_bf16 v[68:71], v[178:181], v[218:221], v[68:71]
	v_mfma_f32_16x16x32_bf16 v[64:67], v[186:189], v[218:221], v[64:67]
	s_setprio 0
	s_barrier
	s_add_i32 s10, s10, s58
	s_mov_b32 m0, s10
	ds_read_b128 v[190:193], v172 offset:49152
	ds_read_b128 v[194:197], v172 offset:50176
	ds_read_b128 v[198:201], v172 offset:51200
	global_load_lds_dwordx4 v146, s[52:53]
	s_add_i32 m0, s10, 0x2000
	ds_read_b128 v[202:205], v172 offset:52224
	global_load_lds_dwordx4 v150, s[52:53]
	s_add_u32 s52, s52, 0x40000
	s_addc_u32 s53, s53, 0
	s_add_i32 s10, s83, s58
	s_mov_b32 m0, s10
	ds_read_b128 v[206:209], v172 offset:53248
	global_load_lds_dwordx4 v146, s[52:53]
	s_add_i32 m0, s10, 0x2000
	ds_read_b128 v[210:213], v172 offset:54272
	global_load_lds_dwordx4 v150, s[52:53]
	s_mov_b32 m0, s68
	ds_read_b128 v[214:217], v172 offset:55296
	global_load_lds_dwordx4 v144, s[50:51]
	s_mov_b32 m0, s69
	ds_read_b128 v[218:221], v172 offset:56320
	global_load_lds_dwordx4 v148, s[50:51]
	s_waitcnt vmcnt(8)
	s_waitcnt lgkmcnt(0)
	s_barrier
	s_setprio 1
	s_waitcnt lgkmcnt(0)
	v_mfma_f32_16x16x32_bf16 v[60:63], v[132:135], v[190:193], v[60:63]
	v_mfma_f32_16x16x32_bf16 v[56:59], v[140:143], v[190:193], v[56:59]
	v_mfma_f32_16x16x32_bf16 v[44:47], v[132:135], v[198:201], v[44:47]
	v_mfma_f32_16x16x32_bf16 v[40:43], v[140:143], v[198:201], v[40:43]
	v_mfma_f32_16x16x32_bf16 v[28:31], v[132:135], v[206:209], v[28:31]
	v_mfma_f32_16x16x32_bf16 v[24:27], v[140:143], v[206:209], v[24:27]
	v_mfma_f32_16x16x32_bf16 v[12:15], v[132:135], v[214:217], v[12:15]
	v_mfma_f32_16x16x32_bf16 v[8:11], v[140:143], v[214:217], v[8:11]
	v_mfma_f32_16x16x32_bf16 v[60:63], v[136:139], v[194:197], v[60:63]
	v_mfma_f32_16x16x32_bf16 v[56:59], v[164:167], v[194:197], v[56:59]
	v_mfma_f32_16x16x32_bf16 v[44:47], v[136:139], v[202:205], v[44:47]
	v_mfma_f32_16x16x32_bf16 v[40:43], v[164:167], v[202:205], v[40:43]
	v_mfma_f32_16x16x32_bf16 v[28:31], v[136:139], v[210:213], v[28:31]
	v_mfma_f32_16x16x32_bf16 v[24:27], v[164:167], v[210:213], v[24:27]
	v_mfma_f32_16x16x32_bf16 v[12:15], v[136:139], v[218:221], v[12:15]
	v_mfma_f32_16x16x32_bf16 v[8:11], v[164:167], v[218:221], v[8:11]
	s_setprio 0
	s_setprio 1
	v_mfma_f32_16x16x32_bf16 v[52:55], v[174:177], v[190:193], v[52:55]
	v_mfma_f32_16x16x32_bf16 v[48:51], v[182:185], v[190:193], v[48:51]
	v_mfma_f32_16x16x32_bf16 v[36:39], v[174:177], v[198:201], v[36:39]
	v_mfma_f32_16x16x32_bf16 v[32:35], v[182:185], v[198:201], v[32:35]
	v_mfma_f32_16x16x32_bf16 v[20:23], v[174:177], v[206:209], v[20:23]
	v_mfma_f32_16x16x32_bf16 v[16:19], v[182:185], v[206:209], v[16:19]
	v_mfma_f32_16x16x32_bf16 v[4:7], v[174:177], v[214:217], v[4:7]
	v_mfma_f32_16x16x32_bf16 v[0:3], v[182:185], v[214:217], v[0:3]
	v_mfma_f32_16x16x32_bf16 v[52:55], v[178:181], v[194:197], v[52:55]
	v_mfma_f32_16x16x32_bf16 v[48:51], v[186:189], v[194:197], v[48:51]
	v_mfma_f32_16x16x32_bf16 v[36:39], v[178:181], v[202:205], v[36:39]
	v_mfma_f32_16x16x32_bf16 v[32:35], v[186:189], v[202:205], v[32:35]
	v_mfma_f32_16x16x32_bf16 v[20:23], v[178:181], v[210:213], v[20:23]
	v_mfma_f32_16x16x32_bf16 v[16:19], v[186:189], v[210:213], v[16:19]
	v_mfma_f32_16x16x32_bf16 v[4:7], v[178:181], v[218:221], v[4:7]
	v_mfma_f32_16x16x32_bf16 v[0:3], v[186:189], v[218:221], v[0:3]
	s_setprio 0
	s_barrier
	s_add_i32 s10, s82, 2
	s_add_u32 s48, s48, 0x100
	s_addc_u32 s49, s49, 0
	s_cmp_gt_u32 s82, 13
	s_mov_b32 s82, s10
	s_cbranch_scc1 .LBB0_721
	s_branch .LBB0_715
.LBB0_714:
	v_add_u32_e32 v164, s72, v171
	v_add_u32_e32 v168, s73, v171
	ds_read_b128 v[132:135], v164
	ds_read_b128 v[136:139], v164 offset:1024
	ds_read_b128 v[140:143], v164 offset:2048
	ds_read_b128 v[164:167], v164 offset:3072
	ds_read_b128 v[174:177], v168
	ds_read_b128 v[178:181], v168 offset:1024
	ds_read_b128 v[182:185], v168 offset:2048
	ds_read_b128 v[186:189], v168 offset:3072
	v_lshl_add_u64 v[168:169], v[128:129], 0, s[48:49]
	s_add_i32 m0, s59, 0xc000
	ds_read_b128 v[190:193], v172
	ds_read_b128 v[194:197], v172 offset:1024
	ds_read_b128 v[198:201], v172 offset:2048
	ds_read_b128 v[202:205], v172 offset:3072
	ds_read_b128 v[206:209], v172 offset:4096
	ds_read_b128 v[210:213], v172 offset:5120
	ds_read_b128 v[214:217], v172 offset:6144
	global_load_lds_dwordx4 v[168:169], off
	v_lshl_add_u64 v[168:169], v[130:131], 0, s[48:49]
	s_add_i32 m0, s59, 0xe000
	ds_read_b128 v[218:221], v172 offset:7168
	global_load_lds_dwordx4 v[168:169], off
	s_waitcnt vmcnt(8)
	s_waitcnt lgkmcnt(0)
	s_barrier
	s_setprio 1
	s_waitcnt lgkmcnt(0)
	v_mfma_f32_16x16x32_bf16 v[124:127], v[132:135], v[190:193], v[124:127]
	v_mfma_f32_16x16x32_bf16 v[120:123], v[140:143], v[190:193], v[120:123]
	v_mfma_f32_16x16x32_bf16 v[108:111], v[132:135], v[198:201], v[108:111]
	v_mfma_f32_16x16x32_bf16 v[104:107], v[140:143], v[198:201], v[104:107]
	v_mfma_f32_16x16x32_bf16 v[92:95], v[132:135], v[206:209], v[92:95]
	v_mfma_f32_16x16x32_bf16 v[88:91], v[140:143], v[206:209], v[88:91]
	v_mfma_f32_16x16x32_bf16 v[76:79], v[132:135], v[214:217], v[76:79]
	v_mfma_f32_16x16x32_bf16 v[72:75], v[140:143], v[214:217], v[72:75]
	v_mfma_f32_16x16x32_bf16 v[124:127], v[136:139], v[194:197], v[124:127]
	v_mfma_f32_16x16x32_bf16 v[120:123], v[164:167], v[194:197], v[120:123]
	v_mfma_f32_16x16x32_bf16 v[108:111], v[136:139], v[202:205], v[108:111]
	v_mfma_f32_16x16x32_bf16 v[104:107], v[164:167], v[202:205], v[104:107]
	v_mfma_f32_16x16x32_bf16 v[92:95], v[136:139], v[210:213], v[92:95]
	v_mfma_f32_16x16x32_bf16 v[88:91], v[164:167], v[210:213], v[88:91]
	v_mfma_f32_16x16x32_bf16 v[76:79], v[136:139], v[218:221], v[76:79]
	v_mfma_f32_16x16x32_bf16 v[72:75], v[164:167], v[218:221], v[72:75]
	s_setprio 0
	s_setprio 1
	v_mfma_f32_16x16x32_bf16 v[116:119], v[174:177], v[190:193], v[116:119]
	v_mfma_f32_16x16x32_bf16 v[112:115], v[182:185], v[190:193], v[112:115]
	v_mfma_f32_16x16x32_bf16 v[100:103], v[174:177], v[198:201], v[100:103]
	v_mfma_f32_16x16x32_bf16 v[96:99], v[182:185], v[198:201], v[96:99]
	v_mfma_f32_16x16x32_bf16 v[84:87], v[174:177], v[206:209], v[84:87]
	v_mfma_f32_16x16x32_bf16 v[80:83], v[182:185], v[206:209], v[80:83]
	v_mfma_f32_16x16x32_bf16 v[68:71], v[174:177], v[214:217], v[68:71]
	v_mfma_f32_16x16x32_bf16 v[64:67], v[182:185], v[214:217], v[64:67]
	v_mfma_f32_16x16x32_bf16 v[116:119], v[178:181], v[194:197], v[116:119]
	v_mfma_f32_16x16x32_bf16 v[112:115], v[186:189], v[194:197], v[112:115]
	v_mfma_f32_16x16x32_bf16 v[100:103], v[178:181], v[202:205], v[100:103]
	v_mfma_f32_16x16x32_bf16 v[96:99], v[186:189], v[202:205], v[96:99]
	v_mfma_f32_16x16x32_bf16 v[84:87], v[178:181], v[210:213], v[84:87]
	v_mfma_f32_16x16x32_bf16 v[80:83], v[186:189], v[210:213], v[80:83]
	v_mfma_f32_16x16x32_bf16 v[68:71], v[178:181], v[218:221], v[68:71]
	v_mfma_f32_16x16x32_bf16 v[64:67], v[186:189], v[218:221], v[64:67]
	s_setprio 0
	s_barrier
	s_add_i32 s10, s72, s58
	s_mov_b32 m0, s10
	ds_read_b128 v[190:193], v172 offset:16384
	ds_read_b128 v[194:197], v172 offset:17408
	ds_read_b128 v[198:201], v172 offset:18432
	global_load_lds_dwordx4 v146, s[54:55]
	s_add_i32 m0, s10, 0x2000
	ds_read_b128 v[202:205], v172 offset:19456
	global_load_lds_dwordx4 v150, s[54:55]
	s_add_u32 s54, s54, 0x40000
	s_addc_u32 s55, s55, 0
	s_add_i32 s10, s73, s58
	s_mov_b32 m0, s10
	ds_read_b128 v[206:209], v172 offset:20480
	global_load_lds_dwordx4 v146, s[54:55]
	s_add_i32 m0, s10, 0x2000
	ds_read_b128 v[210:213], v172 offset:21504
	global_load_lds_dwordx4 v150, s[54:55]
	s_mov_b32 m0, s59
	ds_read_b128 v[214:217], v172 offset:22528
	global_load_lds_dwordx4 v144, s[56:57]
	s_mov_b32 m0, s60
	ds_read_b128 v[218:221], v172 offset:23552
	global_load_lds_dwordx4 v148, s[56:57]
	s_waitcnt vmcnt(8)
	s_waitcnt lgkmcnt(0)
	s_barrier
	s_setprio 1
	s_waitcnt lgkmcnt(0)
	v_mfma_f32_16x16x32_bf16 v[60:63], v[132:135], v[190:193], v[60:63]
	v_mfma_f32_16x16x32_bf16 v[56:59], v[140:143], v[190:193], v[56:59]
	v_mfma_f32_16x16x32_bf16 v[44:47], v[132:135], v[198:201], v[44:47]
	v_mfma_f32_16x16x32_bf16 v[40:43], v[140:143], v[198:201], v[40:43]
	v_mfma_f32_16x16x32_bf16 v[28:31], v[132:135], v[206:209], v[28:31]
	v_mfma_f32_16x16x32_bf16 v[24:27], v[140:143], v[206:209], v[24:27]
	v_mfma_f32_16x16x32_bf16 v[12:15], v[132:135], v[214:217], v[12:15]
	v_mfma_f32_16x16x32_bf16 v[8:11], v[140:143], v[214:217], v[8:11]
	v_mfma_f32_16x16x32_bf16 v[60:63], v[136:139], v[194:197], v[60:63]
	v_mfma_f32_16x16x32_bf16 v[56:59], v[164:167], v[194:197], v[56:59]
	v_mfma_f32_16x16x32_bf16 v[44:47], v[136:139], v[202:205], v[44:47]
	v_mfma_f32_16x16x32_bf16 v[40:43], v[164:167], v[202:205], v[40:43]
	v_mfma_f32_16x16x32_bf16 v[28:31], v[136:139], v[210:213], v[28:31]
	v_mfma_f32_16x16x32_bf16 v[24:27], v[164:167], v[210:213], v[24:27]
	v_mfma_f32_16x16x32_bf16 v[12:15], v[136:139], v[218:221], v[12:15]
	v_mfma_f32_16x16x32_bf16 v[8:11], v[164:167], v[218:221], v[8:11]
	s_setprio 0
	s_setprio 1
	v_mfma_f32_16x16x32_bf16 v[52:55], v[174:177], v[190:193], v[52:55]
	v_mfma_f32_16x16x32_bf16 v[48:51], v[182:185], v[190:193], v[48:51]
	v_mfma_f32_16x16x32_bf16 v[36:39], v[174:177], v[198:201], v[36:39]
	v_mfma_f32_16x16x32_bf16 v[32:35], v[182:185], v[198:201], v[32:35]
	v_mfma_f32_16x16x32_bf16 v[20:23], v[174:177], v[206:209], v[20:23]
	v_mfma_f32_16x16x32_bf16 v[16:19], v[182:185], v[206:209], v[16:19]
	v_mfma_f32_16x16x32_bf16 v[4:7], v[174:177], v[214:217], v[4:7]
	v_mfma_f32_16x16x32_bf16 v[0:3], v[182:185], v[214:217], v[0:3]
	v_mfma_f32_16x16x32_bf16 v[52:55], v[178:181], v[194:197], v[52:55]
	v_mfma_f32_16x16x32_bf16 v[48:51], v[186:189], v[194:197], v[48:51]
	v_mfma_f32_16x16x32_bf16 v[36:39], v[178:181], v[202:205], v[36:39]
	v_mfma_f32_16x16x32_bf16 v[32:35], v[186:189], v[202:205], v[32:35]
	v_mfma_f32_16x16x32_bf16 v[20:23], v[178:181], v[210:213], v[20:23]
	v_mfma_f32_16x16x32_bf16 v[16:19], v[186:189], v[210:213], v[16:19]
	v_mfma_f32_16x16x32_bf16 v[4:7], v[178:181], v[218:221], v[4:7]
	v_mfma_f32_16x16x32_bf16 v[0:3], v[186:189], v[218:221], v[0:3]
	s_setprio 0
	s_barrier
	s_add_i32 s10, 0, 0x18000
	s_add_i32 s83, 0, 0x1c000
	v_add_u32_e32 v164, s10, v171
	v_add_u32_e32 v168, s83, v171
	ds_read_b128 v[132:135], v164
	ds_read_b128 v[136:139], v164 offset:1024
	ds_read_b128 v[140:143], v164 offset:2048
	ds_read_b128 v[164:167], v164 offset:3072
	ds_read_b128 v[174:177], v168
	ds_read_b128 v[178:181], v168 offset:1024
	ds_read_b128 v[182:185], v168 offset:2048
	ds_read_b128 v[186:189], v168 offset:3072
	s_add_u32 s54, s56, 0x40000
	s_addc_u32 s55, s57, 0
	s_mov_b32 m0, s61
	ds_read_b128 v[190:193], v172 offset:32768
	ds_read_b128 v[194:197], v172 offset:33792
	ds_read_b128 v[198:201], v172 offset:34816
	ds_read_b128 v[202:205], v172 offset:35840
	ds_read_b128 v[206:209], v172 offset:36864
	ds_read_b128 v[210:213], v172 offset:37888
	ds_read_b128 v[214:217], v172 offset:38912
	global_load_lds_dwordx4 v144, s[54:55]
	s_mov_b32 m0, s62
	ds_read_b128 v[218:221], v172 offset:39936
	global_load_lds_dwordx4 v148, s[54:55]
	s_waitcnt vmcnt(8)
	s_waitcnt lgkmcnt(0)
	s_barrier
	s_setprio 1
	s_waitcnt lgkmcnt(0)
	v_mfma_f32_16x16x32_bf16 v[124:127], v[132:135], v[190:193], v[124:127]
	v_mfma_f32_16x16x32_bf16 v[120:123], v[140:143], v[190:193], v[120:123]
	v_mfma_f32_16x16x32_bf16 v[108:111], v[132:135], v[198:201], v[108:111]
	v_mfma_f32_16x16x32_bf16 v[104:107], v[140:143], v[198:201], v[104:107]
	v_mfma_f32_16x16x32_bf16 v[92:95], v[132:135], v[206:209], v[92:95]
	v_mfma_f32_16x16x32_bf16 v[88:91], v[140:143], v[206:209], v[88:91]
	v_mfma_f32_16x16x32_bf16 v[76:79], v[132:135], v[214:217], v[76:79]
	v_mfma_f32_16x16x32_bf16 v[72:75], v[140:143], v[214:217], v[72:75]
	v_mfma_f32_16x16x32_bf16 v[124:127], v[136:139], v[194:197], v[124:127]
	v_mfma_f32_16x16x32_bf16 v[120:123], v[164:167], v[194:197], v[120:123]
	v_mfma_f32_16x16x32_bf16 v[108:111], v[136:139], v[202:205], v[108:111]
	v_mfma_f32_16x16x32_bf16 v[104:107], v[164:167], v[202:205], v[104:107]
	v_mfma_f32_16x16x32_bf16 v[92:95], v[136:139], v[210:213], v[92:95]
	v_mfma_f32_16x16x32_bf16 v[88:91], v[164:167], v[210:213], v[88:91]
	v_mfma_f32_16x16x32_bf16 v[76:79], v[136:139], v[218:221], v[76:79]
	v_mfma_f32_16x16x32_bf16 v[72:75], v[164:167], v[218:221], v[72:75]
	s_setprio 0
	s_setprio 1
	v_mfma_f32_16x16x32_bf16 v[116:119], v[174:177], v[190:193], v[116:119]
	v_mfma_f32_16x16x32_bf16 v[112:115], v[182:185], v[190:193], v[112:115]
	v_mfma_f32_16x16x32_bf16 v[100:103], v[174:177], v[198:201], v[100:103]
	v_mfma_f32_16x16x32_bf16 v[96:99], v[182:185], v[198:201], v[96:99]
	v_mfma_f32_16x16x32_bf16 v[84:87], v[174:177], v[206:209], v[84:87]
	v_mfma_f32_16x16x32_bf16 v[80:83], v[182:185], v[206:209], v[80:83]
	v_mfma_f32_16x16x32_bf16 v[68:71], v[174:177], v[214:217], v[68:71]
	v_mfma_f32_16x16x32_bf16 v[64:67], v[182:185], v[214:217], v[64:67]
	v_mfma_f32_16x16x32_bf16 v[116:119], v[178:181], v[194:197], v[116:119]
	v_mfma_f32_16x16x32_bf16 v[112:115], v[186:189], v[194:197], v[112:115]
	v_mfma_f32_16x16x32_bf16 v[100:103], v[178:181], v[202:205], v[100:103]
	v_mfma_f32_16x16x32_bf16 v[96:99], v[186:189], v[202:205], v[96:99]
	v_mfma_f32_16x16x32_bf16 v[84:87], v[178:181], v[210:213], v[84:87]
	v_mfma_f32_16x16x32_bf16 v[80:83], v[186:189], v[210:213], v[80:83]
	v_mfma_f32_16x16x32_bf16 v[68:71], v[178:181], v[218:221], v[68:71]
	v_mfma_f32_16x16x32_bf16 v[64:67], v[186:189], v[218:221], v[64:67]
	s_setprio 0
	s_barrier
	s_add_i32 s10, s10, s58
	s_mov_b32 m0, s10
	ds_read_b128 v[190:193], v172 offset:49152
	ds_read_b128 v[194:197], v172 offset:50176
	ds_read_b128 v[198:201], v172 offset:51200
	global_load_lds_dwordx4 v146, s[52:53]
	s_add_i32 m0, s10, 0x2000
	ds_read_b128 v[202:205], v172 offset:52224
	global_load_lds_dwordx4 v150, s[52:53]
	s_add_u32 s52, s52, 0x40000
	s_addc_u32 s53, s53, 0
	s_add_i32 s10, s83, s58
	s_mov_b32 m0, s10
	ds_read_b128 v[206:209], v172 offset:53248
	global_load_lds_dwordx4 v146, s[52:53]
	s_add_i32 m0, s10, 0x2000
	ds_read_b128 v[210:213], v172 offset:54272
	global_load_lds_dwordx4 v150, s[52:53]
	s_mov_b32 m0, s68
	ds_read_b128 v[214:217], v172 offset:55296
	global_load_lds_dwordx4 v144, s[50:51]
	s_mov_b32 m0, s69
	ds_read_b128 v[218:221], v172 offset:56320
	global_load_lds_dwordx4 v148, s[50:51]
	s_waitcnt vmcnt(8)
	s_waitcnt lgkmcnt(0)
	s_barrier
	s_setprio 1
	s_waitcnt lgkmcnt(0)
	v_mfma_f32_16x16x32_bf16 v[60:63], v[132:135], v[190:193], v[60:63]
	v_mfma_f32_16x16x32_bf16 v[56:59], v[140:143], v[190:193], v[56:59]
	v_mfma_f32_16x16x32_bf16 v[44:47], v[132:135], v[198:201], v[44:47]
	v_mfma_f32_16x16x32_bf16 v[40:43], v[140:143], v[198:201], v[40:43]
	v_mfma_f32_16x16x32_bf16 v[28:31], v[132:135], v[206:209], v[28:31]
	v_mfma_f32_16x16x32_bf16 v[24:27], v[140:143], v[206:209], v[24:27]
	v_mfma_f32_16x16x32_bf16 v[12:15], v[132:135], v[214:217], v[12:15]
	v_mfma_f32_16x16x32_bf16 v[8:11], v[140:143], v[214:217], v[8:11]
	v_mfma_f32_16x16x32_bf16 v[60:63], v[136:139], v[194:197], v[60:63]
	v_mfma_f32_16x16x32_bf16 v[56:59], v[164:167], v[194:197], v[56:59]
	v_mfma_f32_16x16x32_bf16 v[44:47], v[136:139], v[202:205], v[44:47]
	v_mfma_f32_16x16x32_bf16 v[40:43], v[164:167], v[202:205], v[40:43]
	v_mfma_f32_16x16x32_bf16 v[28:31], v[136:139], v[210:213], v[28:31]
	v_mfma_f32_16x16x32_bf16 v[24:27], v[164:167], v[210:213], v[24:27]
	v_mfma_f32_16x16x32_bf16 v[12:15], v[136:139], v[218:221], v[12:15]
	v_mfma_f32_16x16x32_bf16 v[8:11], v[164:167], v[218:221], v[8:11]
	s_setprio 0
	s_setprio 1
	v_mfma_f32_16x16x32_bf16 v[52:55], v[174:177], v[190:193], v[52:55]
	v_mfma_f32_16x16x32_bf16 v[48:51], v[182:185], v[190:193], v[48:51]
	v_mfma_f32_16x16x32_bf16 v[36:39], v[174:177], v[198:201], v[36:39]
	v_mfma_f32_16x16x32_bf16 v[32:35], v[182:185], v[198:201], v[32:35]
	v_mfma_f32_16x16x32_bf16 v[20:23], v[174:177], v[206:209], v[20:23]
	v_mfma_f32_16x16x32_bf16 v[16:19], v[182:185], v[206:209], v[16:19]
	v_mfma_f32_16x16x32_bf16 v[4:7], v[174:177], v[214:217], v[4:7]
	v_mfma_f32_16x16x32_bf16 v[0:3], v[182:185], v[214:217], v[0:3]
	v_mfma_f32_16x16x32_bf16 v[52:55], v[178:181], v[194:197], v[52:55]
	v_mfma_f32_16x16x32_bf16 v[48:51], v[186:189], v[194:197], v[48:51]
	v_mfma_f32_16x16x32_bf16 v[36:39], v[178:181], v[202:205], v[36:39]
	v_mfma_f32_16x16x32_bf16 v[32:35], v[186:189], v[202:205], v[32:35]
	v_mfma_f32_16x16x32_bf16 v[20:23], v[178:181], v[210:213], v[20:23]
	v_mfma_f32_16x16x32_bf16 v[16:19], v[186:189], v[210:213], v[16:19]
	v_mfma_f32_16x16x32_bf16 v[4:7], v[178:181], v[218:221], v[4:7]
	v_mfma_f32_16x16x32_bf16 v[0:3], v[186:189], v[218:221], v[0:3]
	s_setprio 0
	s_barrier
	s_add_i32 s10, s82, 2
	s_add_u32 s48, s48, 0x100
	s_addc_u32 s49, s49, 0
	s_cmp_gt_u32 s82, 13
	s_mov_b32 s82, s10
	s_cbranch_scc1 .LBB0_721
.LBB0_715:
	s_add_u32 s56, s44, s48
	s_addc_u32 s57, s45, s49
	s_add_u32 s84, s38, s48
	s_addc_u32 s83, s39, s49
	s_add_u32 s50, s56, 0x180
	s_addc_u32 s51, s57, 0
	s_add_u32 s52, s84, 0x180
	s_addc_u32 s53, s83, 0
	s_add_u32 s56, s56, 0x100
	s_addc_u32 s57, s57, 0
	s_add_u32 s54, s84, 0x100
	s_addc_u32 s55, s83, 0
	s_cmpk_eq_i32 s48, 0x700
	s_cselect_b32 s50, s36, s50
	s_cselect_b32 s51, s37, s51
	s_cselect_b32 s52, s46, s52
	s_cselect_b32 s53, s47, s53
	s_cselect_b32 s56, s80, s56
	s_cselect_b32 s57, s23, s57
	s_cselect_b32 s54, s81, s54
	s_cselect_b32 s55, s21, s55
	s_branch .LBB0_714

.LBB0_805:
	s_add_u32 s27, s61, s4
	s_addc_u32 s72, s62, s5
	s_add_u32 s73, s63, s6
	s_addc_u32 s78, s64, s7
	s_ashr_i32 s21, s20, 31
	s_lshl_b64 s[4:5], s[20:21], 19
	s_add_u32 s22, s40, s4
	s_addc_u32 s23, s41, s5
	s_and_b64 s[6:7], s[0:1], exec
	s_cselect_b32 s21, s23, s31
	s_cselect_b32 s79, s22, s30
	s_ashr_i32 s19, s18, 31
	s_lshl_b64 s[6:7], s[18:19], 19
	s_add_u32 s24, s42, s6
	s_addc_u32 s25, s43, s7
	s_and_b64 s[36:37], s[0:1], exec
	s_cselect_b32 s19, s25, s29
	s_cselect_b32 s80, s24, s28
	s_add_u32 s36, s79, 0x80
	s_addc_u32 s37, s21, 0
	s_add_u32 s38, s80, 0x80
	s_addc_u32 s39, s19, 0
	v_lshl_add_u64 v[148:149], s[30:31], 0, v[140:141]
	v_lshl_add_u64 v[150:151], s[30:31], 0, v[142:143]
	s_mov_b32 s81, 0
	s_mov_b64 s[44:45], 0
	s_add_u32 s52, s30, s44
	s_addc_u32 s53, s31, s45
	s_add_u32 s83, s28, s44
	s_addc_u32 s82, s29, s45
	s_add_u32 s46, s52, 0x180
	s_addc_u32 s47, s53, 0
	s_add_u32 s48, s83, 0x180
	s_addc_u32 s49, s82, 0
	s_add_u32 s52, s52, 0x100
	s_addc_u32 s53, s53, 0
	s_add_u32 s50, s83, 0x100
	s_addc_u32 s51, s82, 0
	s_cmpk_eq_i32 s44, 0x700
	s_cselect_b32 s46, s36, s46
	s_cselect_b32 s47, s37, s47
	s_cselect_b32 s48, s38, s48
	s_cselect_b32 s49, s39, s49
	s_cselect_b32 s52, s79, s52
	s_cselect_b32 s53, s21, s53
	s_cselect_b32 s50, s80, s50
	s_cselect_b32 s51, s19, s51
	v_add_u32_e32 v152, s68, v157
	ds_read_b128 v[166:169], v152
	ds_read_b128 v[170:173], v152 offset:1024
	ds_read_b128 v[174:177], v152 offset:2048
	ds_read_b128 v[178:181], v152 offset:3072
	v_add_u32_e32 v152, s69, v157
	ds_read_b128 v[182:185], v152
	ds_read_b128 v[186:189], v152 offset:1024
	ds_read_b128 v[190:193], v152 offset:2048
	ds_read_b128 v[194:197], v152 offset:3072
	v_lshl_add_u64 v[154:155], v[148:149], 0, s[44:45]
	s_add_i32 m0, s57, 0xc000
	ds_read_b128 v[198:201], v161
	ds_read_b128 v[202:205], v161 offset:1024
	ds_read_b128 v[206:209], v161 offset:2048
	ds_read_b128 v[210:213], v161 offset:3072
	ds_read_b128 v[214:217], v161 offset:4096
	ds_read_b128 v[218:221], v161 offset:5120
	ds_read_b128 v[222:225], v161 offset:6144
	global_load_lds_dwordx4 v[154:155], off
	v_lshl_add_u64 v[154:155], v[150:151], 0, s[44:45]
	s_add_i32 m0, s57, 0xe000
	ds_read_b128 v[226:229], v161 offset:7168
	global_load_lds_dwordx4 v[154:155], off
	s_waitcnt vmcnt(8)
	s_waitcnt lgkmcnt(0)
	s_barrier
	s_setprio 1
	s_waitcnt lgkmcnt(0)
	v_mfma_f32_16x16x32_bf16 v[124:127], v[166:169], v[198:201], 0
	v_mfma_f32_16x16x32_bf16 v[120:123], v[174:177], v[198:201], 0
	v_mfma_f32_16x16x32_bf16 v[108:111], v[166:169], v[206:209], 0
	v_mfma_f32_16x16x32_bf16 v[104:107], v[174:177], v[206:209], 0
	v_mfma_f32_16x16x32_bf16 v[92:95], v[166:169], v[214:217], 0
	v_mfma_f32_16x16x32_bf16 v[88:91], v[174:177], v[214:217], 0
	v_mfma_f32_16x16x32_bf16 v[76:79], v[166:169], v[222:225], 0
	v_mfma_f32_16x16x32_bf16 v[72:75], v[174:177], v[222:225], 0
	v_mfma_f32_16x16x32_bf16 v[124:127], v[170:173], v[202:205], v[124:127]
	v_mfma_f32_16x16x32_bf16 v[120:123], v[178:181], v[202:205], v[120:123]
	v_mfma_f32_16x16x32_bf16 v[108:111], v[170:173], v[210:213], v[108:111]
	v_mfma_f32_16x16x32_bf16 v[104:107], v[178:181], v[210:213], v[104:107]
	v_mfma_f32_16x16x32_bf16 v[92:95], v[170:173], v[218:221], v[92:95]
	v_mfma_f32_16x16x32_bf16 v[88:91], v[178:181], v[218:221], v[88:91]
	v_mfma_f32_16x16x32_bf16 v[76:79], v[170:173], v[226:229], v[76:79]
	v_mfma_f32_16x16x32_bf16 v[72:75], v[178:181], v[226:229], v[72:75]
	s_setprio 0
	s_setprio 1
	v_mfma_f32_16x16x32_bf16 v[116:119], v[182:185], v[198:201], 0
	v_mfma_f32_16x16x32_bf16 v[112:115], v[190:193], v[198:201], 0
	v_mfma_f32_16x16x32_bf16 v[100:103], v[182:185], v[206:209], 0
	v_mfma_f32_16x16x32_bf16 v[96:99], v[190:193], v[206:209], 0
	v_mfma_f32_16x16x32_bf16 v[84:87], v[182:185], v[214:217], 0
	v_mfma_f32_16x16x32_bf16 v[80:83], v[190:193], v[214:217], 0
	v_mfma_f32_16x16x32_bf16 v[68:71], v[182:185], v[222:225], 0
	v_mfma_f32_16x16x32_bf16 v[64:67], v[190:193], v[222:225], 0
	v_mfma_f32_16x16x32_bf16 v[116:119], v[186:189], v[202:205], v[116:119]
	v_mfma_f32_16x16x32_bf16 v[112:115], v[194:197], v[202:205], v[112:115]
	v_mfma_f32_16x16x32_bf16 v[100:103], v[186:189], v[210:213], v[100:103]
	v_mfma_f32_16x16x32_bf16 v[96:99], v[194:197], v[210:213], v[96:99]
	v_mfma_f32_16x16x32_bf16 v[84:87], v[186:189], v[218:221], v[84:87]
	v_mfma_f32_16x16x32_bf16 v[80:83], v[194:197], v[218:221], v[80:83]
	v_mfma_f32_16x16x32_bf16 v[68:71], v[186:189], v[226:229], v[68:71]
	v_mfma_f32_16x16x32_bf16 v[64:67], v[194:197], v[226:229], v[64:67]
	s_setprio 0
	s_barrier
	s_add_i32 s8, s68, s54
	s_mov_b32 m0, s8
	ds_read_b128 v[198:201], v161 offset:16384
	ds_read_b128 v[202:205], v161 offset:17408
	ds_read_b128 v[206:209], v161 offset:18432
	global_load_lds_dwordx4 v128, s[50:51]
	s_add_i32 m0, s8, 0x2000
	ds_read_b128 v[210:213], v161 offset:19456
	global_load_lds_dwordx4 v130, s[50:51]
	s_add_u32 s50, s50, 0x40000
	s_addc_u32 s51, s51, 0
	s_add_i32 s8, s69, s54
	s_mov_b32 m0, s8
	ds_read_b128 v[214:217], v161 offset:20480
	global_load_lds_dwordx4 v128, s[50:51]
	s_add_i32 m0, s8, 0x2000
	ds_read_b128 v[218:221], v161 offset:21504
	global_load_lds_dwordx4 v130, s[50:51]
	s_mov_b32 m0, s57
	ds_read_b128 v[222:225], v161 offset:22528
	global_load_lds_dwordx4 v134, s[52:53]
	s_mov_b32 m0, s58
	ds_read_b128 v[226:229], v161 offset:23552
	global_load_lds_dwordx4 v132, s[52:53]
	s_waitcnt vmcnt(8)
	s_waitcnt lgkmcnt(0)
	s_barrier
	s_setprio 1
	s_waitcnt lgkmcnt(0)
	v_mfma_f32_16x16x32_bf16 v[60:63], v[166:169], v[198:201], 0
	v_mfma_f32_16x16x32_bf16 v[56:59], v[174:177], v[198:201], 0
	v_mfma_f32_16x16x32_bf16 v[44:47], v[166:169], v[206:209], 0
	v_mfma_f32_16x16x32_bf16 v[40:43], v[174:177], v[206:209], 0
	v_mfma_f32_16x16x32_bf16 v[28:31], v[166:169], v[214:217], 0
	v_mfma_f32_16x16x32_bf16 v[24:27], v[174:177], v[214:217], 0
	v_mfma_f32_16x16x32_bf16 v[12:15], v[166:169], v[222:225], 0
	v_mfma_f32_16x16x32_bf16 v[8:11], v[174:177], v[222:225], 0
	v_mfma_f32_16x16x32_bf16 v[60:63], v[170:173], v[202:205], v[60:63]
	v_mfma_f32_16x16x32_bf16 v[56:59], v[178:181], v[202:205], v[56:59]
	v_mfma_f32_16x16x32_bf16 v[44:47], v[170:173], v[210:213], v[44:47]
	v_mfma_f32_16x16x32_bf16 v[40:43], v[178:181], v[210:213], v[40:43]
	v_mfma_f32_16x16x32_bf16 v[28:31], v[170:173], v[218:221], v[28:31]
	v_mfma_f32_16x16x32_bf16 v[24:27], v[178:181], v[218:221], v[24:27]
	v_mfma_f32_16x16x32_bf16 v[12:15], v[170:173], v[226:229], v[12:15]
	v_mfma_f32_16x16x32_bf16 v[8:11], v[178:181], v[226:229], v[8:11]
	s_setprio 0
	s_setprio 1
	v_mfma_f32_16x16x32_bf16 v[52:55], v[182:185], v[198:201], 0
	v_mfma_f32_16x16x32_bf16 v[48:51], v[190:193], v[198:201], 0
	v_mfma_f32_16x16x32_bf16 v[36:39], v[182:185], v[206:209], 0
	v_mfma_f32_16x16x32_bf16 v[32:35], v[190:193], v[206:209], 0
	v_mfma_f32_16x16x32_bf16 v[20:23], v[182:185], v[214:217], 0
	v_mfma_f32_16x16x32_bf16 v[16:19], v[190:193], v[214:217], 0
	v_mfma_f32_16x16x32_bf16 v[4:7], v[182:185], v[222:225], 0
	v_mfma_f32_16x16x32_bf16 v[0:3], v[190:193], v[222:225], 0
	v_mfma_f32_16x16x32_bf16 v[52:55], v[186:189], v[202:205], v[52:55]
	v_mfma_f32_16x16x32_bf16 v[48:51], v[194:197], v[202:205], v[48:51]
	v_mfma_f32_16x16x32_bf16 v[36:39], v[186:189], v[210:213], v[36:39]
	v_mfma_f32_16x16x32_bf16 v[32:35], v[194:197], v[210:213], v[32:35]
	v_mfma_f32_16x16x32_bf16 v[20:23], v[186:189], v[218:221], v[20:23]
	v_mfma_f32_16x16x32_bf16 v[16:19], v[194:197], v[218:221], v[16:19]
	v_mfma_f32_16x16x32_bf16 v[4:7], v[186:189], v[226:229], v[4:7]
	v_mfma_f32_16x16x32_bf16 v[0:3], v[194:197], v[226:229], v[0:3]
	s_setprio 0
	s_barrier
	s_add_i32 s8, 0, 0x18000
	v_add_u32_e32 v152, s8, v157
	s_add_i32 s82, 0, 0x1c000
	ds_read_b128 v[166:169], v152
	ds_read_b128 v[170:173], v152 offset:1024
	ds_read_b128 v[174:177], v152 offset:2048
	ds_read_b128 v[178:181], v152 offset:3072
	v_add_u32_e32 v152, s82, v157
	ds_read_b128 v[182:185], v152
	ds_read_b128 v[186:189], v152 offset:1024
	ds_read_b128 v[190:193], v152 offset:2048
	ds_read_b128 v[194:197], v152 offset:3072
	s_add_u32 s50, s52, 0x40000
	s_addc_u32 s51, s53, 0
	s_mov_b32 m0, s59
	ds_read_b128 v[198:201], v161 offset:32768
	ds_read_b128 v[202:205], v161 offset:33792
	ds_read_b128 v[206:209], v161 offset:34816
	ds_read_b128 v[210:213], v161 offset:35840
	ds_read_b128 v[214:217], v161 offset:36864
	ds_read_b128 v[218:221], v161 offset:37888
	ds_read_b128 v[222:225], v161 offset:38912
	global_load_lds_dwordx4 v134, s[50:51]
	s_mov_b32 m0, s60
	ds_read_b128 v[226:229], v161 offset:39936
	global_load_lds_dwordx4 v132, s[50:51]
	s_waitcnt vmcnt(8)
	s_waitcnt lgkmcnt(0)
	s_barrier
	s_setprio 1
	s_waitcnt lgkmcnt(0)
	v_mfma_f32_16x16x32_bf16 v[124:127], v[166:169], v[198:201], v[124:127]
	v_mfma_f32_16x16x32_bf16 v[120:123], v[174:177], v[198:201], v[120:123]
	v_mfma_f32_16x16x32_bf16 v[108:111], v[166:169], v[206:209], v[108:111]
	v_mfma_f32_16x16x32_bf16 v[104:107], v[174:177], v[206:209], v[104:107]
	v_mfma_f32_16x16x32_bf16 v[92:95], v[166:169], v[214:217], v[92:95]
	v_mfma_f32_16x16x32_bf16 v[88:91], v[174:177], v[214:217], v[88:91]
	v_mfma_f32_16x16x32_bf16 v[76:79], v[166:169], v[222:225], v[76:79]
	v_mfma_f32_16x16x32_bf16 v[72:75], v[174:177], v[222:225], v[72:75]
	v_mfma_f32_16x16x32_bf16 v[124:127], v[170:173], v[202:205], v[124:127]
	v_mfma_f32_16x16x32_bf16 v[120:123], v[178:181], v[202:205], v[120:123]
	v_mfma_f32_16x16x32_bf16 v[108:111], v[170:173], v[210:213], v[108:111]
	v_mfma_f32_16x16x32_bf16 v[104:107], v[178:181], v[210:213], v[104:107]
	v_mfma_f32_16x16x32_bf16 v[92:95], v[170:173], v[218:221], v[92:95]
	v_mfma_f32_16x16x32_bf16 v[88:91], v[178:181], v[218:221], v[88:91]
	v_mfma_f32_16x16x32_bf16 v[76:79], v[170:173], v[226:229], v[76:79]
	v_mfma_f32_16x16x32_bf16 v[72:75], v[178:181], v[226:229], v[72:75]
	s_setprio 0
	s_setprio 1
	v_mfma_f32_16x16x32_bf16 v[116:119], v[182:185], v[198:201], v[116:119]
	v_mfma_f32_16x16x32_bf16 v[112:115], v[190:193], v[198:201], v[112:115]
	v_mfma_f32_16x16x32_bf16 v[100:103], v[182:185], v[206:209], v[100:103]
	v_mfma_f32_16x16x32_bf16 v[96:99], v[190:193], v[206:209], v[96:99]
	v_mfma_f32_16x16x32_bf16 v[84:87], v[182:185], v[214:217], v[84:87]
	v_mfma_f32_16x16x32_bf16 v[80:83], v[190:193], v[214:217], v[80:83]
	v_mfma_f32_16x16x32_bf16 v[68:71], v[182:185], v[222:225], v[68:71]
	v_mfma_f32_16x16x32_bf16 v[64:67], v[190:193], v[222:225], v[64:67]
	v_mfma_f32_16x16x32_bf16 v[116:119], v[186:189], v[202:205], v[116:119]
	v_mfma_f32_16x16x32_bf16 v[112:115], v[194:197], v[202:205], v[112:115]
	v_mfma_f32_16x16x32_bf16 v[100:103], v[186:189], v[210:213], v[100:103]
	v_mfma_f32_16x16x32_bf16 v[96:99], v[194:197], v[210:213], v[96:99]
	v_mfma_f32_16x16x32_bf16 v[84:87], v[186:189], v[218:221], v[84:87]
	v_mfma_f32_16x16x32_bf16 v[80:83], v[194:197], v[218:221], v[80:83]
	v_mfma_f32_16x16x32_bf16 v[68:71], v[186:189], v[226:229], v[68:71]
	v_mfma_f32_16x16x32_bf16 v[64:67], v[194:197], v[226:229], v[64:67]
	s_setprio 0
	s_barrier
	s_add_i32 s8, s8, s54
	s_mov_b32 m0, s8
	ds_read_b128 v[198:201], v161 offset:49152
	ds_read_b128 v[202:205], v161 offset:50176
	ds_read_b128 v[206:209], v161 offset:51200
	global_load_lds_dwordx4 v128, s[48:49]
	s_add_i32 m0, s8, 0x2000
	ds_read_b128 v[210:213], v161 offset:52224
	global_load_lds_dwordx4 v130, s[48:49]
	s_add_u32 s48, s48, 0x40000
	s_addc_u32 s49, s49, 0
	s_add_i32 s8, s82, s54
	s_mov_b32 m0, s8
	ds_read_b128 v[214:217], v161 offset:53248
	global_load_lds_dwordx4 v128, s[48:49]
	s_add_i32 m0, s8, 0x2000
	ds_read_b128 v[218:221], v161 offset:54272
	global_load_lds_dwordx4 v130, s[48:49]
	s_mov_b32 m0, s65
	ds_read_b128 v[222:225], v161 offset:55296
	global_load_lds_dwordx4 v134, s[46:47]
	s_mov_b32 m0, s66
	ds_read_b128 v[226:229], v161 offset:56320
	global_load_lds_dwordx4 v132, s[46:47]
	s_waitcnt vmcnt(8)
	s_waitcnt lgkmcnt(0)
	s_barrier
	s_setprio 1
	s_waitcnt lgkmcnt(0)
	v_mfma_f32_16x16x32_bf16 v[60:63], v[166:169], v[198:201], v[60:63]
	v_mfma_f32_16x16x32_bf16 v[56:59], v[174:177], v[198:201], v[56:59]
	v_mfma_f32_16x16x32_bf16 v[44:47], v[166:169], v[206:209], v[44:47]
	v_mfma_f32_16x16x32_bf16 v[40:43], v[174:177], v[206:209], v[40:43]
	v_mfma_f32_16x16x32_bf16 v[28:31], v[166:169], v[214:217], v[28:31]
	v_mfma_f32_16x16x32_bf16 v[24:27], v[174:177], v[214:217], v[24:27]
	v_mfma_f32_16x16x32_bf16 v[12:15], v[166:169], v[222:225], v[12:15]
	v_mfma_f32_16x16x32_bf16 v[8:11], v[174:177], v[222:225], v[8:11]
	v_mfma_f32_16x16x32_bf16 v[60:63], v[170:173], v[202:205], v[60:63]
	v_mfma_f32_16x16x32_bf16 v[56:59], v[178:181], v[202:205], v[56:59]
	v_mfma_f32_16x16x32_bf16 v[44:47], v[170:173], v[210:213], v[44:47]
	v_mfma_f32_16x16x32_bf16 v[40:43], v[178:181], v[210:213], v[40:43]
	v_mfma_f32_16x16x32_bf16 v[28:31], v[170:173], v[218:221], v[28:31]
	v_mfma_f32_16x16x32_bf16 v[24:27], v[178:181], v[218:221], v[24:27]
	v_mfma_f32_16x16x32_bf16 v[12:15], v[170:173], v[226:229], v[12:15]
	v_mfma_f32_16x16x32_bf16 v[8:11], v[178:181], v[226:229], v[8:11]
	s_setprio 0
	s_setprio 1
	v_mfma_f32_16x16x32_bf16 v[52:55], v[182:185], v[198:201], v[52:55]
	v_mfma_f32_16x16x32_bf16 v[48:51], v[190:193], v[198:201], v[48:51]
	v_mfma_f32_16x16x32_bf16 v[36:39], v[182:185], v[206:209], v[36:39]
	v_mfma_f32_16x16x32_bf16 v[32:35], v[190:193], v[206:209], v[32:35]
	v_mfma_f32_16x16x32_bf16 v[20:23], v[182:185], v[214:217], v[20:23]
	v_mfma_f32_16x16x32_bf16 v[16:19], v[190:193], v[214:217], v[16:19]
	v_mfma_f32_16x16x32_bf16 v[4:7], v[182:185], v[222:225], v[4:7]
	v_mfma_f32_16x16x32_bf16 v[0:3], v[190:193], v[222:225], v[0:3]
	v_mfma_f32_16x16x32_bf16 v[52:55], v[186:189], v[202:205], v[52:55]
	v_mfma_f32_16x16x32_bf16 v[48:51], v[194:197], v[202:205], v[48:51]
	v_mfma_f32_16x16x32_bf16 v[36:39], v[186:189], v[210:213], v[36:39]
	v_mfma_f32_16x16x32_bf16 v[32:35], v[194:197], v[210:213], v[32:35]
	v_mfma_f32_16x16x32_bf16 v[20:23], v[186:189], v[218:221], v[20:23]
	v_mfma_f32_16x16x32_bf16 v[16:19], v[194:197], v[218:221], v[16:19]
	v_mfma_f32_16x16x32_bf16 v[4:7], v[186:189], v[226:229], v[4:7]
	v_mfma_f32_16x16x32_bf16 v[0:3], v[194:197], v[226:229], v[0:3]
	s_setprio 0
	s_barrier
	s_add_i32 s8, s81, 2
	s_add_u32 s44, s44, 0x100
	s_addc_u32 s45, s45, 0
	s_cmp_gt_u32 s81, 13
	s_mov_b32 s81, s8
	s_cbranch_scc1 .LBB0_813
	s_branch .LBB0_807
.LBB0_806:
	v_add_u32_e32 v152, s68, v157
	ds_read_b128 v[166:169], v152
	ds_read_b128 v[170:173], v152 offset:1024
	ds_read_b128 v[174:177], v152 offset:2048
	ds_read_b128 v[178:181], v152 offset:3072
	v_add_u32_e32 v152, s69, v157
	ds_read_b128 v[182:185], v152
	ds_read_b128 v[186:189], v152 offset:1024
	ds_read_b128 v[190:193], v152 offset:2048
	ds_read_b128 v[194:197], v152 offset:3072
	v_lshl_add_u64 v[154:155], v[148:149], 0, s[44:45]
	s_add_i32 m0, s57, 0xc000
	ds_read_b128 v[198:201], v161
	ds_read_b128 v[202:205], v161 offset:1024
	ds_read_b128 v[206:209], v161 offset:2048
	ds_read_b128 v[210:213], v161 offset:3072
	ds_read_b128 v[214:217], v161 offset:4096
	ds_read_b128 v[218:221], v161 offset:5120
	ds_read_b128 v[222:225], v161 offset:6144
	global_load_lds_dwordx4 v[154:155], off
	v_lshl_add_u64 v[154:155], v[150:151], 0, s[44:45]
	s_add_i32 m0, s57, 0xe000
	ds_read_b128 v[226:229], v161 offset:7168
	global_load_lds_dwordx4 v[154:155], off
	s_waitcnt vmcnt(8)
	s_waitcnt lgkmcnt(0)
	s_barrier
	s_setprio 1
	s_waitcnt lgkmcnt(0)
	v_mfma_f32_16x16x32_bf16 v[124:127], v[166:169], v[198:201], v[124:127]
	v_mfma_f32_16x16x32_bf16 v[120:123], v[174:177], v[198:201], v[120:123]
	v_mfma_f32_16x16x32_bf16 v[108:111], v[166:169], v[206:209], v[108:111]
	v_mfma_f32_16x16x32_bf16 v[104:107], v[174:177], v[206:209], v[104:107]
	v_mfma_f32_16x16x32_bf16 v[92:95], v[166:169], v[214:217], v[92:95]
	v_mfma_f32_16x16x32_bf16 v[88:91], v[174:177], v[214:217], v[88:91]
	v_mfma_f32_16x16x32_bf16 v[76:79], v[166:169], v[222:225], v[76:79]
	v_mfma_f32_16x16x32_bf16 v[72:75], v[174:177], v[222:225], v[72:75]
	v_mfma_f32_16x16x32_bf16 v[124:127], v[170:173], v[202:205], v[124:127]
	v_mfma_f32_16x16x32_bf16 v[120:123], v[178:181], v[202:205], v[120:123]
	v_mfma_f32_16x16x32_bf16 v[108:111], v[170:173], v[210:213], v[108:111]
	v_mfma_f32_16x16x32_bf16 v[104:107], v[178:181], v[210:213], v[104:107]
	v_mfma_f32_16x16x32_bf16 v[92:95], v[170:173], v[218:221], v[92:95]
	v_mfma_f32_16x16x32_bf16 v[88:91], v[178:181], v[218:221], v[88:91]
	v_mfma_f32_16x16x32_bf16 v[76:79], v[170:173], v[226:229], v[76:79]
	v_mfma_f32_16x16x32_bf16 v[72:75], v[178:181], v[226:229], v[72:75]
	s_setprio 0
	s_setprio 1
	v_mfma_f32_16x16x32_bf16 v[116:119], v[182:185], v[198:201], v[116:119]
	v_mfma_f32_16x16x32_bf16 v[112:115], v[190:193], v[198:201], v[112:115]
	v_mfma_f32_16x16x32_bf16 v[100:103], v[182:185], v[206:209], v[100:103]
	v_mfma_f32_16x16x32_bf16 v[96:99], v[190:193], v[206:209], v[96:99]
	v_mfma_f32_16x16x32_bf16 v[84:87], v[182:185], v[214:217], v[84:87]
	v_mfma_f32_16x16x32_bf16 v[80:83], v[190:193], v[214:217], v[80:83]
	v_mfma_f32_16x16x32_bf16 v[68:71], v[182:185], v[222:225], v[68:71]
	v_mfma_f32_16x16x32_bf16 v[64:67], v[190:193], v[222:225], v[64:67]
	v_mfma_f32_16x16x32_bf16 v[116:119], v[186:189], v[202:205], v[116:119]
	v_mfma_f32_16x16x32_bf16 v[112:115], v[194:197], v[202:205], v[112:115]
	v_mfma_f32_16x16x32_bf16 v[100:103], v[186:189], v[210:213], v[100:103]
	v_mfma_f32_16x16x32_bf16 v[96:99], v[194:197], v[210:213], v[96:99]
	v_mfma_f32_16x16x32_bf16 v[84:87], v[186:189], v[218:221], v[84:87]
	v_mfma_f32_16x16x32_bf16 v[80:83], v[194:197], v[218:221], v[80:83]
	v_mfma_f32_16x16x32_bf16 v[68:71], v[186:189], v[226:229], v[68:71]
	v_mfma_f32_16x16x32_bf16 v[64:67], v[194:197], v[226:229], v[64:67]
	s_setprio 0
	s_barrier
	s_add_i32 s8, s68, s54
	s_mov_b32 m0, s8
	ds_read_b128 v[198:201], v161 offset:16384
	ds_read_b128 v[202:205], v161 offset:17408
	ds_read_b128 v[206:209], v161 offset:18432
	global_load_lds_dwordx4 v128, s[50:51]
	s_add_i32 m0, s8, 0x2000
	ds_read_b128 v[210:213], v161 offset:19456
	global_load_lds_dwordx4 v130, s[50:51]
	s_add_u32 s50, s50, 0x40000
	s_addc_u32 s51, s51, 0
	s_add_i32 s8, s69, s54
	s_mov_b32 m0, s8
	ds_read_b128 v[214:217], v161 offset:20480
	global_load_lds_dwordx4 v128, s[50:51]
	s_add_i32 m0, s8, 0x2000
	ds_read_b128 v[218:221], v161 offset:21504
	global_load_lds_dwordx4 v130, s[50:51]
	s_mov_b32 m0, s57
	ds_read_b128 v[222:225], v161 offset:22528
	global_load_lds_dwordx4 v134, s[52:53]
	s_mov_b32 m0, s58
	ds_read_b128 v[226:229], v161 offset:23552
	global_load_lds_dwordx4 v132, s[52:53]
	s_waitcnt vmcnt(8)
	s_waitcnt lgkmcnt(0)
	s_barrier
	s_setprio 1
	s_waitcnt lgkmcnt(0)
	v_mfma_f32_16x16x32_bf16 v[60:63], v[166:169], v[198:201], v[60:63]
	v_mfma_f32_16x16x32_bf16 v[56:59], v[174:177], v[198:201], v[56:59]
	v_mfma_f32_16x16x32_bf16 v[44:47], v[166:169], v[206:209], v[44:47]
	v_mfma_f32_16x16x32_bf16 v[40:43], v[174:177], v[206:209], v[40:43]
	v_mfma_f32_16x16x32_bf16 v[28:31], v[166:169], v[214:217], v[28:31]
	v_mfma_f32_16x16x32_bf16 v[24:27], v[174:177], v[214:217], v[24:27]
	v_mfma_f32_16x16x32_bf16 v[12:15], v[166:169], v[222:225], v[12:15]
	v_mfma_f32_16x16x32_bf16 v[8:11], v[174:177], v[222:225], v[8:11]
	v_mfma_f32_16x16x32_bf16 v[60:63], v[170:173], v[202:205], v[60:63]
	v_mfma_f32_16x16x32_bf16 v[56:59], v[178:181], v[202:205], v[56:59]
	v_mfma_f32_16x16x32_bf16 v[44:47], v[170:173], v[210:213], v[44:47]
	v_mfma_f32_16x16x32_bf16 v[40:43], v[178:181], v[210:213], v[40:43]
	v_mfma_f32_16x16x32_bf16 v[28:31], v[170:173], v[218:221], v[28:31]
	v_mfma_f32_16x16x32_bf16 v[24:27], v[178:181], v[218:221], v[24:27]
	v_mfma_f32_16x16x32_bf16 v[12:15], v[170:173], v[226:229], v[12:15]
	v_mfma_f32_16x16x32_bf16 v[8:11], v[178:181], v[226:229], v[8:11]
	s_setprio 0
	s_setprio 1
	v_mfma_f32_16x16x32_bf16 v[52:55], v[182:185], v[198:201], v[52:55]
	v_mfma_f32_16x16x32_bf16 v[48:51], v[190:193], v[198:201], v[48:51]
	v_mfma_f32_16x16x32_bf16 v[36:39], v[182:185], v[206:209], v[36:39]
	v_mfma_f32_16x16x32_bf16 v[32:35], v[190:193], v[206:209], v[32:35]
	v_mfma_f32_16x16x32_bf16 v[20:23], v[182:185], v[214:217], v[20:23]
	v_mfma_f32_16x16x32_bf16 v[16:19], v[190:193], v[214:217], v[16:19]
	v_mfma_f32_16x16x32_bf16 v[4:7], v[182:185], v[222:225], v[4:7]
	v_mfma_f32_16x16x32_bf16 v[0:3], v[190:193], v[222:225], v[0:3]
	v_mfma_f32_16x16x32_bf16 v[52:55], v[186:189], v[202:205], v[52:55]
	v_mfma_f32_16x16x32_bf16 v[48:51], v[194:197], v[202:205], v[48:51]
	v_mfma_f32_16x16x32_bf16 v[36:39], v[186:189], v[210:213], v[36:39]
	v_mfma_f32_16x16x32_bf16 v[32:35], v[194:197], v[210:213], v[32:35]
	v_mfma_f32_16x16x32_bf16 v[20:23], v[186:189], v[218:221], v[20:23]
	v_mfma_f32_16x16x32_bf16 v[16:19], v[194:197], v[218:221], v[16:19]
	v_mfma_f32_16x16x32_bf16 v[4:7], v[186:189], v[226:229], v[4:7]
	v_mfma_f32_16x16x32_bf16 v[0:3], v[194:197], v[226:229], v[0:3]
	s_setprio 0
	s_barrier
	s_add_i32 s8, 0, 0x18000
	v_add_u32_e32 v152, s8, v157
	s_add_i32 s82, 0, 0x1c000
	ds_read_b128 v[166:169], v152
	ds_read_b128 v[170:173], v152 offset:1024
	ds_read_b128 v[174:177], v152 offset:2048
	ds_read_b128 v[178:181], v152 offset:3072
	v_add_u32_e32 v152, s82, v157
	ds_read_b128 v[182:185], v152
	ds_read_b128 v[186:189], v152 offset:1024
	ds_read_b128 v[190:193], v152 offset:2048
	ds_read_b128 v[194:197], v152 offset:3072
	s_add_u32 s50, s52, 0x40000
	s_addc_u32 s51, s53, 0
	s_mov_b32 m0, s59
	ds_read_b128 v[198:201], v161 offset:32768
	ds_read_b128 v[202:205], v161 offset:33792
	ds_read_b128 v[206:209], v161 offset:34816
	ds_read_b128 v[210:213], v161 offset:35840
	ds_read_b128 v[214:217], v161 offset:36864
	ds_read_b128 v[218:221], v161 offset:37888
	ds_read_b128 v[222:225], v161 offset:38912
	global_load_lds_dwordx4 v134, s[50:51]
	s_mov_b32 m0, s60
	ds_read_b128 v[226:229], v161 offset:39936
	global_load_lds_dwordx4 v132, s[50:51]
	s_waitcnt vmcnt(8)
	s_waitcnt lgkmcnt(0)
	s_barrier
	s_setprio 1
	s_waitcnt lgkmcnt(0)
	v_mfma_f32_16x16x32_bf16 v[124:127], v[166:169], v[198:201], v[124:127]
	v_mfma_f32_16x16x32_bf16 v[120:123], v[174:177], v[198:201], v[120:123]
	v_mfma_f32_16x16x32_bf16 v[108:111], v[166:169], v[206:209], v[108:111]
	v_mfma_f32_16x16x32_bf16 v[104:107], v[174:177], v[206:209], v[104:107]
	v_mfma_f32_16x16x32_bf16 v[92:95], v[166:169], v[214:217], v[92:95]
	v_mfma_f32_16x16x32_bf16 v[88:91], v[174:177], v[214:217], v[88:91]
	v_mfma_f32_16x16x32_bf16 v[76:79], v[166:169], v[222:225], v[76:79]
	v_mfma_f32_16x16x32_bf16 v[72:75], v[174:177], v[222:225], v[72:75]
	v_mfma_f32_16x16x32_bf16 v[124:127], v[170:173], v[202:205], v[124:127]
	v_mfma_f32_16x16x32_bf16 v[120:123], v[178:181], v[202:205], v[120:123]
	v_mfma_f32_16x16x32_bf16 v[108:111], v[170:173], v[210:213], v[108:111]
	v_mfma_f32_16x16x32_bf16 v[104:107], v[178:181], v[210:213], v[104:107]
	v_mfma_f32_16x16x32_bf16 v[92:95], v[170:173], v[218:221], v[92:95]
	v_mfma_f32_16x16x32_bf16 v[88:91], v[178:181], v[218:221], v[88:91]
	v_mfma_f32_16x16x32_bf16 v[76:79], v[170:173], v[226:229], v[76:79]
	v_mfma_f32_16x16x32_bf16 v[72:75], v[178:181], v[226:229], v[72:75]
	s_setprio 0
	s_setprio 1
	v_mfma_f32_16x16x32_bf16 v[116:119], v[182:185], v[198:201], v[116:119]
	v_mfma_f32_16x16x32_bf16 v[112:115], v[190:193], v[198:201], v[112:115]
	v_mfma_f32_16x16x32_bf16 v[100:103], v[182:185], v[206:209], v[100:103]
	v_mfma_f32_16x16x32_bf16 v[96:99], v[190:193], v[206:209], v[96:99]
	v_mfma_f32_16x16x32_bf16 v[84:87], v[182:185], v[214:217], v[84:87]
	v_mfma_f32_16x16x32_bf16 v[80:83], v[190:193], v[214:217], v[80:83]
	v_mfma_f32_16x16x32_bf16 v[68:71], v[182:185], v[222:225], v[68:71]
	v_mfma_f32_16x16x32_bf16 v[64:67], v[190:193], v[222:225], v[64:67]
	v_mfma_f32_16x16x32_bf16 v[116:119], v[186:189], v[202:205], v[116:119]
	v_mfma_f32_16x16x32_bf16 v[112:115], v[194:197], v[202:205], v[112:115]
	v_mfma_f32_16x16x32_bf16 v[100:103], v[186:189], v[210:213], v[100:103]
	v_mfma_f32_16x16x32_bf16 v[96:99], v[194:197], v[210:213], v[96:99]
	v_mfma_f32_16x16x32_bf16 v[84:87], v[186:189], v[218:221], v[84:87]
	v_mfma_f32_16x16x32_bf16 v[80:83], v[194:197], v[218:221], v[80:83]
	v_mfma_f32_16x16x32_bf16 v[68:71], v[186:189], v[226:229], v[68:71]
	v_mfma_f32_16x16x32_bf16 v[64:67], v[194:197], v[226:229], v[64:67]
	s_setprio 0
	s_barrier
	s_add_i32 s8, s8, s54
	s_mov_b32 m0, s8
	ds_read_b128 v[198:201], v161 offset:49152
	ds_read_b128 v[202:205], v161 offset:50176
	ds_read_b128 v[206:209], v161 offset:51200
	global_load_lds_dwordx4 v128, s[48:49]
	s_add_i32 m0, s8, 0x2000
	ds_read_b128 v[210:213], v161 offset:52224
	global_load_lds_dwordx4 v130, s[48:49]
	s_add_u32 s48, s48, 0x40000
	s_addc_u32 s49, s49, 0
	s_add_i32 s8, s82, s54
	s_mov_b32 m0, s8
	ds_read_b128 v[214:217], v161 offset:53248
	global_load_lds_dwordx4 v128, s[48:49]
	s_add_i32 m0, s8, 0x2000
	ds_read_b128 v[218:221], v161 offset:54272
	global_load_lds_dwordx4 v130, s[48:49]
	s_mov_b32 m0, s65
	ds_read_b128 v[222:225], v161 offset:55296
	global_load_lds_dwordx4 v134, s[46:47]
	s_mov_b32 m0, s66
	ds_read_b128 v[226:229], v161 offset:56320
	global_load_lds_dwordx4 v132, s[46:47]
	s_waitcnt vmcnt(8)
	s_waitcnt lgkmcnt(0)
	s_barrier
	s_setprio 1
	s_waitcnt lgkmcnt(0)
	v_mfma_f32_16x16x32_bf16 v[60:63], v[166:169], v[198:201], v[60:63]
	v_mfma_f32_16x16x32_bf16 v[56:59], v[174:177], v[198:201], v[56:59]
	v_mfma_f32_16x16x32_bf16 v[44:47], v[166:169], v[206:209], v[44:47]
	v_mfma_f32_16x16x32_bf16 v[40:43], v[174:177], v[206:209], v[40:43]
	v_mfma_f32_16x16x32_bf16 v[28:31], v[166:169], v[214:217], v[28:31]
	v_mfma_f32_16x16x32_bf16 v[24:27], v[174:177], v[214:217], v[24:27]
	v_mfma_f32_16x16x32_bf16 v[12:15], v[166:169], v[222:225], v[12:15]
	v_mfma_f32_16x16x32_bf16 v[8:11], v[174:177], v[222:225], v[8:11]
	v_mfma_f32_16x16x32_bf16 v[60:63], v[170:173], v[202:205], v[60:63]
	v_mfma_f32_16x16x32_bf16 v[56:59], v[178:181], v[202:205], v[56:59]
	v_mfma_f32_16x16x32_bf16 v[44:47], v[170:173], v[210:213], v[44:47]
	v_mfma_f32_16x16x32_bf16 v[40:43], v[178:181], v[210:213], v[40:43]
	v_mfma_f32_16x16x32_bf16 v[28:31], v[170:173], v[218:221], v[28:31]
	v_mfma_f32_16x16x32_bf16 v[24:27], v[178:181], v[218:221], v[24:27]
	v_mfma_f32_16x16x32_bf16 v[12:15], v[170:173], v[226:229], v[12:15]
	v_mfma_f32_16x16x32_bf16 v[8:11], v[178:181], v[226:229], v[8:11]
	s_setprio 0
	s_setprio 1
	v_mfma_f32_16x16x32_bf16 v[52:55], v[182:185], v[198:201], v[52:55]
	v_mfma_f32_16x16x32_bf16 v[48:51], v[190:193], v[198:201], v[48:51]
	v_mfma_f32_16x16x32_bf16 v[36:39], v[182:185], v[206:209], v[36:39]
	v_mfma_f32_16x16x32_bf16 v[32:35], v[190:193], v[206:209], v[32:35]
	v_mfma_f32_16x16x32_bf16 v[20:23], v[182:185], v[214:217], v[20:23]
	v_mfma_f32_16x16x32_bf16 v[16:19], v[190:193], v[214:217], v[16:19]
	v_mfma_f32_16x16x32_bf16 v[4:7], v[182:185], v[222:225], v[4:7]
	v_mfma_f32_16x16x32_bf16 v[0:3], v[190:193], v[222:225], v[0:3]
	v_mfma_f32_16x16x32_bf16 v[52:55], v[186:189], v[202:205], v[52:55]
	v_mfma_f32_16x16x32_bf16 v[48:51], v[194:197], v[202:205], v[48:51]
	v_mfma_f32_16x16x32_bf16 v[36:39], v[186:189], v[210:213], v[36:39]
	v_mfma_f32_16x16x32_bf16 v[32:35], v[194:197], v[210:213], v[32:35]
	v_mfma_f32_16x16x32_bf16 v[20:23], v[186:189], v[218:221], v[20:23]
	v_mfma_f32_16x16x32_bf16 v[16:19], v[194:197], v[218:221], v[16:19]
	v_mfma_f32_16x16x32_bf16 v[4:7], v[186:189], v[226:229], v[4:7]
	v_mfma_f32_16x16x32_bf16 v[0:3], v[194:197], v[226:229], v[0:3]
	s_setprio 0
	s_barrier
	s_add_i32 s8, s81, 2
	s_add_u32 s44, s44, 0x100
	s_addc_u32 s45, s45, 0
	s_cmp_gt_u32 s81, 13
	s_mov_b32 s81, s8
	s_cbranch_scc1 .LBB0_813
.LBB0_807:
	s_add_u32 s52, s30, s44
	s_addc_u32 s53, s31, s45
	s_add_u32 s83, s28, s44
	s_addc_u32 s82, s29, s45
	s_add_u32 s46, s52, 0x180
	s_addc_u32 s47, s53, 0
	s_add_u32 s48, s83, 0x180
	s_addc_u32 s49, s82, 0
	s_add_u32 s52, s52, 0x100
	s_addc_u32 s53, s53, 0
	s_add_u32 s50, s83, 0x100
	s_addc_u32 s51, s82, 0
	s_cmpk_eq_i32 s44, 0x700
	s_cselect_b32 s46, s36, s46
	s_cselect_b32 s47, s37, s47
	s_cselect_b32 s48, s38, s48
	s_cselect_b32 s49, s39, s49
	s_cselect_b32 s52, s79, s52
	s_cselect_b32 s53, s21, s53
	s_cselect_b32 s50, s80, s50
	s_cselect_b32 s51, s19, s51
	s_branch .LBB0_806

.LBB0_895:
	s_add_u32 s70, s55, s28
	s_addc_u32 s71, s56, s29
	s_add_u32 s72, s57, s30
	s_addc_u32 s73, s58, s31
	s_add_u32 s28, s4, 0x80
	s_addc_u32 s29, s5, 0
	s_add_u32 s30, s20, 0x80
	s_addc_u32 s31, s21, 0
	v_lshl_add_u64 v[128:129], s[26:27], 0, v[148:149]
	v_lshl_add_u64 v[130:131], s[26:27], 0, v[150:151]
	s_mov_b32 s78, 0
	s_mov_b64 s[36:37], 0
	s_add_u32 s46, s26, s36
	s_addc_u32 s47, s27, s37
	s_add_u32 s80, s24, s36
	s_addc_u32 s79, s25, s37
	s_add_u32 s38, s46, 0x180
	s_addc_u32 s39, s47, 0
	s_add_u32 s40, s80, 0x180
	s_addc_u32 s41, s79, 0
	s_add_u32 s46, s46, 0x100
	s_addc_u32 s47, s47, 0
	s_add_u32 s44, s80, 0x100
	s_addc_u32 s45, s79, 0
	s_cmpk_eq_i32 s36, 0x1500
	s_cselect_b32 s38, s28, s38
	s_cselect_b32 s39, s29, s39
	s_cselect_b32 s40, s30, s40
	s_cselect_b32 s41, s31, s41
	s_cselect_b32 s46, s4, s46
	s_cselect_b32 s47, s5, s47
	s_cselect_b32 s44, s20, s44
	s_cselect_b32 s45, s21, s45
	v_add_u32_e32 v167, s64, v165
	ds_read_b128 v[132:135], v167
	ds_read_b128 v[156:159], v167 offset:1024
	ds_read_b128 v[160:163], v167 offset:2048
	ds_read_b128 v[168:171], v167 offset:3072
	v_add_u32_e32 v167, s65, v165
	ds_read_b128 v[172:175], v167
	ds_read_b128 v[176:179], v167 offset:1024
	ds_read_b128 v[180:183], v167 offset:2048
	ds_read_b128 v[184:187], v167 offset:3072
	v_lshl_add_u64 v[220:221], v[128:129], 0, s[36:37]
	s_add_i32 m0, s51, 0xc000
	ds_read_b128 v[188:191], v166
	ds_read_b128 v[192:195], v166 offset:1024
	ds_read_b128 v[196:199], v166 offset:2048
	ds_read_b128 v[200:203], v166 offset:3072
	ds_read_b128 v[204:207], v166 offset:4096
	ds_read_b128 v[208:211], v166 offset:5120
	ds_read_b128 v[212:215], v166 offset:6144
	global_load_lds_dwordx4 v[220:221], off
	v_lshl_add_u64 v[220:221], v[130:131], 0, s[36:37]
	s_add_i32 m0, s51, 0xe000
	ds_read_b128 v[216:219], v166 offset:7168
	global_load_lds_dwordx4 v[220:221], off
	s_waitcnt vmcnt(8)
	s_waitcnt lgkmcnt(0)
	s_barrier
	s_setprio 1
	s_waitcnt lgkmcnt(0)
	v_mfma_f32_16x16x32_bf16 v[124:127], v[132:135], v[188:191], 0
	v_mfma_f32_16x16x32_bf16 v[120:123], v[160:163], v[188:191], 0
	v_mfma_f32_16x16x32_bf16 v[108:111], v[132:135], v[196:199], 0
	v_mfma_f32_16x16x32_bf16 v[104:107], v[160:163], v[196:199], 0
	v_mfma_f32_16x16x32_bf16 v[92:95], v[132:135], v[204:207], 0
	v_mfma_f32_16x16x32_bf16 v[88:91], v[160:163], v[204:207], 0
	v_mfma_f32_16x16x32_bf16 v[76:79], v[132:135], v[212:215], 0
	v_mfma_f32_16x16x32_bf16 v[72:75], v[160:163], v[212:215], 0
	v_mfma_f32_16x16x32_bf16 v[124:127], v[156:159], v[192:195], v[124:127]
	v_mfma_f32_16x16x32_bf16 v[120:123], v[168:171], v[192:195], v[120:123]
	v_mfma_f32_16x16x32_bf16 v[108:111], v[156:159], v[200:203], v[108:111]
	v_mfma_f32_16x16x32_bf16 v[104:107], v[168:171], v[200:203], v[104:107]
	v_mfma_f32_16x16x32_bf16 v[92:95], v[156:159], v[208:211], v[92:95]
	v_mfma_f32_16x16x32_bf16 v[88:91], v[168:171], v[208:211], v[88:91]
	v_mfma_f32_16x16x32_bf16 v[76:79], v[156:159], v[216:219], v[76:79]
	v_mfma_f32_16x16x32_bf16 v[72:75], v[168:171], v[216:219], v[72:75]
	s_setprio 0
	s_setprio 1
	v_mfma_f32_16x16x32_bf16 v[116:119], v[172:175], v[188:191], 0
	v_mfma_f32_16x16x32_bf16 v[112:115], v[180:183], v[188:191], 0
	v_mfma_f32_16x16x32_bf16 v[100:103], v[172:175], v[196:199], 0
	v_mfma_f32_16x16x32_bf16 v[96:99], v[180:183], v[196:199], 0
	v_mfma_f32_16x16x32_bf16 v[84:87], v[172:175], v[204:207], 0
	v_mfma_f32_16x16x32_bf16 v[80:83], v[180:183], v[204:207], 0
	v_mfma_f32_16x16x32_bf16 v[68:71], v[172:175], v[212:215], 0
	v_mfma_f32_16x16x32_bf16 v[64:67], v[180:183], v[212:215], 0
	v_mfma_f32_16x16x32_bf16 v[116:119], v[176:179], v[192:195], v[116:119]
	v_mfma_f32_16x16x32_bf16 v[112:115], v[184:187], v[192:195], v[112:115]
	v_mfma_f32_16x16x32_bf16 v[100:103], v[176:179], v[200:203], v[100:103]
	v_mfma_f32_16x16x32_bf16 v[96:99], v[184:187], v[200:203], v[96:99]
	v_mfma_f32_16x16x32_bf16 v[84:87], v[176:179], v[208:211], v[84:87]
	v_mfma_f32_16x16x32_bf16 v[80:83], v[184:187], v[208:211], v[80:83]
	v_mfma_f32_16x16x32_bf16 v[68:71], v[176:179], v[216:219], v[68:71]
	v_mfma_f32_16x16x32_bf16 v[64:67], v[184:187], v[216:219], v[64:67]
	s_setprio 0
	s_barrier
	s_add_i32 s8, s64, s50
	s_mov_b32 m0, s8
	ds_read_b128 v[188:191], v166 offset:16384
	ds_read_b128 v[192:195], v166 offset:17408
	ds_read_b128 v[196:199], v166 offset:18432
	global_load_lds_dwordx4 v138, s[44:45]
	s_add_i32 m0, s8, 0x2000
	ds_read_b128 v[200:203], v166 offset:19456
	global_load_lds_dwordx4 v142, s[44:45]
	s_add_u32 s44, s44, 0xb0000
	s_addc_u32 s45, s45, 0
	s_add_i32 s8, s65, s50
	s_mov_b32 m0, s8
	ds_read_b128 v[204:207], v166 offset:20480
	global_load_lds_dwordx4 v138, s[44:45]
	s_add_i32 m0, s8, 0x2000
	ds_read_b128 v[208:211], v166 offset:21504
	global_load_lds_dwordx4 v142, s[44:45]
	s_mov_b32 m0, s51
	ds_read_b128 v[212:215], v166 offset:22528
	global_load_lds_dwordx4 v136, s[46:47]
	s_mov_b32 m0, s52
	ds_read_b128 v[216:219], v166 offset:23552
	global_load_lds_dwordx4 v140, s[46:47]
	s_waitcnt vmcnt(8)
	s_waitcnt lgkmcnt(0)
	s_barrier
	s_setprio 1
	s_waitcnt lgkmcnt(0)
	v_mfma_f32_16x16x32_bf16 v[60:63], v[132:135], v[188:191], 0
	v_mfma_f32_16x16x32_bf16 v[56:59], v[160:163], v[188:191], 0
	v_mfma_f32_16x16x32_bf16 v[44:47], v[132:135], v[196:199], 0
	v_mfma_f32_16x16x32_bf16 v[40:43], v[160:163], v[196:199], 0
	v_mfma_f32_16x16x32_bf16 v[28:31], v[132:135], v[204:207], 0
	v_mfma_f32_16x16x32_bf16 v[24:27], v[160:163], v[204:207], 0
	v_mfma_f32_16x16x32_bf16 v[12:15], v[132:135], v[212:215], 0
	v_mfma_f32_16x16x32_bf16 v[8:11], v[160:163], v[212:215], 0
	v_mfma_f32_16x16x32_bf16 v[60:63], v[156:159], v[192:195], v[60:63]
	v_mfma_f32_16x16x32_bf16 v[56:59], v[168:171], v[192:195], v[56:59]
	v_mfma_f32_16x16x32_bf16 v[44:47], v[156:159], v[200:203], v[44:47]
	v_mfma_f32_16x16x32_bf16 v[40:43], v[168:171], v[200:203], v[40:43]
	v_mfma_f32_16x16x32_bf16 v[28:31], v[156:159], v[208:211], v[28:31]
	v_mfma_f32_16x16x32_bf16 v[24:27], v[168:171], v[208:211], v[24:27]
	v_mfma_f32_16x16x32_bf16 v[12:15], v[156:159], v[216:219], v[12:15]
	v_mfma_f32_16x16x32_bf16 v[8:11], v[168:171], v[216:219], v[8:11]
	s_setprio 0
	s_setprio 1
	v_mfma_f32_16x16x32_bf16 v[52:55], v[172:175], v[188:191], 0
	v_mfma_f32_16x16x32_bf16 v[48:51], v[180:183], v[188:191], 0
	v_mfma_f32_16x16x32_bf16 v[36:39], v[172:175], v[196:199], 0
	v_mfma_f32_16x16x32_bf16 v[32:35], v[180:183], v[196:199], 0
	v_mfma_f32_16x16x32_bf16 v[20:23], v[172:175], v[204:207], 0
	v_mfma_f32_16x16x32_bf16 v[16:19], v[180:183], v[204:207], 0
	v_mfma_f32_16x16x32_bf16 v[4:7], v[172:175], v[212:215], 0
	v_mfma_f32_16x16x32_bf16 v[0:3], v[180:183], v[212:215], 0
	v_mfma_f32_16x16x32_bf16 v[52:55], v[176:179], v[192:195], v[52:55]
	v_mfma_f32_16x16x32_bf16 v[48:51], v[184:187], v[192:195], v[48:51]
	v_mfma_f32_16x16x32_bf16 v[36:39], v[176:179], v[200:203], v[36:39]
	v_mfma_f32_16x16x32_bf16 v[32:35], v[184:187], v[200:203], v[32:35]
	v_mfma_f32_16x16x32_bf16 v[20:23], v[176:179], v[208:211], v[20:23]
	v_mfma_f32_16x16x32_bf16 v[16:19], v[184:187], v[208:211], v[16:19]
	v_mfma_f32_16x16x32_bf16 v[4:7], v[176:179], v[216:219], v[4:7]
	v_mfma_f32_16x16x32_bf16 v[0:3], v[184:187], v[216:219], v[0:3]
	s_setprio 0
	s_barrier
	s_add_i32 s8, 0, 0x18000
	v_add_u32_e32 v167, s8, v165
	s_add_i32 s79, 0, 0x1c000
	ds_read_b128 v[132:135], v167
	ds_read_b128 v[156:159], v167 offset:1024
	ds_read_b128 v[160:163], v167 offset:2048
	ds_read_b128 v[168:171], v167 offset:3072
	v_add_u32_e32 v167, s79, v165
	ds_read_b128 v[172:175], v167
	ds_read_b128 v[176:179], v167 offset:1024
	ds_read_b128 v[180:183], v167 offset:2048
	ds_read_b128 v[184:187], v167 offset:3072
	s_add_u32 s44, s46, 0xb0000
	s_addc_u32 s45, s47, 0
	s_mov_b32 m0, s53
	ds_read_b128 v[188:191], v166 offset:32768
	ds_read_b128 v[192:195], v166 offset:33792
	ds_read_b128 v[196:199], v166 offset:34816
	ds_read_b128 v[200:203], v166 offset:35840
	ds_read_b128 v[204:207], v166 offset:36864
	ds_read_b128 v[208:211], v166 offset:37888
	ds_read_b128 v[212:215], v166 offset:38912
	global_load_lds_dwordx4 v136, s[44:45]
	s_mov_b32 m0, s54
	ds_read_b128 v[216:219], v166 offset:39936
	global_load_lds_dwordx4 v140, s[44:45]
	s_waitcnt vmcnt(8)
	s_waitcnt lgkmcnt(0)
	s_barrier
	s_setprio 1
	s_waitcnt lgkmcnt(0)
	v_mfma_f32_16x16x32_bf16 v[124:127], v[132:135], v[188:191], v[124:127]
	v_mfma_f32_16x16x32_bf16 v[120:123], v[160:163], v[188:191], v[120:123]
	v_mfma_f32_16x16x32_bf16 v[108:111], v[132:135], v[196:199], v[108:111]
	v_mfma_f32_16x16x32_bf16 v[104:107], v[160:163], v[196:199], v[104:107]
	v_mfma_f32_16x16x32_bf16 v[92:95], v[132:135], v[204:207], v[92:95]
	v_mfma_f32_16x16x32_bf16 v[88:91], v[160:163], v[204:207], v[88:91]
	v_mfma_f32_16x16x32_bf16 v[76:79], v[132:135], v[212:215], v[76:79]
	v_mfma_f32_16x16x32_bf16 v[72:75], v[160:163], v[212:215], v[72:75]
	v_mfma_f32_16x16x32_bf16 v[124:127], v[156:159], v[192:195], v[124:127]
	v_mfma_f32_16x16x32_bf16 v[120:123], v[168:171], v[192:195], v[120:123]
	v_mfma_f32_16x16x32_bf16 v[108:111], v[156:159], v[200:203], v[108:111]
	v_mfma_f32_16x16x32_bf16 v[104:107], v[168:171], v[200:203], v[104:107]
	v_mfma_f32_16x16x32_bf16 v[92:95], v[156:159], v[208:211], v[92:95]
	v_mfma_f32_16x16x32_bf16 v[88:91], v[168:171], v[208:211], v[88:91]
	v_mfma_f32_16x16x32_bf16 v[76:79], v[156:159], v[216:219], v[76:79]
	v_mfma_f32_16x16x32_bf16 v[72:75], v[168:171], v[216:219], v[72:75]
	s_setprio 0
	s_setprio 1
	v_mfma_f32_16x16x32_bf16 v[116:119], v[172:175], v[188:191], v[116:119]
	v_mfma_f32_16x16x32_bf16 v[112:115], v[180:183], v[188:191], v[112:115]
	v_mfma_f32_16x16x32_bf16 v[100:103], v[172:175], v[196:199], v[100:103]
	v_mfma_f32_16x16x32_bf16 v[96:99], v[180:183], v[196:199], v[96:99]
	v_mfma_f32_16x16x32_bf16 v[84:87], v[172:175], v[204:207], v[84:87]
	v_mfma_f32_16x16x32_bf16 v[80:83], v[180:183], v[204:207], v[80:83]
	v_mfma_f32_16x16x32_bf16 v[68:71], v[172:175], v[212:215], v[68:71]
	v_mfma_f32_16x16x32_bf16 v[64:67], v[180:183], v[212:215], v[64:67]
	v_mfma_f32_16x16x32_bf16 v[116:119], v[176:179], v[192:195], v[116:119]
	v_mfma_f32_16x16x32_bf16 v[112:115], v[184:187], v[192:195], v[112:115]
	v_mfma_f32_16x16x32_bf16 v[100:103], v[176:179], v[200:203], v[100:103]
	v_mfma_f32_16x16x32_bf16 v[96:99], v[184:187], v[200:203], v[96:99]
	v_mfma_f32_16x16x32_bf16 v[84:87], v[176:179], v[208:211], v[84:87]
	v_mfma_f32_16x16x32_bf16 v[80:83], v[184:187], v[208:211], v[80:83]
	v_mfma_f32_16x16x32_bf16 v[68:71], v[176:179], v[216:219], v[68:71]
	v_mfma_f32_16x16x32_bf16 v[64:67], v[184:187], v[216:219], v[64:67]
	s_setprio 0
	s_barrier
	s_add_i32 s8, s8, s50
	s_mov_b32 m0, s8
	ds_read_b128 v[188:191], v166 offset:49152
	ds_read_b128 v[192:195], v166 offset:50176
	ds_read_b128 v[196:199], v166 offset:51200
	global_load_lds_dwordx4 v138, s[40:41]
	s_add_i32 m0, s8, 0x2000
	ds_read_b128 v[200:203], v166 offset:52224
	global_load_lds_dwordx4 v142, s[40:41]
	s_add_u32 s40, s40, 0xb0000
	s_addc_u32 s41, s41, 0
	s_add_i32 s8, s79, s50
	s_mov_b32 m0, s8
	ds_read_b128 v[204:207], v166 offset:53248
	global_load_lds_dwordx4 v138, s[40:41]
	s_add_i32 m0, s8, 0x2000
	ds_read_b128 v[208:211], v166 offset:54272
	global_load_lds_dwordx4 v142, s[40:41]
	s_mov_b32 m0, s60
	ds_read_b128 v[212:215], v166 offset:55296
	global_load_lds_dwordx4 v136, s[38:39]
	s_mov_b32 m0, s61
	ds_read_b128 v[216:219], v166 offset:56320
	global_load_lds_dwordx4 v140, s[38:39]
	s_waitcnt vmcnt(8)
	s_waitcnt lgkmcnt(0)
	s_barrier
	s_setprio 1
	s_waitcnt lgkmcnt(0)
	v_mfma_f32_16x16x32_bf16 v[60:63], v[132:135], v[188:191], v[60:63]
	v_mfma_f32_16x16x32_bf16 v[56:59], v[160:163], v[188:191], v[56:59]
	v_mfma_f32_16x16x32_bf16 v[44:47], v[132:135], v[196:199], v[44:47]
	v_mfma_f32_16x16x32_bf16 v[40:43], v[160:163], v[196:199], v[40:43]
	v_mfma_f32_16x16x32_bf16 v[28:31], v[132:135], v[204:207], v[28:31]
	v_mfma_f32_16x16x32_bf16 v[24:27], v[160:163], v[204:207], v[24:27]
	v_mfma_f32_16x16x32_bf16 v[12:15], v[132:135], v[212:215], v[12:15]
	v_mfma_f32_16x16x32_bf16 v[8:11], v[160:163], v[212:215], v[8:11]
	v_mfma_f32_16x16x32_bf16 v[60:63], v[156:159], v[192:195], v[60:63]
	v_mfma_f32_16x16x32_bf16 v[56:59], v[168:171], v[192:195], v[56:59]
	v_mfma_f32_16x16x32_bf16 v[44:47], v[156:159], v[200:203], v[44:47]
	v_mfma_f32_16x16x32_bf16 v[40:43], v[168:171], v[200:203], v[40:43]
	v_mfma_f32_16x16x32_bf16 v[28:31], v[156:159], v[208:211], v[28:31]
	v_mfma_f32_16x16x32_bf16 v[24:27], v[168:171], v[208:211], v[24:27]
	v_mfma_f32_16x16x32_bf16 v[12:15], v[156:159], v[216:219], v[12:15]
	v_mfma_f32_16x16x32_bf16 v[8:11], v[168:171], v[216:219], v[8:11]
	s_setprio 0
	s_setprio 1
	v_mfma_f32_16x16x32_bf16 v[52:55], v[172:175], v[188:191], v[52:55]
	v_mfma_f32_16x16x32_bf16 v[48:51], v[180:183], v[188:191], v[48:51]
	v_mfma_f32_16x16x32_bf16 v[36:39], v[172:175], v[196:199], v[36:39]
	v_mfma_f32_16x16x32_bf16 v[32:35], v[180:183], v[196:199], v[32:35]
	v_mfma_f32_16x16x32_bf16 v[20:23], v[172:175], v[204:207], v[20:23]
	v_mfma_f32_16x16x32_bf16 v[16:19], v[180:183], v[204:207], v[16:19]
	v_mfma_f32_16x16x32_bf16 v[4:7], v[172:175], v[212:215], v[4:7]
	v_mfma_f32_16x16x32_bf16 v[0:3], v[180:183], v[212:215], v[0:3]
	v_mfma_f32_16x16x32_bf16 v[52:55], v[176:179], v[192:195], v[52:55]
	v_mfma_f32_16x16x32_bf16 v[48:51], v[184:187], v[192:195], v[48:51]
	v_mfma_f32_16x16x32_bf16 v[36:39], v[176:179], v[200:203], v[36:39]
	v_mfma_f32_16x16x32_bf16 v[32:35], v[184:187], v[200:203], v[32:35]
	v_mfma_f32_16x16x32_bf16 v[20:23], v[176:179], v[208:211], v[20:23]
	v_mfma_f32_16x16x32_bf16 v[16:19], v[184:187], v[208:211], v[16:19]
	v_mfma_f32_16x16x32_bf16 v[4:7], v[176:179], v[216:219], v[4:7]
	v_mfma_f32_16x16x32_bf16 v[0:3], v[184:187], v[216:219], v[0:3]
	s_setprio 0
	s_barrier
	s_add_i32 s8, s78, 2
	s_add_u32 s36, s36, 0x100
	s_addc_u32 s37, s37, 0
	s_cmp_gt_u32 s78, 41
	s_mov_b32 s78, s8
	s_cbranch_scc1 .LBB0_903
	s_branch .LBB0_897
.LBB0_896:
	v_add_u32_e32 v167, s64, v165
	ds_read_b128 v[132:135], v167
	ds_read_b128 v[156:159], v167 offset:1024
	ds_read_b128 v[160:163], v167 offset:2048
	ds_read_b128 v[168:171], v167 offset:3072
	v_add_u32_e32 v167, s65, v165
	ds_read_b128 v[172:175], v167
	ds_read_b128 v[176:179], v167 offset:1024
	ds_read_b128 v[180:183], v167 offset:2048
	ds_read_b128 v[184:187], v167 offset:3072
	v_lshl_add_u64 v[220:221], v[128:129], 0, s[36:37]
	s_add_i32 m0, s51, 0xc000
	ds_read_b128 v[188:191], v166
	ds_read_b128 v[192:195], v166 offset:1024
	ds_read_b128 v[196:199], v166 offset:2048
	ds_read_b128 v[200:203], v166 offset:3072
	ds_read_b128 v[204:207], v166 offset:4096
	ds_read_b128 v[208:211], v166 offset:5120
	ds_read_b128 v[212:215], v166 offset:6144
	global_load_lds_dwordx4 v[220:221], off
	v_lshl_add_u64 v[220:221], v[130:131], 0, s[36:37]
	s_add_i32 m0, s51, 0xe000
	ds_read_b128 v[216:219], v166 offset:7168
	global_load_lds_dwordx4 v[220:221], off
	s_waitcnt vmcnt(8)
	s_waitcnt lgkmcnt(0)
	s_barrier
	s_setprio 1
	s_waitcnt lgkmcnt(0)
	v_mfma_f32_16x16x32_bf16 v[124:127], v[132:135], v[188:191], v[124:127]
	v_mfma_f32_16x16x32_bf16 v[120:123], v[160:163], v[188:191], v[120:123]
	v_mfma_f32_16x16x32_bf16 v[108:111], v[132:135], v[196:199], v[108:111]
	v_mfma_f32_16x16x32_bf16 v[104:107], v[160:163], v[196:199], v[104:107]
	v_mfma_f32_16x16x32_bf16 v[92:95], v[132:135], v[204:207], v[92:95]
	v_mfma_f32_16x16x32_bf16 v[88:91], v[160:163], v[204:207], v[88:91]
	v_mfma_f32_16x16x32_bf16 v[76:79], v[132:135], v[212:215], v[76:79]
	v_mfma_f32_16x16x32_bf16 v[72:75], v[160:163], v[212:215], v[72:75]
	v_mfma_f32_16x16x32_bf16 v[124:127], v[156:159], v[192:195], v[124:127]
	v_mfma_f32_16x16x32_bf16 v[120:123], v[168:171], v[192:195], v[120:123]
	v_mfma_f32_16x16x32_bf16 v[108:111], v[156:159], v[200:203], v[108:111]
	v_mfma_f32_16x16x32_bf16 v[104:107], v[168:171], v[200:203], v[104:107]
	v_mfma_f32_16x16x32_bf16 v[92:95], v[156:159], v[208:211], v[92:95]
	v_mfma_f32_16x16x32_bf16 v[88:91], v[168:171], v[208:211], v[88:91]
	v_mfma_f32_16x16x32_bf16 v[76:79], v[156:159], v[216:219], v[76:79]
	v_mfma_f32_16x16x32_bf16 v[72:75], v[168:171], v[216:219], v[72:75]
	s_setprio 0
	s_setprio 1
	v_mfma_f32_16x16x32_bf16 v[116:119], v[172:175], v[188:191], v[116:119]
	v_mfma_f32_16x16x32_bf16 v[112:115], v[180:183], v[188:191], v[112:115]
	v_mfma_f32_16x16x32_bf16 v[100:103], v[172:175], v[196:199], v[100:103]
	v_mfma_f32_16x16x32_bf16 v[96:99], v[180:183], v[196:199], v[96:99]
	v_mfma_f32_16x16x32_bf16 v[84:87], v[172:175], v[204:207], v[84:87]
	v_mfma_f32_16x16x32_bf16 v[80:83], v[180:183], v[204:207], v[80:83]
	v_mfma_f32_16x16x32_bf16 v[68:71], v[172:175], v[212:215], v[68:71]
	v_mfma_f32_16x16x32_bf16 v[64:67], v[180:183], v[212:215], v[64:67]
	v_mfma_f32_16x16x32_bf16 v[116:119], v[176:179], v[192:195], v[116:119]
	v_mfma_f32_16x16x32_bf16 v[112:115], v[184:187], v[192:195], v[112:115]
	v_mfma_f32_16x16x32_bf16 v[100:103], v[176:179], v[200:203], v[100:103]
	v_mfma_f32_16x16x32_bf16 v[96:99], v[184:187], v[200:203], v[96:99]
	v_mfma_f32_16x16x32_bf16 v[84:87], v[176:179], v[208:211], v[84:87]
	v_mfma_f32_16x16x32_bf16 v[80:83], v[184:187], v[208:211], v[80:83]
	v_mfma_f32_16x16x32_bf16 v[68:71], v[176:179], v[216:219], v[68:71]
	v_mfma_f32_16x16x32_bf16 v[64:67], v[184:187], v[216:219], v[64:67]
	s_setprio 0
	s_barrier
	s_add_i32 s8, s64, s50
	s_mov_b32 m0, s8
	ds_read_b128 v[188:191], v166 offset:16384
	ds_read_b128 v[192:195], v166 offset:17408
	ds_read_b128 v[196:199], v166 offset:18432
	global_load_lds_dwordx4 v138, s[44:45]
	s_add_i32 m0, s8, 0x2000
	ds_read_b128 v[200:203], v166 offset:19456
	global_load_lds_dwordx4 v142, s[44:45]
	s_add_u32 s44, s44, 0xb0000
	s_addc_u32 s45, s45, 0
	s_add_i32 s8, s65, s50
	s_mov_b32 m0, s8
	ds_read_b128 v[204:207], v166 offset:20480
	global_load_lds_dwordx4 v138, s[44:45]
	s_add_i32 m0, s8, 0x2000
	ds_read_b128 v[208:211], v166 offset:21504
	global_load_lds_dwordx4 v142, s[44:45]
	s_mov_b32 m0, s51
	ds_read_b128 v[212:215], v166 offset:22528
	global_load_lds_dwordx4 v136, s[46:47]
	s_mov_b32 m0, s52
	ds_read_b128 v[216:219], v166 offset:23552
	global_load_lds_dwordx4 v140, s[46:47]
	s_waitcnt vmcnt(8)
	s_waitcnt lgkmcnt(0)
	s_barrier
	s_setprio 1
	s_waitcnt lgkmcnt(0)
	v_mfma_f32_16x16x32_bf16 v[60:63], v[132:135], v[188:191], v[60:63]
	v_mfma_f32_16x16x32_bf16 v[56:59], v[160:163], v[188:191], v[56:59]
	v_mfma_f32_16x16x32_bf16 v[44:47], v[132:135], v[196:199], v[44:47]
	v_mfma_f32_16x16x32_bf16 v[40:43], v[160:163], v[196:199], v[40:43]
	v_mfma_f32_16x16x32_bf16 v[28:31], v[132:135], v[204:207], v[28:31]
	v_mfma_f32_16x16x32_bf16 v[24:27], v[160:163], v[204:207], v[24:27]
	v_mfma_f32_16x16x32_bf16 v[12:15], v[132:135], v[212:215], v[12:15]
	v_mfma_f32_16x16x32_bf16 v[8:11], v[160:163], v[212:215], v[8:11]
	v_mfma_f32_16x16x32_bf16 v[60:63], v[156:159], v[192:195], v[60:63]
	v_mfma_f32_16x16x32_bf16 v[56:59], v[168:171], v[192:195], v[56:59]
	v_mfma_f32_16x16x32_bf16 v[44:47], v[156:159], v[200:203], v[44:47]
	v_mfma_f32_16x16x32_bf16 v[40:43], v[168:171], v[200:203], v[40:43]
	v_mfma_f32_16x16x32_bf16 v[28:31], v[156:159], v[208:211], v[28:31]
	v_mfma_f32_16x16x32_bf16 v[24:27], v[168:171], v[208:211], v[24:27]
	v_mfma_f32_16x16x32_bf16 v[12:15], v[156:159], v[216:219], v[12:15]
	v_mfma_f32_16x16x32_bf16 v[8:11], v[168:171], v[216:219], v[8:11]
	s_setprio 0
	s_setprio 1
	v_mfma_f32_16x16x32_bf16 v[52:55], v[172:175], v[188:191], v[52:55]
	v_mfma_f32_16x16x32_bf16 v[48:51], v[180:183], v[188:191], v[48:51]
	v_mfma_f32_16x16x32_bf16 v[36:39], v[172:175], v[196:199], v[36:39]
	v_mfma_f32_16x16x32_bf16 v[32:35], v[180:183], v[196:199], v[32:35]
	v_mfma_f32_16x16x32_bf16 v[20:23], v[172:175], v[204:207], v[20:23]
	v_mfma_f32_16x16x32_bf16 v[16:19], v[180:183], v[204:207], v[16:19]
	v_mfma_f32_16x16x32_bf16 v[4:7], v[172:175], v[212:215], v[4:7]
	v_mfma_f32_16x16x32_bf16 v[0:3], v[180:183], v[212:215], v[0:3]
	v_mfma_f32_16x16x32_bf16 v[52:55], v[176:179], v[192:195], v[52:55]
	v_mfma_f32_16x16x32_bf16 v[48:51], v[184:187], v[192:195], v[48:51]
	v_mfma_f32_16x16x32_bf16 v[36:39], v[176:179], v[200:203], v[36:39]
	v_mfma_f32_16x16x32_bf16 v[32:35], v[184:187], v[200:203], v[32:35]
	v_mfma_f32_16x16x32_bf16 v[20:23], v[176:179], v[208:211], v[20:23]
	v_mfma_f32_16x16x32_bf16 v[16:19], v[184:187], v[208:211], v[16:19]
	v_mfma_f32_16x16x32_bf16 v[4:7], v[176:179], v[216:219], v[4:7]
	v_mfma_f32_16x16x32_bf16 v[0:3], v[184:187], v[216:219], v[0:3]
	s_setprio 0
	s_barrier
	s_add_i32 s8, 0, 0x18000
	v_add_u32_e32 v167, s8, v165
	s_add_i32 s79, 0, 0x1c000
	ds_read_b128 v[132:135], v167
	ds_read_b128 v[156:159], v167 offset:1024
	ds_read_b128 v[160:163], v167 offset:2048
	ds_read_b128 v[168:171], v167 offset:3072
	v_add_u32_e32 v167, s79, v165
	ds_read_b128 v[172:175], v167
	ds_read_b128 v[176:179], v167 offset:1024
	ds_read_b128 v[180:183], v167 offset:2048
	ds_read_b128 v[184:187], v167 offset:3072
	s_add_u32 s44, s46, 0xb0000
	s_addc_u32 s45, s47, 0
	s_mov_b32 m0, s53
	ds_read_b128 v[188:191], v166 offset:32768
	ds_read_b128 v[192:195], v166 offset:33792
	ds_read_b128 v[196:199], v166 offset:34816
	ds_read_b128 v[200:203], v166 offset:35840
	ds_read_b128 v[204:207], v166 offset:36864
	ds_read_b128 v[208:211], v166 offset:37888
	ds_read_b128 v[212:215], v166 offset:38912
	global_load_lds_dwordx4 v136, s[44:45]
	s_mov_b32 m0, s54
	ds_read_b128 v[216:219], v166 offset:39936
	global_load_lds_dwordx4 v140, s[44:45]
	s_waitcnt vmcnt(8)
	s_waitcnt lgkmcnt(0)
	s_barrier
	s_setprio 1
	s_waitcnt lgkmcnt(0)
	v_mfma_f32_16x16x32_bf16 v[124:127], v[132:135], v[188:191], v[124:127]
	v_mfma_f32_16x16x32_bf16 v[120:123], v[160:163], v[188:191], v[120:123]
	v_mfma_f32_16x16x32_bf16 v[108:111], v[132:135], v[196:199], v[108:111]
	v_mfma_f32_16x16x32_bf16 v[104:107], v[160:163], v[196:199], v[104:107]
	v_mfma_f32_16x16x32_bf16 v[92:95], v[132:135], v[204:207], v[92:95]
	v_mfma_f32_16x16x32_bf16 v[88:91], v[160:163], v[204:207], v[88:91]
	v_mfma_f32_16x16x32_bf16 v[76:79], v[132:135], v[212:215], v[76:79]
	v_mfma_f32_16x16x32_bf16 v[72:75], v[160:163], v[212:215], v[72:75]
	v_mfma_f32_16x16x32_bf16 v[124:127], v[156:159], v[192:195], v[124:127]
	v_mfma_f32_16x16x32_bf16 v[120:123], v[168:171], v[192:195], v[120:123]
	v_mfma_f32_16x16x32_bf16 v[108:111], v[156:159], v[200:203], v[108:111]
	v_mfma_f32_16x16x32_bf16 v[104:107], v[168:171], v[200:203], v[104:107]
	v_mfma_f32_16x16x32_bf16 v[92:95], v[156:159], v[208:211], v[92:95]
	v_mfma_f32_16x16x32_bf16 v[88:91], v[168:171], v[208:211], v[88:91]
	v_mfma_f32_16x16x32_bf16 v[76:79], v[156:159], v[216:219], v[76:79]
	v_mfma_f32_16x16x32_bf16 v[72:75], v[168:171], v[216:219], v[72:75]
	s_setprio 0
	s_setprio 1
	v_mfma_f32_16x16x32_bf16 v[116:119], v[172:175], v[188:191], v[116:119]
	v_mfma_f32_16x16x32_bf16 v[112:115], v[180:183], v[188:191], v[112:115]
	v_mfma_f32_16x16x32_bf16 v[100:103], v[172:175], v[196:199], v[100:103]
	v_mfma_f32_16x16x32_bf16 v[96:99], v[180:183], v[196:199], v[96:99]
	v_mfma_f32_16x16x32_bf16 v[84:87], v[172:175], v[204:207], v[84:87]
	v_mfma_f32_16x16x32_bf16 v[80:83], v[180:183], v[204:207], v[80:83]
	v_mfma_f32_16x16x32_bf16 v[68:71], v[172:175], v[212:215], v[68:71]
	v_mfma_f32_16x16x32_bf16 v[64:67], v[180:183], v[212:215], v[64:67]
	v_mfma_f32_16x16x32_bf16 v[116:119], v[176:179], v[192:195], v[116:119]
	v_mfma_f32_16x16x32_bf16 v[112:115], v[184:187], v[192:195], v[112:115]
	v_mfma_f32_16x16x32_bf16 v[100:103], v[176:179], v[200:203], v[100:103]
	v_mfma_f32_16x16x32_bf16 v[96:99], v[184:187], v[200:203], v[96:99]
	v_mfma_f32_16x16x32_bf16 v[84:87], v[176:179], v[208:211], v[84:87]
	v_mfma_f32_16x16x32_bf16 v[80:83], v[184:187], v[208:211], v[80:83]
	v_mfma_f32_16x16x32_bf16 v[68:71], v[176:179], v[216:219], v[68:71]
	v_mfma_f32_16x16x32_bf16 v[64:67], v[184:187], v[216:219], v[64:67]
	s_setprio 0
	s_barrier
	s_add_i32 s8, s8, s50
	s_mov_b32 m0, s8
	ds_read_b128 v[188:191], v166 offset:49152
	ds_read_b128 v[192:195], v166 offset:50176
	ds_read_b128 v[196:199], v166 offset:51200
	global_load_lds_dwordx4 v138, s[40:41]
	s_add_i32 m0, s8, 0x2000
	ds_read_b128 v[200:203], v166 offset:52224
	global_load_lds_dwordx4 v142, s[40:41]
	s_add_u32 s40, s40, 0xb0000
	s_addc_u32 s41, s41, 0
	s_add_i32 s8, s79, s50
	s_mov_b32 m0, s8
	ds_read_b128 v[204:207], v166 offset:53248
	global_load_lds_dwordx4 v138, s[40:41]
	s_add_i32 m0, s8, 0x2000
	ds_read_b128 v[208:211], v166 offset:54272
	global_load_lds_dwordx4 v142, s[40:41]
	s_mov_b32 m0, s60
	ds_read_b128 v[212:215], v166 offset:55296
	global_load_lds_dwordx4 v136, s[38:39]
	s_mov_b32 m0, s61
	ds_read_b128 v[216:219], v166 offset:56320
	global_load_lds_dwordx4 v140, s[38:39]
	s_waitcnt vmcnt(8)
	s_waitcnt lgkmcnt(0)
	s_barrier
	s_setprio 1
	s_waitcnt lgkmcnt(0)
	v_mfma_f32_16x16x32_bf16 v[60:63], v[132:135], v[188:191], v[60:63]
	v_mfma_f32_16x16x32_bf16 v[56:59], v[160:163], v[188:191], v[56:59]
	v_mfma_f32_16x16x32_bf16 v[44:47], v[132:135], v[196:199], v[44:47]
	v_mfma_f32_16x16x32_bf16 v[40:43], v[160:163], v[196:199], v[40:43]
	v_mfma_f32_16x16x32_bf16 v[28:31], v[132:135], v[204:207], v[28:31]
	v_mfma_f32_16x16x32_bf16 v[24:27], v[160:163], v[204:207], v[24:27]
	v_mfma_f32_16x16x32_bf16 v[12:15], v[132:135], v[212:215], v[12:15]
	v_mfma_f32_16x16x32_bf16 v[8:11], v[160:163], v[212:215], v[8:11]
	v_mfma_f32_16x16x32_bf16 v[60:63], v[156:159], v[192:195], v[60:63]
	v_mfma_f32_16x16x32_bf16 v[56:59], v[168:171], v[192:195], v[56:59]
	v_mfma_f32_16x16x32_bf16 v[44:47], v[156:159], v[200:203], v[44:47]
	v_mfma_f32_16x16x32_bf16 v[40:43], v[168:171], v[200:203], v[40:43]
	v_mfma_f32_16x16x32_bf16 v[28:31], v[156:159], v[208:211], v[28:31]
	v_mfma_f32_16x16x32_bf16 v[24:27], v[168:171], v[208:211], v[24:27]
	v_mfma_f32_16x16x32_bf16 v[12:15], v[156:159], v[216:219], v[12:15]
	v_mfma_f32_16x16x32_bf16 v[8:11], v[168:171], v[216:219], v[8:11]
	s_setprio 0
	s_setprio 1
	v_mfma_f32_16x16x32_bf16 v[52:55], v[172:175], v[188:191], v[52:55]
	v_mfma_f32_16x16x32_bf16 v[48:51], v[180:183], v[188:191], v[48:51]
	v_mfma_f32_16x16x32_bf16 v[36:39], v[172:175], v[196:199], v[36:39]
	v_mfma_f32_16x16x32_bf16 v[32:35], v[180:183], v[196:199], v[32:35]
	v_mfma_f32_16x16x32_bf16 v[20:23], v[172:175], v[204:207], v[20:23]
	v_mfma_f32_16x16x32_bf16 v[16:19], v[180:183], v[204:207], v[16:19]
	v_mfma_f32_16x16x32_bf16 v[4:7], v[172:175], v[212:215], v[4:7]
	v_mfma_f32_16x16x32_bf16 v[0:3], v[180:183], v[212:215], v[0:3]
	v_mfma_f32_16x16x32_bf16 v[52:55], v[176:179], v[192:195], v[52:55]
	v_mfma_f32_16x16x32_bf16 v[48:51], v[184:187], v[192:195], v[48:51]
	v_mfma_f32_16x16x32_bf16 v[36:39], v[176:179], v[200:203], v[36:39]
	v_mfma_f32_16x16x32_bf16 v[32:35], v[184:187], v[200:203], v[32:35]
	v_mfma_f32_16x16x32_bf16 v[20:23], v[176:179], v[208:211], v[20:23]
	v_mfma_f32_16x16x32_bf16 v[16:19], v[184:187], v[208:211], v[16:19]
	v_mfma_f32_16x16x32_bf16 v[4:7], v[176:179], v[216:219], v[4:7]
	v_mfma_f32_16x16x32_bf16 v[0:3], v[184:187], v[216:219], v[0:3]
	s_setprio 0
	s_barrier
	s_add_i32 s8, s78, 2
	s_add_u32 s36, s36, 0x100
	s_addc_u32 s37, s37, 0
	s_cmp_gt_u32 s78, 41
	s_mov_b32 s78, s8
	s_cbranch_scc1 .LBB0_903
.LBB0_897:
	s_add_u32 s46, s26, s36
	s_addc_u32 s47, s27, s37
	s_add_u32 s80, s24, s36
	s_addc_u32 s79, s25, s37
	s_add_u32 s38, s46, 0x180
	s_addc_u32 s39, s47, 0
	s_add_u32 s40, s80, 0x180
	s_addc_u32 s41, s79, 0
	s_add_u32 s46, s46, 0x100
	s_addc_u32 s47, s47, 0
	s_add_u32 s44, s80, 0x100
	s_addc_u32 s45, s79, 0
	s_cmpk_eq_i32 s36, 0x1500
	s_cselect_b32 s38, s28, s38
	s_cselect_b32 s39, s29, s39
	s_cselect_b32 s40, s30, s40
	s_cselect_b32 s41, s31, s41
	s_cselect_b32 s46, s4, s46
	s_cselect_b32 s47, s5, s47
	s_cselect_b32 s44, s20, s44
	s_cselect_b32 s45, s21, s45
	s_branch .LBB0_896

.LBB0_1017:
	s_add_u32 s65, s54, s6
	s_addc_u32 s66, s55, s7
	s_add_u32 s67, s56, s8
	s_addc_u32 s68, s57, s9
	s_ashr_i32 s19, s18, 31
	s_lshl_b64 s[6:7], s[18:19], 19
	s_add_u32 s20, s34, s6
	s_addc_u32 s21, s35, s7
	s_and_b64 s[8:9], s[0:1], exec
	s_cselect_b32 s19, s21, s29
	s_cselect_b32 s69, s20, s28
	s_ashr_i32 s17, s16, 31
	s_lshl_b64 s[8:9], s[16:17], 19
	s_add_u32 s22, s48, s8
	s_addc_u32 s23, s49, s9
	s_and_b64 s[30:31], s[0:1], exec
	s_cselect_b32 s17, s23, s27
	s_cselect_b32 s70, s22, s26
	s_add_u32 s30, s69, 0x80
	s_addc_u32 s31, s19, 0
	s_add_u32 s36, s70, 0x80
	s_addc_u32 s37, s17, 0
	v_lshl_add_u64 v[128:129], s[28:29], 0, v[196:197]
	v_lshl_add_u64 v[130:131], s[28:29], 0, v[198:199]
	s_mov_b32 s71, 0
	s_mov_b64 s[38:39], 0
	s_add_u32 s46, s28, s38
	s_addc_u32 s47, s29, s39
	s_add_u32 s73, s26, s38
	s_addc_u32 s72, s27, s39
	s_add_u32 s40, s46, 0x180
	s_addc_u32 s41, s47, 0
	s_add_u32 s42, s73, 0x180
	s_addc_u32 s43, s72, 0
	s_add_u32 s46, s46, 0x100
	s_addc_u32 s47, s47, 0
	s_add_u32 s44, s73, 0x100
	s_addc_u32 s45, s72, 0
	s_cmpk_eq_i32 s38, 0x700
	s_cselect_b32 s40, s30, s40
	s_cselect_b32 s41, s31, s41
	s_cselect_b32 s42, s36, s42
	s_cselect_b32 s43, s37, s43
	s_cselect_b32 s46, s69, s46
	s_cselect_b32 s47, s19, s47
	s_cselect_b32 s44, s70, s44
	s_cselect_b32 s45, s17, s45
	v_add_u32_e32 v144, s61, v220
	v_add_u32_e32 v160, s62, v220
	ds_read_b128 v[132:135], v144
	ds_read_b128 v[136:139], v144 offset:1024
	ds_read_b128 v[140:143], v144 offset:2048
	ds_read_b128 v[144:147], v144 offset:3072
	ds_read_b128 v[148:151], v160
	ds_read_b128 v[152:155], v160 offset:1024
	ds_read_b128 v[156:159], v160 offset:2048
	ds_read_b128 v[160:163], v160 offset:3072
	v_lshl_add_u64 v[216:217], v[128:129], 0, s[38:39]
	s_add_i32 m0, s25, 0xc000
	ds_read_b128 v[164:167], v221
	ds_read_b128 v[168:171], v221 offset:1024
	ds_read_b128 v[172:175], v221 offset:2048
	ds_read_b128 v[176:179], v221 offset:3072
	ds_read_b128 v[180:183], v221 offset:4096
	ds_read_b128 v[204:207], v221 offset:5120
	ds_read_b128 v[208:211], v221 offset:6144
	global_load_lds_dwordx4 v[216:217], off
	v_lshl_add_u64 v[216:217], v[130:131], 0, s[38:39]
	s_add_i32 m0, s25, 0xe000
	ds_read_b128 v[212:215], v221 offset:7168
	global_load_lds_dwordx4 v[216:217], off
	s_waitcnt vmcnt(8)
	s_waitcnt lgkmcnt(0)
	s_barrier
	s_setprio 1
	s_waitcnt lgkmcnt(0)
	v_mfma_f32_16x16x32_bf16 v[124:127], v[132:135], v[164:167], 0
	v_mfma_f32_16x16x32_bf16 v[120:123], v[140:143], v[164:167], 0
	v_mfma_f32_16x16x32_bf16 v[108:111], v[132:135], v[172:175], 0
	v_mfma_f32_16x16x32_bf16 v[104:107], v[140:143], v[172:175], 0
	v_mfma_f32_16x16x32_bf16 v[92:95], v[132:135], v[180:183], 0
	v_mfma_f32_16x16x32_bf16 v[88:91], v[140:143], v[180:183], 0
	v_mfma_f32_16x16x32_bf16 v[76:79], v[132:135], v[208:211], 0
	v_mfma_f32_16x16x32_bf16 v[72:75], v[140:143], v[208:211], 0
	v_mfma_f32_16x16x32_bf16 v[124:127], v[136:139], v[168:171], v[124:127]
	v_mfma_f32_16x16x32_bf16 v[120:123], v[144:147], v[168:171], v[120:123]
	v_mfma_f32_16x16x32_bf16 v[108:111], v[136:139], v[176:179], v[108:111]
	v_mfma_f32_16x16x32_bf16 v[104:107], v[144:147], v[176:179], v[104:107]
	v_mfma_f32_16x16x32_bf16 v[92:95], v[136:139], v[204:207], v[92:95]
	v_mfma_f32_16x16x32_bf16 v[88:91], v[144:147], v[204:207], v[88:91]
	v_mfma_f32_16x16x32_bf16 v[76:79], v[136:139], v[212:215], v[76:79]
	v_mfma_f32_16x16x32_bf16 v[72:75], v[144:147], v[212:215], v[72:75]
	s_setprio 0
	s_setprio 1
	v_mfma_f32_16x16x32_bf16 v[116:119], v[148:151], v[164:167], 0
	v_mfma_f32_16x16x32_bf16 v[112:115], v[156:159], v[164:167], 0
	v_mfma_f32_16x16x32_bf16 v[100:103], v[148:151], v[172:175], 0
	v_mfma_f32_16x16x32_bf16 v[96:99], v[156:159], v[172:175], 0
	v_mfma_f32_16x16x32_bf16 v[84:87], v[148:151], v[180:183], 0
	v_mfma_f32_16x16x32_bf16 v[80:83], v[156:159], v[180:183], 0
	v_mfma_f32_16x16x32_bf16 v[68:71], v[148:151], v[208:211], 0
	v_mfma_f32_16x16x32_bf16 v[64:67], v[156:159], v[208:211], 0
	v_mfma_f32_16x16x32_bf16 v[116:119], v[152:155], v[168:171], v[116:119]
	v_mfma_f32_16x16x32_bf16 v[112:115], v[160:163], v[168:171], v[112:115]
	v_mfma_f32_16x16x32_bf16 v[100:103], v[152:155], v[176:179], v[100:103]
	v_mfma_f32_16x16x32_bf16 v[96:99], v[160:163], v[176:179], v[96:99]
	v_mfma_f32_16x16x32_bf16 v[84:87], v[152:155], v[204:207], v[84:87]
	v_mfma_f32_16x16x32_bf16 v[80:83], v[160:163], v[204:207], v[80:83]
	v_mfma_f32_16x16x32_bf16 v[68:71], v[152:155], v[212:215], v[68:71]
	v_mfma_f32_16x16x32_bf16 v[64:67], v[160:163], v[212:215], v[64:67]
	s_setprio 0
	s_barrier
	s_add_i32 s10, s61, s50
	s_mov_b32 m0, s10
	ds_read_b128 v[164:167], v221 offset:16384
	ds_read_b128 v[168:171], v221 offset:17408
	ds_read_b128 v[172:175], v221 offset:18432
	global_load_lds_dwordx4 v186, s[44:45]
	s_add_i32 m0, s10, 0x2000
	ds_read_b128 v[176:179], v221 offset:19456
	global_load_lds_dwordx4 v190, s[44:45]
	s_add_u32 s44, s44, 0x40000
	s_addc_u32 s45, s45, 0
	s_add_i32 s10, s62, s50
	s_mov_b32 m0, s10
	ds_read_b128 v[180:183], v221 offset:20480
	global_load_lds_dwordx4 v186, s[44:45]
	s_add_i32 m0, s10, 0x2000
	ds_read_b128 v[204:207], v221 offset:21504
	global_load_lds_dwordx4 v190, s[44:45]
	s_mov_b32 m0, s25
	ds_read_b128 v[208:211], v221 offset:22528
	global_load_lds_dwordx4 v184, s[46:47]
	s_mov_b32 m0, s51
	ds_read_b128 v[212:215], v221 offset:23552
	global_load_lds_dwordx4 v188, s[46:47]
	s_waitcnt vmcnt(8)
	s_waitcnt lgkmcnt(0)
	s_barrier
	s_setprio 1
	s_waitcnt lgkmcnt(0)
	v_mfma_f32_16x16x32_bf16 v[60:63], v[132:135], v[164:167], 0
	v_mfma_f32_16x16x32_bf16 v[56:59], v[140:143], v[164:167], 0
	v_mfma_f32_16x16x32_bf16 v[44:47], v[132:135], v[172:175], 0
	v_mfma_f32_16x16x32_bf16 v[40:43], v[140:143], v[172:175], 0
	v_mfma_f32_16x16x32_bf16 v[28:31], v[132:135], v[180:183], 0
	v_mfma_f32_16x16x32_bf16 v[24:27], v[140:143], v[180:183], 0
	v_mfma_f32_16x16x32_bf16 v[12:15], v[132:135], v[208:211], 0
	v_mfma_f32_16x16x32_bf16 v[8:11], v[140:143], v[208:211], 0
	v_mfma_f32_16x16x32_bf16 v[60:63], v[136:139], v[168:171], v[60:63]
	v_mfma_f32_16x16x32_bf16 v[56:59], v[144:147], v[168:171], v[56:59]
	v_mfma_f32_16x16x32_bf16 v[44:47], v[136:139], v[176:179], v[44:47]
	v_mfma_f32_16x16x32_bf16 v[40:43], v[144:147], v[176:179], v[40:43]
	v_mfma_f32_16x16x32_bf16 v[28:31], v[136:139], v[204:207], v[28:31]
	v_mfma_f32_16x16x32_bf16 v[24:27], v[144:147], v[204:207], v[24:27]
	v_mfma_f32_16x16x32_bf16 v[12:15], v[136:139], v[212:215], v[12:15]
	v_mfma_f32_16x16x32_bf16 v[8:11], v[144:147], v[212:215], v[8:11]
	s_setprio 0
	s_setprio 1
	v_mfma_f32_16x16x32_bf16 v[52:55], v[148:151], v[164:167], 0
	v_mfma_f32_16x16x32_bf16 v[48:51], v[156:159], v[164:167], 0
	v_mfma_f32_16x16x32_bf16 v[36:39], v[148:151], v[172:175], 0
	v_mfma_f32_16x16x32_bf16 v[32:35], v[156:159], v[172:175], 0
	v_mfma_f32_16x16x32_bf16 v[20:23], v[148:151], v[180:183], 0
	v_mfma_f32_16x16x32_bf16 v[16:19], v[156:159], v[180:183], 0
	v_mfma_f32_16x16x32_bf16 v[4:7], v[148:151], v[208:211], 0
	v_mfma_f32_16x16x32_bf16 v[0:3], v[156:159], v[208:211], 0
	v_mfma_f32_16x16x32_bf16 v[52:55], v[152:155], v[168:171], v[52:55]
	v_mfma_f32_16x16x32_bf16 v[48:51], v[160:163], v[168:171], v[48:51]
	v_mfma_f32_16x16x32_bf16 v[36:39], v[152:155], v[176:179], v[36:39]
	v_mfma_f32_16x16x32_bf16 v[32:35], v[160:163], v[176:179], v[32:35]
	v_mfma_f32_16x16x32_bf16 v[20:23], v[152:155], v[204:207], v[20:23]
	v_mfma_f32_16x16x32_bf16 v[16:19], v[160:163], v[204:207], v[16:19]
	v_mfma_f32_16x16x32_bf16 v[4:7], v[152:155], v[212:215], v[4:7]
	v_mfma_f32_16x16x32_bf16 v[0:3], v[160:163], v[212:215], v[0:3]
	s_setprio 0
	s_barrier
	s_add_i32 s10, 0, 0x18000
	s_add_i32 s72, 0, 0x1c000
	v_add_u32_e32 v144, s10, v220
	v_add_u32_e32 v160, s72, v220
	ds_read_b128 v[132:135], v144
	ds_read_b128 v[136:139], v144 offset:1024
	ds_read_b128 v[140:143], v144 offset:2048
	ds_read_b128 v[144:147], v144 offset:3072
	ds_read_b128 v[148:151], v160
	ds_read_b128 v[152:155], v160 offset:1024
	ds_read_b128 v[156:159], v160 offset:2048
	ds_read_b128 v[160:163], v160 offset:3072
	s_add_u32 s44, s46, 0x40000
	s_addc_u32 s45, s47, 0
	s_mov_b32 m0, s52
	ds_read_b128 v[164:167], v221 offset:32768
	ds_read_b128 v[168:171], v221 offset:33792
	ds_read_b128 v[172:175], v221 offset:34816
	ds_read_b128 v[176:179], v221 offset:35840
	ds_read_b128 v[180:183], v221 offset:36864
	ds_read_b128 v[204:207], v221 offset:37888
	ds_read_b128 v[208:211], v221 offset:38912
	global_load_lds_dwordx4 v184, s[44:45]
	s_mov_b32 m0, s53
	ds_read_b128 v[212:215], v221 offset:39936
	global_load_lds_dwordx4 v188, s[44:45]
	s_waitcnt vmcnt(8)
	s_waitcnt lgkmcnt(0)
	s_barrier
	s_setprio 1
	s_waitcnt lgkmcnt(0)
	v_mfma_f32_16x16x32_bf16 v[124:127], v[132:135], v[164:167], v[124:127]
	v_mfma_f32_16x16x32_bf16 v[120:123], v[140:143], v[164:167], v[120:123]
	v_mfma_f32_16x16x32_bf16 v[108:111], v[132:135], v[172:175], v[108:111]
	v_mfma_f32_16x16x32_bf16 v[104:107], v[140:143], v[172:175], v[104:107]
	v_mfma_f32_16x16x32_bf16 v[92:95], v[132:135], v[180:183], v[92:95]
	v_mfma_f32_16x16x32_bf16 v[88:91], v[140:143], v[180:183], v[88:91]
	v_mfma_f32_16x16x32_bf16 v[76:79], v[132:135], v[208:211], v[76:79]
	v_mfma_f32_16x16x32_bf16 v[72:75], v[140:143], v[208:211], v[72:75]
	v_mfma_f32_16x16x32_bf16 v[124:127], v[136:139], v[168:171], v[124:127]
	v_mfma_f32_16x16x32_bf16 v[120:123], v[144:147], v[168:171], v[120:123]
	v_mfma_f32_16x16x32_bf16 v[108:111], v[136:139], v[176:179], v[108:111]
	v_mfma_f32_16x16x32_bf16 v[104:107], v[144:147], v[176:179], v[104:107]
	v_mfma_f32_16x16x32_bf16 v[92:95], v[136:139], v[204:207], v[92:95]
	v_mfma_f32_16x16x32_bf16 v[88:91], v[144:147], v[204:207], v[88:91]
	v_mfma_f32_16x16x32_bf16 v[76:79], v[136:139], v[212:215], v[76:79]
	v_mfma_f32_16x16x32_bf16 v[72:75], v[144:147], v[212:215], v[72:75]
	s_setprio 0
	s_setprio 1
	v_mfma_f32_16x16x32_bf16 v[116:119], v[148:151], v[164:167], v[116:119]
	v_mfma_f32_16x16x32_bf16 v[112:115], v[156:159], v[164:167], v[112:115]
	v_mfma_f32_16x16x32_bf16 v[100:103], v[148:151], v[172:175], v[100:103]
	v_mfma_f32_16x16x32_bf16 v[96:99], v[156:159], v[172:175], v[96:99]
	v_mfma_f32_16x16x32_bf16 v[84:87], v[148:151], v[180:183], v[84:87]
	v_mfma_f32_16x16x32_bf16 v[80:83], v[156:159], v[180:183], v[80:83]
	v_mfma_f32_16x16x32_bf16 v[68:71], v[148:151], v[208:211], v[68:71]
	v_mfma_f32_16x16x32_bf16 v[64:67], v[156:159], v[208:211], v[64:67]
	v_mfma_f32_16x16x32_bf16 v[116:119], v[152:155], v[168:171], v[116:119]
	v_mfma_f32_16x16x32_bf16 v[112:115], v[160:163], v[168:171], v[112:115]
	v_mfma_f32_16x16x32_bf16 v[100:103], v[152:155], v[176:179], v[100:103]
	v_mfma_f32_16x16x32_bf16 v[96:99], v[160:163], v[176:179], v[96:99]
	v_mfma_f32_16x16x32_bf16 v[84:87], v[152:155], v[204:207], v[84:87]
	v_mfma_f32_16x16x32_bf16 v[80:83], v[160:163], v[204:207], v[80:83]
	v_mfma_f32_16x16x32_bf16 v[68:71], v[152:155], v[212:215], v[68:71]
	v_mfma_f32_16x16x32_bf16 v[64:67], v[160:163], v[212:215], v[64:67]
	s_setprio 0
	s_barrier
	s_add_i32 s10, s10, s50
	s_mov_b32 m0, s10
	ds_read_b128 v[164:167], v221 offset:49152
	ds_read_b128 v[168:171], v221 offset:50176
	ds_read_b128 v[172:175], v221 offset:51200
	global_load_lds_dwordx4 v186, s[42:43]
	s_add_i32 m0, s10, 0x2000
	ds_read_b128 v[176:179], v221 offset:52224
	global_load_lds_dwordx4 v190, s[42:43]
	s_add_u32 s42, s42, 0x40000
	s_addc_u32 s43, s43, 0
	s_add_i32 s10, s72, s50
	s_mov_b32 m0, s10
	ds_read_b128 v[180:183], v221 offset:53248
	global_load_lds_dwordx4 v186, s[42:43]
	s_add_i32 m0, s10, 0x2000
	ds_read_b128 v[204:207], v221 offset:54272
	global_load_lds_dwordx4 v190, s[42:43]
	s_mov_b32 m0, s58
	ds_read_b128 v[208:211], v221 offset:55296
	global_load_lds_dwordx4 v184, s[40:41]
	s_mov_b32 m0, s59
	ds_read_b128 v[212:215], v221 offset:56320
	global_load_lds_dwordx4 v188, s[40:41]
	s_waitcnt vmcnt(8)
	s_waitcnt lgkmcnt(0)
	s_barrier
	s_setprio 1
	s_waitcnt lgkmcnt(0)
	v_mfma_f32_16x16x32_bf16 v[60:63], v[132:135], v[164:167], v[60:63]
	v_mfma_f32_16x16x32_bf16 v[56:59], v[140:143], v[164:167], v[56:59]
	v_mfma_f32_16x16x32_bf16 v[44:47], v[132:135], v[172:175], v[44:47]
	v_mfma_f32_16x16x32_bf16 v[40:43], v[140:143], v[172:175], v[40:43]
	v_mfma_f32_16x16x32_bf16 v[28:31], v[132:135], v[180:183], v[28:31]
	v_mfma_f32_16x16x32_bf16 v[24:27], v[140:143], v[180:183], v[24:27]
	v_mfma_f32_16x16x32_bf16 v[12:15], v[132:135], v[208:211], v[12:15]
	v_mfma_f32_16x16x32_bf16 v[8:11], v[140:143], v[208:211], v[8:11]
	v_mfma_f32_16x16x32_bf16 v[60:63], v[136:139], v[168:171], v[60:63]
	v_mfma_f32_16x16x32_bf16 v[56:59], v[144:147], v[168:171], v[56:59]
	v_mfma_f32_16x16x32_bf16 v[44:47], v[136:139], v[176:179], v[44:47]
	v_mfma_f32_16x16x32_bf16 v[40:43], v[144:147], v[176:179], v[40:43]
	v_mfma_f32_16x16x32_bf16 v[28:31], v[136:139], v[204:207], v[28:31]
	v_mfma_f32_16x16x32_bf16 v[24:27], v[144:147], v[204:207], v[24:27]
	v_mfma_f32_16x16x32_bf16 v[12:15], v[136:139], v[212:215], v[12:15]
	v_mfma_f32_16x16x32_bf16 v[8:11], v[144:147], v[212:215], v[8:11]
	s_setprio 0
	s_setprio 1
	v_mfma_f32_16x16x32_bf16 v[52:55], v[148:151], v[164:167], v[52:55]
	v_mfma_f32_16x16x32_bf16 v[48:51], v[156:159], v[164:167], v[48:51]
	v_mfma_f32_16x16x32_bf16 v[36:39], v[148:151], v[172:175], v[36:39]
	v_mfma_f32_16x16x32_bf16 v[32:35], v[156:159], v[172:175], v[32:35]
	v_mfma_f32_16x16x32_bf16 v[20:23], v[148:151], v[180:183], v[20:23]
	v_mfma_f32_16x16x32_bf16 v[16:19], v[156:159], v[180:183], v[16:19]
	v_mfma_f32_16x16x32_bf16 v[4:7], v[148:151], v[208:211], v[4:7]
	v_mfma_f32_16x16x32_bf16 v[0:3], v[156:159], v[208:211], v[0:3]
	v_mfma_f32_16x16x32_bf16 v[52:55], v[152:155], v[168:171], v[52:55]
	v_mfma_f32_16x16x32_bf16 v[48:51], v[160:163], v[168:171], v[48:51]
	v_mfma_f32_16x16x32_bf16 v[36:39], v[152:155], v[176:179], v[36:39]
	v_mfma_f32_16x16x32_bf16 v[32:35], v[160:163], v[176:179], v[32:35]
	v_mfma_f32_16x16x32_bf16 v[20:23], v[152:155], v[204:207], v[20:23]
	v_mfma_f32_16x16x32_bf16 v[16:19], v[160:163], v[204:207], v[16:19]
	v_mfma_f32_16x16x32_bf16 v[4:7], v[152:155], v[212:215], v[4:7]
	v_mfma_f32_16x16x32_bf16 v[0:3], v[160:163], v[212:215], v[0:3]
	s_setprio 0
	s_barrier
	s_add_i32 s10, s71, 2
	s_add_u32 s38, s38, 0x100
	s_addc_u32 s39, s39, 0
	s_cmp_gt_u32 s71, 13
	s_mov_b32 s71, s10
	s_cbranch_scc1 .LBB0_1025
	s_branch .LBB0_1019
.LBB0_1018:
	v_add_u32_e32 v144, s61, v220
	v_add_u32_e32 v160, s62, v220
	ds_read_b128 v[132:135], v144
	ds_read_b128 v[136:139], v144 offset:1024
	ds_read_b128 v[140:143], v144 offset:2048
	ds_read_b128 v[144:147], v144 offset:3072
	ds_read_b128 v[148:151], v160
	ds_read_b128 v[152:155], v160 offset:1024
	ds_read_b128 v[156:159], v160 offset:2048
	ds_read_b128 v[160:163], v160 offset:3072
	v_lshl_add_u64 v[216:217], v[128:129], 0, s[38:39]
	s_add_i32 m0, s25, 0xc000
	ds_read_b128 v[164:167], v221
	ds_read_b128 v[168:171], v221 offset:1024
	ds_read_b128 v[172:175], v221 offset:2048
	ds_read_b128 v[176:179], v221 offset:3072
	ds_read_b128 v[180:183], v221 offset:4096
	ds_read_b128 v[204:207], v221 offset:5120
	ds_read_b128 v[208:211], v221 offset:6144
	global_load_lds_dwordx4 v[216:217], off
	v_lshl_add_u64 v[216:217], v[130:131], 0, s[38:39]
	s_add_i32 m0, s25, 0xe000
	ds_read_b128 v[212:215], v221 offset:7168
	global_load_lds_dwordx4 v[216:217], off
	s_waitcnt vmcnt(8)
	s_waitcnt lgkmcnt(0)
	s_barrier
	s_setprio 1
	s_waitcnt lgkmcnt(0)
	v_mfma_f32_16x16x32_bf16 v[124:127], v[132:135], v[164:167], v[124:127]
	v_mfma_f32_16x16x32_bf16 v[120:123], v[140:143], v[164:167], v[120:123]
	v_mfma_f32_16x16x32_bf16 v[108:111], v[132:135], v[172:175], v[108:111]
	v_mfma_f32_16x16x32_bf16 v[104:107], v[140:143], v[172:175], v[104:107]
	v_mfma_f32_16x16x32_bf16 v[92:95], v[132:135], v[180:183], v[92:95]
	v_mfma_f32_16x16x32_bf16 v[88:91], v[140:143], v[180:183], v[88:91]
	v_mfma_f32_16x16x32_bf16 v[76:79], v[132:135], v[208:211], v[76:79]
	v_mfma_f32_16x16x32_bf16 v[72:75], v[140:143], v[208:211], v[72:75]
	v_mfma_f32_16x16x32_bf16 v[124:127], v[136:139], v[168:171], v[124:127]
	v_mfma_f32_16x16x32_bf16 v[120:123], v[144:147], v[168:171], v[120:123]
	v_mfma_f32_16x16x32_bf16 v[108:111], v[136:139], v[176:179], v[108:111]
	v_mfma_f32_16x16x32_bf16 v[104:107], v[144:147], v[176:179], v[104:107]
	v_mfma_f32_16x16x32_bf16 v[92:95], v[136:139], v[204:207], v[92:95]
	v_mfma_f32_16x16x32_bf16 v[88:91], v[144:147], v[204:207], v[88:91]
	v_mfma_f32_16x16x32_bf16 v[76:79], v[136:139], v[212:215], v[76:79]
	v_mfma_f32_16x16x32_bf16 v[72:75], v[144:147], v[212:215], v[72:75]
	s_setprio 0
	s_setprio 1
	v_mfma_f32_16x16x32_bf16 v[116:119], v[148:151], v[164:167], v[116:119]
	v_mfma_f32_16x16x32_bf16 v[112:115], v[156:159], v[164:167], v[112:115]
	v_mfma_f32_16x16x32_bf16 v[100:103], v[148:151], v[172:175], v[100:103]
	v_mfma_f32_16x16x32_bf16 v[96:99], v[156:159], v[172:175], v[96:99]
	v_mfma_f32_16x16x32_bf16 v[84:87], v[148:151], v[180:183], v[84:87]
	v_mfma_f32_16x16x32_bf16 v[80:83], v[156:159], v[180:183], v[80:83]
	v_mfma_f32_16x16x32_bf16 v[68:71], v[148:151], v[208:211], v[68:71]
	v_mfma_f32_16x16x32_bf16 v[64:67], v[156:159], v[208:211], v[64:67]
	v_mfma_f32_16x16x32_bf16 v[116:119], v[152:155], v[168:171], v[116:119]
	v_mfma_f32_16x16x32_bf16 v[112:115], v[160:163], v[168:171], v[112:115]
	v_mfma_f32_16x16x32_bf16 v[100:103], v[152:155], v[176:179], v[100:103]
	v_mfma_f32_16x16x32_bf16 v[96:99], v[160:163], v[176:179], v[96:99]
	v_mfma_f32_16x16x32_bf16 v[84:87], v[152:155], v[204:207], v[84:87]
	v_mfma_f32_16x16x32_bf16 v[80:83], v[160:163], v[204:207], v[80:83]
	v_mfma_f32_16x16x32_bf16 v[68:71], v[152:155], v[212:215], v[68:71]
	v_mfma_f32_16x16x32_bf16 v[64:67], v[160:163], v[212:215], v[64:67]
	s_setprio 0
	s_barrier
	s_add_i32 s10, s61, s50
	s_mov_b32 m0, s10
	ds_read_b128 v[164:167], v221 offset:16384
	ds_read_b128 v[168:171], v221 offset:17408
	ds_read_b128 v[172:175], v221 offset:18432
	global_load_lds_dwordx4 v186, s[44:45]
	s_add_i32 m0, s10, 0x2000
	ds_read_b128 v[176:179], v221 offset:19456
	global_load_lds_dwordx4 v190, s[44:45]
	s_add_u32 s44, s44, 0x40000
	s_addc_u32 s45, s45, 0
	s_add_i32 s10, s62, s50
	s_mov_b32 m0, s10
	ds_read_b128 v[180:183], v221 offset:20480
	global_load_lds_dwordx4 v186, s[44:45]
	s_add_i32 m0, s10, 0x2000
	ds_read_b128 v[204:207], v221 offset:21504
	global_load_lds_dwordx4 v190, s[44:45]
	s_mov_b32 m0, s25
	ds_read_b128 v[208:211], v221 offset:22528
	global_load_lds_dwordx4 v184, s[46:47]
	s_mov_b32 m0, s51
	ds_read_b128 v[212:215], v221 offset:23552
	global_load_lds_dwordx4 v188, s[46:47]
	s_waitcnt vmcnt(8)
	s_waitcnt lgkmcnt(0)
	s_barrier
	s_setprio 1
	s_waitcnt lgkmcnt(0)
	v_mfma_f32_16x16x32_bf16 v[60:63], v[132:135], v[164:167], v[60:63]
	v_mfma_f32_16x16x32_bf16 v[56:59], v[140:143], v[164:167], v[56:59]
	v_mfma_f32_16x16x32_bf16 v[44:47], v[132:135], v[172:175], v[44:47]
	v_mfma_f32_16x16x32_bf16 v[40:43], v[140:143], v[172:175], v[40:43]
	v_mfma_f32_16x16x32_bf16 v[28:31], v[132:135], v[180:183], v[28:31]
	v_mfma_f32_16x16x32_bf16 v[24:27], v[140:143], v[180:183], v[24:27]
	v_mfma_f32_16x16x32_bf16 v[12:15], v[132:135], v[208:211], v[12:15]
	v_mfma_f32_16x16x32_bf16 v[8:11], v[140:143], v[208:211], v[8:11]
	v_mfma_f32_16x16x32_bf16 v[60:63], v[136:139], v[168:171], v[60:63]
	v_mfma_f32_16x16x32_bf16 v[56:59], v[144:147], v[168:171], v[56:59]
	v_mfma_f32_16x16x32_bf16 v[44:47], v[136:139], v[176:179], v[44:47]
	v_mfma_f32_16x16x32_bf16 v[40:43], v[144:147], v[176:179], v[40:43]
	v_mfma_f32_16x16x32_bf16 v[28:31], v[136:139], v[204:207], v[28:31]
	v_mfma_f32_16x16x32_bf16 v[24:27], v[144:147], v[204:207], v[24:27]
	v_mfma_f32_16x16x32_bf16 v[12:15], v[136:139], v[212:215], v[12:15]
	v_mfma_f32_16x16x32_bf16 v[8:11], v[144:147], v[212:215], v[8:11]
	s_setprio 0
	s_setprio 1
	v_mfma_f32_16x16x32_bf16 v[52:55], v[148:151], v[164:167], v[52:55]
	v_mfma_f32_16x16x32_bf16 v[48:51], v[156:159], v[164:167], v[48:51]
	v_mfma_f32_16x16x32_bf16 v[36:39], v[148:151], v[172:175], v[36:39]
	v_mfma_f32_16x16x32_bf16 v[32:35], v[156:159], v[172:175], v[32:35]
	v_mfma_f32_16x16x32_bf16 v[20:23], v[148:151], v[180:183], v[20:23]
	v_mfma_f32_16x16x32_bf16 v[16:19], v[156:159], v[180:183], v[16:19]
	v_mfma_f32_16x16x32_bf16 v[4:7], v[148:151], v[208:211], v[4:7]
	v_mfma_f32_16x16x32_bf16 v[0:3], v[156:159], v[208:211], v[0:3]
	v_mfma_f32_16x16x32_bf16 v[52:55], v[152:155], v[168:171], v[52:55]
	v_mfma_f32_16x16x32_bf16 v[48:51], v[160:163], v[168:171], v[48:51]
	v_mfma_f32_16x16x32_bf16 v[36:39], v[152:155], v[176:179], v[36:39]
	v_mfma_f32_16x16x32_bf16 v[32:35], v[160:163], v[176:179], v[32:35]
	v_mfma_f32_16x16x32_bf16 v[20:23], v[152:155], v[204:207], v[20:23]
	v_mfma_f32_16x16x32_bf16 v[16:19], v[160:163], v[204:207], v[16:19]
	v_mfma_f32_16x16x32_bf16 v[4:7], v[152:155], v[212:215], v[4:7]
	v_mfma_f32_16x16x32_bf16 v[0:3], v[160:163], v[212:215], v[0:3]
	s_setprio 0
	s_barrier
	s_add_i32 s10, 0, 0x18000
	s_add_i32 s72, 0, 0x1c000
	v_add_u32_e32 v144, s10, v220
	v_add_u32_e32 v160, s72, v220
	ds_read_b128 v[132:135], v144
	ds_read_b128 v[136:139], v144 offset:1024
	ds_read_b128 v[140:143], v144 offset:2048
	ds_read_b128 v[144:147], v144 offset:3072
	ds_read_b128 v[148:151], v160
	ds_read_b128 v[152:155], v160 offset:1024
	ds_read_b128 v[156:159], v160 offset:2048
	ds_read_b128 v[160:163], v160 offset:3072
	s_add_u32 s44, s46, 0x40000
	s_addc_u32 s45, s47, 0
	s_mov_b32 m0, s52
	ds_read_b128 v[164:167], v221 offset:32768
	ds_read_b128 v[168:171], v221 offset:33792
	ds_read_b128 v[172:175], v221 offset:34816
	ds_read_b128 v[176:179], v221 offset:35840
	ds_read_b128 v[180:183], v221 offset:36864
	ds_read_b128 v[204:207], v221 offset:37888
	ds_read_b128 v[208:211], v221 offset:38912
	global_load_lds_dwordx4 v184, s[44:45]
	s_mov_b32 m0, s53
	ds_read_b128 v[212:215], v221 offset:39936
	global_load_lds_dwordx4 v188, s[44:45]
	s_waitcnt vmcnt(8)
	s_waitcnt lgkmcnt(0)
	s_barrier
	s_setprio 1
	s_waitcnt lgkmcnt(0)
	v_mfma_f32_16x16x32_bf16 v[124:127], v[132:135], v[164:167], v[124:127]
	v_mfma_f32_16x16x32_bf16 v[120:123], v[140:143], v[164:167], v[120:123]
	v_mfma_f32_16x16x32_bf16 v[108:111], v[132:135], v[172:175], v[108:111]
	v_mfma_f32_16x16x32_bf16 v[104:107], v[140:143], v[172:175], v[104:107]
	v_mfma_f32_16x16x32_bf16 v[92:95], v[132:135], v[180:183], v[92:95]
	v_mfma_f32_16x16x32_bf16 v[88:91], v[140:143], v[180:183], v[88:91]
	v_mfma_f32_16x16x32_bf16 v[76:79], v[132:135], v[208:211], v[76:79]
	v_mfma_f32_16x16x32_bf16 v[72:75], v[140:143], v[208:211], v[72:75]
	v_mfma_f32_16x16x32_bf16 v[124:127], v[136:139], v[168:171], v[124:127]
	v_mfma_f32_16x16x32_bf16 v[120:123], v[144:147], v[168:171], v[120:123]
	v_mfma_f32_16x16x32_bf16 v[108:111], v[136:139], v[176:179], v[108:111]
	v_mfma_f32_16x16x32_bf16 v[104:107], v[144:147], v[176:179], v[104:107]
	v_mfma_f32_16x16x32_bf16 v[92:95], v[136:139], v[204:207], v[92:95]
	v_mfma_f32_16x16x32_bf16 v[88:91], v[144:147], v[204:207], v[88:91]
	v_mfma_f32_16x16x32_bf16 v[76:79], v[136:139], v[212:215], v[76:79]
	v_mfma_f32_16x16x32_bf16 v[72:75], v[144:147], v[212:215], v[72:75]
	s_setprio 0
	s_setprio 1
	v_mfma_f32_16x16x32_bf16 v[116:119], v[148:151], v[164:167], v[116:119]
	v_mfma_f32_16x16x32_bf16 v[112:115], v[156:159], v[164:167], v[112:115]
	v_mfma_f32_16x16x32_bf16 v[100:103], v[148:151], v[172:175], v[100:103]
	v_mfma_f32_16x16x32_bf16 v[96:99], v[156:159], v[172:175], v[96:99]
	v_mfma_f32_16x16x32_bf16 v[84:87], v[148:151], v[180:183], v[84:87]
	v_mfma_f32_16x16x32_bf16 v[80:83], v[156:159], v[180:183], v[80:83]
	v_mfma_f32_16x16x32_bf16 v[68:71], v[148:151], v[208:211], v[68:71]
	v_mfma_f32_16x16x32_bf16 v[64:67], v[156:159], v[208:211], v[64:67]
	v_mfma_f32_16x16x32_bf16 v[116:119], v[152:155], v[168:171], v[116:119]
	v_mfma_f32_16x16x32_bf16 v[112:115], v[160:163], v[168:171], v[112:115]
	v_mfma_f32_16x16x32_bf16 v[100:103], v[152:155], v[176:179], v[100:103]
	v_mfma_f32_16x16x32_bf16 v[96:99], v[160:163], v[176:179], v[96:99]
	v_mfma_f32_16x16x32_bf16 v[84:87], v[152:155], v[204:207], v[84:87]
	v_mfma_f32_16x16x32_bf16 v[80:83], v[160:163], v[204:207], v[80:83]
	v_mfma_f32_16x16x32_bf16 v[68:71], v[152:155], v[212:215], v[68:71]
	v_mfma_f32_16x16x32_bf16 v[64:67], v[160:163], v[212:215], v[64:67]
	s_setprio 0
	s_barrier
	s_add_i32 s10, s10, s50
	s_mov_b32 m0, s10
	ds_read_b128 v[164:167], v221 offset:49152
	ds_read_b128 v[168:171], v221 offset:50176
	ds_read_b128 v[172:175], v221 offset:51200
	global_load_lds_dwordx4 v186, s[42:43]
	s_add_i32 m0, s10, 0x2000
	ds_read_b128 v[176:179], v221 offset:52224
	global_load_lds_dwordx4 v190, s[42:43]
	s_add_u32 s42, s42, 0x40000
	s_addc_u32 s43, s43, 0
	s_add_i32 s10, s72, s50
	s_mov_b32 m0, s10
	ds_read_b128 v[180:183], v221 offset:53248
	global_load_lds_dwordx4 v186, s[42:43]
	s_add_i32 m0, s10, 0x2000
	ds_read_b128 v[204:207], v221 offset:54272
	global_load_lds_dwordx4 v190, s[42:43]
	s_mov_b32 m0, s58
	ds_read_b128 v[208:211], v221 offset:55296
	global_load_lds_dwordx4 v184, s[40:41]
	s_mov_b32 m0, s59
	ds_read_b128 v[212:215], v221 offset:56320
	global_load_lds_dwordx4 v188, s[40:41]
	s_waitcnt vmcnt(8)
	s_waitcnt lgkmcnt(0)
	s_barrier
	s_setprio 1
	s_waitcnt lgkmcnt(0)
	v_mfma_f32_16x16x32_bf16 v[60:63], v[132:135], v[164:167], v[60:63]
	v_mfma_f32_16x16x32_bf16 v[56:59], v[140:143], v[164:167], v[56:59]
	v_mfma_f32_16x16x32_bf16 v[44:47], v[132:135], v[172:175], v[44:47]
	v_mfma_f32_16x16x32_bf16 v[40:43], v[140:143], v[172:175], v[40:43]
	v_mfma_f32_16x16x32_bf16 v[28:31], v[132:135], v[180:183], v[28:31]
	v_mfma_f32_16x16x32_bf16 v[24:27], v[140:143], v[180:183], v[24:27]
	v_mfma_f32_16x16x32_bf16 v[12:15], v[132:135], v[208:211], v[12:15]
	v_mfma_f32_16x16x32_bf16 v[8:11], v[140:143], v[208:211], v[8:11]
	v_mfma_f32_16x16x32_bf16 v[60:63], v[136:139], v[168:171], v[60:63]
	v_mfma_f32_16x16x32_bf16 v[56:59], v[144:147], v[168:171], v[56:59]
	v_mfma_f32_16x16x32_bf16 v[44:47], v[136:139], v[176:179], v[44:47]
	v_mfma_f32_16x16x32_bf16 v[40:43], v[144:147], v[176:179], v[40:43]
	v_mfma_f32_16x16x32_bf16 v[28:31], v[136:139], v[204:207], v[28:31]
	v_mfma_f32_16x16x32_bf16 v[24:27], v[144:147], v[204:207], v[24:27]
	v_mfma_f32_16x16x32_bf16 v[12:15], v[136:139], v[212:215], v[12:15]
	v_mfma_f32_16x16x32_bf16 v[8:11], v[144:147], v[212:215], v[8:11]
	s_setprio 0
	s_setprio 1
	v_mfma_f32_16x16x32_bf16 v[52:55], v[148:151], v[164:167], v[52:55]
	v_mfma_f32_16x16x32_bf16 v[48:51], v[156:159], v[164:167], v[48:51]
	v_mfma_f32_16x16x32_bf16 v[36:39], v[148:151], v[172:175], v[36:39]
	v_mfma_f32_16x16x32_bf16 v[32:35], v[156:159], v[172:175], v[32:35]
	v_mfma_f32_16x16x32_bf16 v[20:23], v[148:151], v[180:183], v[20:23]
	v_mfma_f32_16x16x32_bf16 v[16:19], v[156:159], v[180:183], v[16:19]
	v_mfma_f32_16x16x32_bf16 v[4:7], v[148:151], v[208:211], v[4:7]
	v_mfma_f32_16x16x32_bf16 v[0:3], v[156:159], v[208:211], v[0:3]
	v_mfma_f32_16x16x32_bf16 v[52:55], v[152:155], v[168:171], v[52:55]
	v_mfma_f32_16x16x32_bf16 v[48:51], v[160:163], v[168:171], v[48:51]
	v_mfma_f32_16x16x32_bf16 v[36:39], v[152:155], v[176:179], v[36:39]
	v_mfma_f32_16x16x32_bf16 v[32:35], v[160:163], v[176:179], v[32:35]
	v_mfma_f32_16x16x32_bf16 v[20:23], v[152:155], v[204:207], v[20:23]
	v_mfma_f32_16x16x32_bf16 v[16:19], v[160:163], v[204:207], v[16:19]
	v_mfma_f32_16x16x32_bf16 v[4:7], v[152:155], v[212:215], v[4:7]
	v_mfma_f32_16x16x32_bf16 v[0:3], v[160:163], v[212:215], v[0:3]
	s_setprio 0
	s_barrier
	s_add_i32 s10, s71, 2
	s_add_u32 s38, s38, 0x100
	s_addc_u32 s39, s39, 0
	s_cmp_gt_u32 s71, 13
	s_mov_b32 s71, s10
	s_cbranch_scc1 .LBB0_1025
.LBB0_1019:
	s_add_u32 s46, s28, s38
	s_addc_u32 s47, s29, s39
	s_add_u32 s73, s26, s38
	s_addc_u32 s72, s27, s39
	s_add_u32 s40, s46, 0x180
	s_addc_u32 s41, s47, 0
	s_add_u32 s42, s73, 0x180
	s_addc_u32 s43, s72, 0
	s_add_u32 s46, s46, 0x100
	s_addc_u32 s47, s47, 0
	s_add_u32 s44, s73, 0x100
	s_addc_u32 s45, s72, 0
	s_cmpk_eq_i32 s38, 0x700
	s_cselect_b32 s40, s30, s40
	s_cselect_b32 s41, s31, s41
	s_cselect_b32 s42, s36, s42
	s_cselect_b32 s43, s37, s43
	s_cselect_b32 s46, s69, s46
	s_cselect_b32 s47, s19, s47
	s_cselect_b32 s44, s70, s44
	s_cselect_b32 s45, s17, s45
	s_branch .LBB0_1018
